# EpiQ q6val: 256 IEEE divisions by a power-of-two step replaced by exact reciprocal multiplies
# baseline (speedup 1.0000x reference)
.LBB0_584:
	s_or_b64 exec, exec, s[4:5]
	v_mul_f32_e32 v194, 0x3dd53b94, v139
	v_pk_mul_f32 v[18:19], v[194:195], v[18:19] op_sel_hi:[0,1]
	v_pk_mul_f32 v[2:3], v[194:195], v[2:3] op_sel_hi:[0,1]
	v_pk_mul_f32 v[20:21], v[194:195], v[20:21] op_sel_hi:[0,1]
	v_pk_mul_f32 v[4:5], v[194:195], v[4:5] op_sel_hi:[0,1]
	v_max_f32_e64 v139, |v18|, |v2|
	v_max_f32_e64 v143, |v19|, |v3|
	v_pk_mul_f32 v[22:23], v[194:195], v[22:23] op_sel_hi:[0,1]
	v_pk_mul_f32 v[6:7], v[194:195], v[6:7] op_sel_hi:[0,1]
	v_max3_f32 v139, v139, 0, v143
	v_max_f32_e64 v143, |v20|, |v4|
	v_max_f32_e64 v145, |v21|, |v5|
	v_pk_mul_f32 v[24:25], v[194:195], v[24:25] op_sel_hi:[0,1]
	v_pk_mul_f32 v[8:9], v[194:195], v[8:9] op_sel_hi:[0,1]
	v_max3_f32 v139, v139, v143, v145
	v_max_f32_e64 v143, |v22|, |v6|
	v_max_f32_e64 v145, |v23|, |v7|
	v_pk_mul_f32 v[26:27], v[194:195], v[26:27] op_sel_hi:[0,1]
	v_pk_mul_f32 v[10:11], v[194:195], v[10:11] op_sel_hi:[0,1]
	v_max3_f32 v139, v139, v143, v145
	v_max_f32_e64 v143, |v24|, |v8|
	v_max_f32_e64 v145, |v25|, |v9|
	v_pk_mul_f32 v[28:29], v[194:195], v[28:29] op_sel_hi:[0,1]
	v_pk_mul_f32 v[12:13], v[194:195], v[12:13] op_sel_hi:[0,1]
	v_max3_f32 v139, v139, v143, v145
	v_max_f32_e64 v143, |v26|, |v10|
	v_max_f32_e64 v145, |v27|, |v11|
	v_pk_mul_f32 v[30:31], v[194:195], v[30:31] op_sel_hi:[0,1]
	v_pk_mul_f32 v[14:15], v[194:195], v[14:15] op_sel_hi:[0,1]
	v_max3_f32 v139, v139, v143, v145
	v_max_f32_e64 v143, |v28|, |v12|
	v_max_f32_e64 v145, |v29|, |v13|
	v_pk_mul_f32 v[32:33], v[194:195], v[32:33] op_sel_hi:[0,1]
	v_pk_mul_f32 v[16:17], v[194:195], v[16:17] op_sel_hi:[0,1]
	v_max3_f32 v139, v139, v143, v145
	v_max_f32_e64 v143, |v30|, |v14|
	v_max_f32_e64 v145, |v31|, |v15|
	v_max3_f32 v139, v139, v143, v145
	v_max_f32_e64 v143, |v32|, |v16|
	v_max_f32_e64 v145, |v33|, |v17|
	v_max3_f32 v139, v139, v143, v145
	v_cmp_gt_u32_e32 vcc, 64, v188
	v_bfe_u32 v143, v139, 23, 8
	v_and_b32_e32 v139, 0x7fffff, v139
	v_cndmask_b32_e32 v34, v177, v181, vcc
	v_cndmask_b32_e64 v190, 64, 0, vcc
	v_cmp_gt_u32_e32 vcc, s11, v139
	v_mov_b64_e32 v[194:195], s[26:27]
	v_mad_i64_i32 v[194:195], s[4:5], v141, s10, v[194:195]
	v_cndmask_b32_e64 v139, -2, -3, vcc
	v_add3_u32 v139, v143, v139, s0
	v_max_i32_e32 v139, 0xffffff88, v139
	v_add_u32_e32 v139, 0x7f, v139
	v_lshl_add_u64 v[194:195], v[192:193], 1, v[194:195]
	v_and_b32_e32 v188, 32, v188
	v_mov_b32_e32 v189, v35
	v_lshlrev_b32_e32 v196, 23, v139
	v_lshl_add_u64 v[218:219], v[194:195], 0, v[34:35]
	v_cvt_scalef32_2xpk16_fp6_f32 v[210:215], v[18:33], v[2:17], v196
	v_sub_u32_e32 v198, 0x7f000000, v196
	v_lshl_add_u64 v[218:219], v[218:219], 0, v[188:189]
	global_store_dwordx4 v[218:219], v[210:213], off
	v_mul_lo_u32 v216, v139, s1
	v_mov_b32_e32 v217, v35
	v_pk_mul_f32 v[210:211], v[18:19], v[198:199] op_sel_hi:[1,0]
	v_pk_mul_f32 v[212:213], v[2:3], v[198:199] op_sel_hi:[1,0]
	v_cmp_lt_f32_e64 vcc, |v210|, 4.0
	v_and_b32_e32 v139, 0x7fffffff, v210
	global_store_dwordx4 v[218:219], v[214:217], off offset:16
	v_cndmask_b32_e32 v143, 0.5, v185, vcc
	v_cmp_nlt_f32_e64 vcc, |v210|, 2.0
	v_pk_mul_f32 v[214:215], v[20:21], v[198:199] op_sel_hi:[1,0]
	v_mov_b32_e32 v191, v35
	v_cndmask_b32_e32 v143, v197, v143, vcc
	v_permlane32_swap_b32_e32 v116, v100
	v_cmp_lt_f32_e64 vcc, |v211|, 4.0
	v_and_b32_e32 v145, 0x7fffffff, v211
	v_sub_u32_e32 v147, 0x7f000000, v143
	v_mul_f32_e64 v139, |v210|, v147
	v_cndmask_b32_e32 v147, 0.5, v185, vcc
	v_cmp_nlt_f32_e64 vcc, |v211|, 2.0
	v_rndne_f32_e32 v139, v139
	v_mul_f32_e32 v139, v143, v139
	v_cndmask_b32_e32 v147, v197, v147, vcc
	v_min_f32_e32 v139, 0x40f00000, v139
	v_bfi_b32 v210, s22, v139, v210
	v_permlane32_swap_b32_e32 v117, v101
	v_sub_u32_e32 v145, 0x7f000000, v147
	v_mul_f32_e64 v143, |v211|, v145
	v_rndne_f32_e32 v143, v143
	v_mul_f32_e32 v143, v147, v143
	v_cmp_lt_f32_e64 vcc, |v212|, 4.0
	v_min_f32_e32 v143, 0x40f00000, v143
	v_bfi_b32 v211, s22, v143, v211
	v_cndmask_b32_e32 v145, 0.5, v185, vcc
	v_cmp_nlt_f32_e64 vcc, |v212|, 2.0
	v_and_b32_e32 v143, 0x7fffffff, v212
	v_pk_mul_f32 v[210:211], v[210:211], v[196:197] op_sel_hi:[1,0]
	v_cndmask_b32_e32 v145, v197, v145, vcc
	v_pk_fma_f32 v[18:19], v[18:19], 2.0, v[210:211] op_sel_hi:[1,0,1] neg_lo:[0,0,1] neg_hi:[0,0,1]
	v_permlane32_swap_b32_e32 v118, v102
	v_cmp_lt_f32_e64 vcc, |v213|, 4.0
	v_and_b32_e32 v143, 0x7fffffff, v213
	v_sub_u32_e32 v147, 0x7f000000, v145
	v_mul_f32_e64 v139, |v212|, v147
	v_cndmask_b32_e32 v147, 0.5, v185, vcc
	v_cmp_nlt_f32_e64 vcc, |v213|, 2.0
	v_rndne_f32_e32 v139, v139
	v_mul_f32_e32 v139, v145, v139
	v_cndmask_b32_e32 v147, v197, v147, vcc
	v_min_f32_e32 v139, 0x40f00000, v139
	v_sub_u32_e32 v145, 0x7f000000, v147
	v_mul_f32_e64 v143, |v213|, v145
	v_rndne_f32_e32 v143, v143
	v_mul_f32_e32 v143, v147, v143
	v_cmp_lt_f32_e64 vcc, |v214|, 4.0
	v_min_f32_e32 v143, 0x40f00000, v143
	v_bfi_b32 v211, s22, v143, v213
	v_cndmask_b32_e32 v145, 0.5, v185, vcc
	v_cmp_nlt_f32_e64 vcc, |v214|, 2.0
	v_and_b32_e32 v143, 0x7fffffff, v214
	v_bfi_b32 v210, s22, v139, v212
	v_cndmask_b32_e32 v145, v197, v145, vcc
	v_pk_mul_f32 v[212:213], v[4:5], v[198:199] op_sel_hi:[1,0]
	v_pk_mul_f32 v[210:211], v[210:211], v[196:197] op_sel_hi:[1,0]
	v_permlane32_swap_b32_e32 v119, v103
	v_cmp_lt_f32_e64 vcc, |v215|, 4.0
	v_and_b32_e32 v143, 0x7fffffff, v215
	v_sub_u32_e32 v147, 0x7f000000, v145
	v_mul_f32_e64 v139, |v214|, v147
	v_cndmask_b32_e32 v147, 0.5, v185, vcc
	v_cmp_nlt_f32_e64 vcc, |v215|, 2.0
	v_rndne_f32_e32 v139, v139
	v_mul_f32_e32 v139, v145, v139
	v_cndmask_b32_e32 v147, v197, v147, vcc
	v_pk_fma_f32 v[2:3], v[2:3], 2.0, v[210:211] op_sel_hi:[1,0,1] neg_lo:[0,0,1] neg_hi:[0,0,1]
	v_sub_u32_e32 v145, 0x7f000000, v147
	v_mul_f32_e64 v143, |v215|, v145
	v_rndne_f32_e32 v143, v143
	v_mul_f32_e32 v143, v147, v143
	v_cmp_lt_f32_e64 vcc, |v212|, 4.0
	v_min_f32_e32 v143, 0x40f00000, v143
	v_bfi_b32 v211, s22, v143, v215
	v_cndmask_b32_e32 v145, 0.5, v185, vcc
	v_cmp_nlt_f32_e64 vcc, |v212|, 2.0
	v_and_b32_e32 v143, 0x7fffffff, v212
	v_min_f32_e32 v139, 0x40f00000, v139
	v_cndmask_b32_e32 v145, v197, v145, vcc
	v_bfi_b32 v210, s22, v139, v214
	v_pk_mul_f32 v[214:215], v[22:23], v[198:199] op_sel_hi:[1,0]
	v_pk_mul_f32 v[210:211], v[210:211], v[196:197] op_sel_hi:[1,0]
	v_cmp_lt_f32_e64 vcc, |v213|, 4.0
	v_and_b32_e32 v143, 0x7fffffff, v213
	v_sub_u32_e32 v147, 0x7f000000, v145
	v_mul_f32_e64 v139, |v212|, v147
	v_cndmask_b32_e32 v147, 0.5, v185, vcc
	v_cmp_nlt_f32_e64 vcc, |v213|, 2.0
	v_rndne_f32_e32 v139, v139
	v_mul_f32_e32 v139, v145, v139
	v_cndmask_b32_e32 v147, v197, v147, vcc
	v_pk_fma_f32 v[20:21], v[20:21], 2.0, v[210:211] op_sel_hi:[1,0,1] neg_lo:[0,0,1] neg_hi:[0,0,1]
	v_sub_u32_e32 v145, 0x7f000000, v147
	v_mul_f32_e64 v143, |v213|, v145
	v_rndne_f32_e32 v143, v143
	v_mul_f32_e32 v143, v147, v143
	v_cmp_lt_f32_e64 vcc, |v214|, 4.0
	v_min_f32_e32 v143, 0x40f00000, v143
	v_bfi_b32 v211, s22, v143, v213
	v_cndmask_b32_e32 v145, 0.5, v185, vcc
	v_cmp_nlt_f32_e64 vcc, |v214|, 2.0
	v_and_b32_e32 v143, 0x7fffffff, v214
	v_min_f32_e32 v139, 0x40f00000, v139
	v_cndmask_b32_e32 v145, v197, v145, vcc
	v_bfi_b32 v210, s22, v139, v212
	v_pk_mul_f32 v[212:213], v[6:7], v[198:199] op_sel_hi:[1,0]
	v_pk_mul_f32 v[210:211], v[210:211], v[196:197] op_sel_hi:[1,0]
	v_cmp_lt_f32_e64 vcc, |v215|, 4.0
	v_and_b32_e32 v143, 0x7fffffff, v215
	v_sub_u32_e32 v147, 0x7f000000, v145
	v_mul_f32_e64 v139, |v214|, v147
	v_cndmask_b32_e32 v147, 0.5, v185, vcc
	v_cmp_nlt_f32_e64 vcc, |v215|, 2.0
	v_rndne_f32_e32 v139, v139
	v_mul_f32_e32 v139, v145, v139
	v_cndmask_b32_e32 v147, v197, v147, vcc
	v_pk_fma_f32 v[4:5], v[4:5], 2.0, v[210:211] op_sel_hi:[1,0,1] neg_lo:[0,0,1] neg_hi:[0,0,1]
	v_sub_u32_e32 v145, 0x7f000000, v147
	v_mul_f32_e64 v143, |v215|, v145
	v_rndne_f32_e32 v143, v143
	v_mul_f32_e32 v143, v147, v143
	v_cmp_lt_f32_e64 vcc, |v212|, 4.0
	v_min_f32_e32 v143, 0x40f00000, v143
	v_bfi_b32 v211, s22, v143, v215
	v_cndmask_b32_e32 v145, 0.5, v185, vcc
	v_cmp_nlt_f32_e64 vcc, |v212|, 2.0
	v_and_b32_e32 v143, 0x7fffffff, v212
	v_min_f32_e32 v139, 0x40f00000, v139
	v_cndmask_b32_e32 v145, v197, v145, vcc
	v_bfi_b32 v210, s22, v139, v214
	v_pk_mul_f32 v[214:215], v[24:25], v[198:199] op_sel_hi:[1,0]
	v_pk_mul_f32 v[210:211], v[210:211], v[196:197] op_sel_hi:[1,0]
	v_cmp_lt_f32_e64 vcc, |v213|, 4.0
	v_and_b32_e32 v143, 0x7fffffff, v213
	v_sub_u32_e32 v147, 0x7f000000, v145
	v_mul_f32_e64 v139, |v212|, v147
	v_cndmask_b32_e32 v147, 0.5, v185, vcc
	v_cmp_nlt_f32_e64 vcc, |v213|, 2.0
	v_rndne_f32_e32 v139, v139
	v_mul_f32_e32 v139, v145, v139
	v_cndmask_b32_e32 v147, v197, v147, vcc
	v_pk_fma_f32 v[22:23], v[22:23], 2.0, v[210:211] op_sel_hi:[1,0,1] neg_lo:[0,0,1] neg_hi:[0,0,1]
	v_sub_u32_e32 v145, 0x7f000000, v147
	v_mul_f32_e64 v143, |v213|, v145
	v_rndne_f32_e32 v143, v143
	v_mul_f32_e32 v143, v147, v143
	v_cmp_lt_f32_e64 vcc, |v214|, 4.0
	v_min_f32_e32 v143, 0x40f00000, v143
	v_bfi_b32 v211, s22, v143, v213
	v_cndmask_b32_e32 v145, 0.5, v185, vcc
	v_cmp_nlt_f32_e64 vcc, |v214|, 2.0
	v_and_b32_e32 v143, 0x7fffffff, v214
	v_min_f32_e32 v139, 0x40f00000, v139
	v_cndmask_b32_e32 v145, v197, v145, vcc
	v_bfi_b32 v210, s22, v139, v212
	v_pk_mul_f32 v[212:213], v[8:9], v[198:199] op_sel_hi:[1,0]
	v_pk_mul_f32 v[210:211], v[210:211], v[196:197] op_sel_hi:[1,0]
	v_cmp_lt_f32_e64 vcc, |v215|, 4.0
	v_and_b32_e32 v143, 0x7fffffff, v215
	v_sub_u32_e32 v147, 0x7f000000, v145
	v_mul_f32_e64 v139, |v214|, v147
	v_cndmask_b32_e32 v147, 0.5, v185, vcc
	v_cmp_nlt_f32_e64 vcc, |v215|, 2.0
	v_rndne_f32_e32 v139, v139
	v_mul_f32_e32 v139, v145, v139
	v_cndmask_b32_e32 v147, v197, v147, vcc
	v_pk_fma_f32 v[6:7], v[6:7], 2.0, v[210:211] op_sel_hi:[1,0,1] neg_lo:[0,0,1] neg_hi:[0,0,1]
	v_sub_u32_e32 v145, 0x7f000000, v147
	v_mul_f32_e64 v143, |v215|, v145
	v_rndne_f32_e32 v143, v143
	v_mul_f32_e32 v143, v147, v143
	v_cmp_lt_f32_e64 vcc, |v212|, 4.0
	v_min_f32_e32 v143, 0x40f00000, v143
	v_bfi_b32 v211, s22, v143, v215
	v_cndmask_b32_e32 v145, 0.5, v185, vcc
	v_cmp_nlt_f32_e64 vcc, |v212|, 2.0
	v_and_b32_e32 v143, 0x7fffffff, v212
	v_min_f32_e32 v139, 0x40f00000, v139
	v_cndmask_b32_e32 v145, v197, v145, vcc
	v_bfi_b32 v210, s22, v139, v214
	v_pk_mul_f32 v[214:215], v[26:27], v[198:199] op_sel_hi:[1,0]
	v_pk_mul_f32 v[210:211], v[210:211], v[196:197] op_sel_hi:[1,0]
	v_cmp_lt_f32_e64 vcc, |v213|, 4.0
	v_and_b32_e32 v143, 0x7fffffff, v213
	v_sub_u32_e32 v147, 0x7f000000, v145
	v_mul_f32_e64 v139, |v212|, v147
	v_cndmask_b32_e32 v147, 0.5, v185, vcc
	v_cmp_nlt_f32_e64 vcc, |v213|, 2.0
	v_rndne_f32_e32 v139, v139
	v_mul_f32_e32 v139, v145, v139
	v_cndmask_b32_e32 v147, v197, v147, vcc
	v_pk_fma_f32 v[24:25], v[24:25], 2.0, v[210:211] op_sel_hi:[1,0,1] neg_lo:[0,0,1] neg_hi:[0,0,1]
	v_sub_u32_e32 v145, 0x7f000000, v147
	v_mul_f32_e64 v143, |v213|, v145
	v_rndne_f32_e32 v143, v143
	v_mul_f32_e32 v143, v147, v143
	v_cmp_lt_f32_e64 vcc, |v214|, 4.0
	v_min_f32_e32 v143, 0x40f00000, v143
	v_bfi_b32 v211, s22, v143, v213
	v_cndmask_b32_e32 v145, 0.5, v185, vcc
	v_cmp_nlt_f32_e64 vcc, |v214|, 2.0
	v_and_b32_e32 v143, 0x7fffffff, v214
	v_min_f32_e32 v139, 0x40f00000, v139
	v_cndmask_b32_e32 v145, v197, v145, vcc
	v_bfi_b32 v210, s22, v139, v212
	v_pk_mul_f32 v[212:213], v[10:11], v[198:199] op_sel_hi:[1,0]
	v_pk_mul_f32 v[210:211], v[210:211], v[196:197] op_sel_hi:[1,0]
	v_cmp_lt_f32_e64 vcc, |v215|, 4.0
	v_and_b32_e32 v143, 0x7fffffff, v215
	v_sub_u32_e32 v147, 0x7f000000, v145
	v_mul_f32_e64 v139, |v214|, v147
	v_cndmask_b32_e32 v147, 0.5, v185, vcc
	v_cmp_nlt_f32_e64 vcc, |v215|, 2.0
	v_rndne_f32_e32 v139, v139
	v_mul_f32_e32 v139, v145, v139
	v_cndmask_b32_e32 v147, v197, v147, vcc
	v_pk_fma_f32 v[8:9], v[8:9], 2.0, v[210:211] op_sel_hi:[1,0,1] neg_lo:[0,0,1] neg_hi:[0,0,1]
	v_sub_u32_e32 v145, 0x7f000000, v147
	v_mul_f32_e64 v143, |v215|, v145
	v_rndne_f32_e32 v143, v143
	v_mul_f32_e32 v143, v147, v143
	v_cmp_lt_f32_e64 vcc, |v212|, 4.0
	v_min_f32_e32 v143, 0x40f00000, v143
	v_bfi_b32 v211, s22, v143, v215
	v_cndmask_b32_e32 v145, 0.5, v185, vcc
	v_cmp_nlt_f32_e64 vcc, |v212|, 2.0
	v_and_b32_e32 v143, 0x7fffffff, v212
	v_min_f32_e32 v139, 0x40f00000, v139
	v_cndmask_b32_e32 v145, v197, v145, vcc
	v_bfi_b32 v210, s22, v139, v214
	v_pk_mul_f32 v[214:215], v[28:29], v[198:199] op_sel_hi:[1,0]
	v_pk_mul_f32 v[210:211], v[210:211], v[196:197] op_sel_hi:[1,0]
	v_cmp_lt_f32_e64 vcc, |v213|, 4.0
	v_and_b32_e32 v143, 0x7fffffff, v213
	v_sub_u32_e32 v147, 0x7f000000, v145
	v_mul_f32_e64 v139, |v212|, v147
	v_cndmask_b32_e32 v147, 0.5, v185, vcc
	v_cmp_nlt_f32_e64 vcc, |v213|, 2.0
	v_rndne_f32_e32 v139, v139
	v_mul_f32_e32 v139, v145, v139
	v_cndmask_b32_e32 v147, v197, v147, vcc
	v_pk_fma_f32 v[26:27], v[26:27], 2.0, v[210:211] op_sel_hi:[1,0,1] neg_lo:[0,0,1] neg_hi:[0,0,1]
	v_sub_u32_e32 v145, 0x7f000000, v147
	v_mul_f32_e64 v143, |v213|, v145
	v_rndne_f32_e32 v143, v143
	v_mul_f32_e32 v143, v147, v143
	v_cmp_lt_f32_e64 vcc, |v214|, 4.0
	v_min_f32_e32 v143, 0x40f00000, v143
	v_bfi_b32 v211, s22, v143, v213
	v_cndmask_b32_e32 v145, 0.5, v185, vcc
	v_cmp_nlt_f32_e64 vcc, |v214|, 2.0
	v_and_b32_e32 v143, 0x7fffffff, v214
	v_min_f32_e32 v139, 0x40f00000, v139
	v_cndmask_b32_e32 v145, v197, v145, vcc
	v_bfi_b32 v210, s22, v139, v212
	v_pk_mul_f32 v[212:213], v[12:13], v[198:199] op_sel_hi:[1,0]
	v_pk_mul_f32 v[210:211], v[210:211], v[196:197] op_sel_hi:[1,0]
	v_cmp_lt_f32_e64 vcc, |v215|, 4.0
	v_and_b32_e32 v143, 0x7fffffff, v215
	v_sub_u32_e32 v147, 0x7f000000, v145
	v_mul_f32_e64 v139, |v214|, v147
	v_cndmask_b32_e32 v147, 0.5, v185, vcc
	v_cmp_nlt_f32_e64 vcc, |v215|, 2.0
	v_rndne_f32_e32 v139, v139
	v_mul_f32_e32 v139, v145, v139
	v_cndmask_b32_e32 v147, v197, v147, vcc
	v_pk_fma_f32 v[10:11], v[10:11], 2.0, v[210:211] op_sel_hi:[1,0,1] neg_lo:[0,0,1] neg_hi:[0,0,1]
	v_sub_u32_e32 v145, 0x7f000000, v147
	v_mul_f32_e64 v143, |v215|, v145
	v_rndne_f32_e32 v143, v143
	v_mul_f32_e32 v143, v147, v143
	v_cmp_lt_f32_e64 vcc, |v212|, 4.0
	v_min_f32_e32 v143, 0x40f00000, v143
	v_bfi_b32 v211, s22, v143, v215
	v_cndmask_b32_e32 v145, 0.5, v185, vcc
	v_cmp_nlt_f32_e64 vcc, |v212|, 2.0
	v_and_b32_e32 v143, 0x7fffffff, v212
	v_min_f32_e32 v139, 0x40f00000, v139
	v_cndmask_b32_e32 v145, v197, v145, vcc
	v_bfi_b32 v210, s22, v139, v214
	v_pk_mul_f32 v[214:215], v[30:31], v[198:199] op_sel_hi:[1,0]
	v_pk_mul_f32 v[210:211], v[210:211], v[196:197] op_sel_hi:[1,0]
	v_cmp_lt_f32_e64 vcc, |v213|, 4.0
	v_and_b32_e32 v143, 0x7fffffff, v213
	v_sub_u32_e32 v147, 0x7f000000, v145
	v_mul_f32_e64 v139, |v212|, v147
	v_cndmask_b32_e32 v147, 0.5, v185, vcc
	v_cmp_nlt_f32_e64 vcc, |v213|, 2.0
	v_rndne_f32_e32 v139, v139
	v_mul_f32_e32 v139, v145, v139
	v_cndmask_b32_e32 v147, v197, v147, vcc
	v_pk_fma_f32 v[28:29], v[28:29], 2.0, v[210:211] op_sel_hi:[1,0,1] neg_lo:[0,0,1] neg_hi:[0,0,1]
	v_sub_u32_e32 v145, 0x7f000000, v147
	v_mul_f32_e64 v143, |v213|, v145
	v_rndne_f32_e32 v143, v143
	v_mul_f32_e32 v143, v147, v143
	v_cmp_lt_f32_e64 vcc, |v214|, 4.0
	v_min_f32_e32 v143, 0x40f00000, v143
	v_bfi_b32 v211, s22, v143, v213
	v_cndmask_b32_e32 v145, 0.5, v185, vcc
	v_cmp_nlt_f32_e64 vcc, |v214|, 2.0
	v_and_b32_e32 v143, 0x7fffffff, v214
	v_min_f32_e32 v139, 0x40f00000, v139
	v_cndmask_b32_e32 v145, v197, v145, vcc
	v_bfi_b32 v210, s22, v139, v212
	v_pk_mul_f32 v[212:213], v[14:15], v[198:199] op_sel_hi:[1,0]
	v_pk_mul_f32 v[210:211], v[210:211], v[196:197] op_sel_hi:[1,0]
	v_cmp_lt_f32_e64 vcc, |v215|, 4.0
	v_and_b32_e32 v143, 0x7fffffff, v215
	v_sub_u32_e32 v147, 0x7f000000, v145
	v_mul_f32_e64 v139, |v214|, v147
	v_cndmask_b32_e32 v147, 0.5, v185, vcc
	v_cmp_nlt_f32_e64 vcc, |v215|, 2.0
	v_rndne_f32_e32 v139, v139
	v_mul_f32_e32 v139, v145, v139
	v_cndmask_b32_e32 v147, v197, v147, vcc
	v_pk_fma_f32 v[12:13], v[12:13], 2.0, v[210:211] op_sel_hi:[1,0,1] neg_lo:[0,0,1] neg_hi:[0,0,1]
	v_sub_u32_e32 v145, 0x7f000000, v147
	v_mul_f32_e64 v143, |v215|, v145
	v_rndne_f32_e32 v143, v143
	v_mul_f32_e32 v143, v147, v143
	v_cmp_lt_f32_e64 vcc, |v212|, 4.0
	v_min_f32_e32 v143, 0x40f00000, v143
	v_bfi_b32 v211, s22, v143, v215
	v_cndmask_b32_e32 v145, 0.5, v185, vcc
	v_cmp_nlt_f32_e64 vcc, |v212|, 2.0
	v_and_b32_e32 v143, 0x7fffffff, v212
	v_min_f32_e32 v139, 0x40f00000, v139
	v_cndmask_b32_e32 v145, v197, v145, vcc
	v_bfi_b32 v210, s22, v139, v214
	v_pk_mul_f32 v[214:215], v[32:33], v[198:199] op_sel_hi:[1,0]
	v_pk_mul_f32 v[210:211], v[210:211], v[196:197] op_sel_hi:[1,0]
	v_cmp_lt_f32_e64 vcc, |v213|, 4.0
	v_and_b32_e32 v143, 0x7fffffff, v213
	v_sub_u32_e32 v147, 0x7f000000, v145
	v_mul_f32_e64 v139, |v212|, v147
	v_cndmask_b32_e32 v147, 0.5, v185, vcc
	v_cmp_nlt_f32_e64 vcc, |v213|, 2.0
	v_rndne_f32_e32 v139, v139
	v_mul_f32_e32 v139, v145, v139
	v_cndmask_b32_e32 v147, v197, v147, vcc
	v_pk_fma_f32 v[30:31], v[30:31], 2.0, v[210:211] op_sel_hi:[1,0,1] neg_lo:[0,0,1] neg_hi:[0,0,1]
	v_sub_u32_e32 v145, 0x7f000000, v147
	v_mul_f32_e64 v143, |v213|, v145
	v_rndne_f32_e32 v143, v143
	v_mul_f32_e32 v143, v147, v143
	v_cmp_lt_f32_e64 vcc, |v214|, 4.0
	v_min_f32_e32 v143, 0x40f00000, v143
	v_bfi_b32 v211, s22, v143, v213
	v_cndmask_b32_e32 v145, 0.5, v185, vcc
	v_cmp_nlt_f32_e64 vcc, |v214|, 2.0
	v_and_b32_e32 v143, 0x7fffffff, v214
	v_min_f32_e32 v139, 0x40f00000, v139
	v_cndmask_b32_e32 v145, v197, v145, vcc
	v_bfi_b32 v210, s22, v139, v212
	v_pk_mul_f32 v[212:213], v[16:17], v[198:199] op_sel_hi:[1,0]
	v_pk_mul_f32 v[210:211], v[210:211], v[196:197] op_sel_hi:[1,0]
	v_cmp_lt_f32_e64 vcc, |v215|, 4.0
	v_and_b32_e32 v143, 0x7fffffff, v215
	v_sub_u32_e32 v147, 0x7f000000, v145
	v_mul_f32_e64 v139, |v214|, v147
	v_cndmask_b32_e32 v147, 0.5, v185, vcc
	v_cmp_nlt_f32_e64 vcc, |v215|, 2.0
	v_rndne_f32_e32 v139, v139
	v_mul_f32_e32 v139, v145, v139
	v_cndmask_b32_e32 v147, v197, v147, vcc
	v_pk_fma_f32 v[14:15], v[14:15], 2.0, v[210:211] op_sel_hi:[1,0,1] neg_lo:[0,0,1] neg_hi:[0,0,1]
	v_sub_u32_e32 v145, 0x7f000000, v147
	v_mul_f32_e64 v143, |v215|, v145
	v_rndne_f32_e32 v143, v143
	v_mul_f32_e32 v143, v147, v143
	v_cmp_lt_f32_e64 vcc, |v212|, 4.0
	v_min_f32_e32 v143, 0x40f00000, v143
	v_bfi_b32 v211, s22, v143, v215
	v_cndmask_b32_e32 v145, 0.5, v185, vcc
	v_cmp_nlt_f32_e64 vcc, |v212|, 2.0
	v_and_b32_e32 v143, 0x7fffffff, v212
	v_min_f32_e32 v139, 0x40f00000, v139
	v_cndmask_b32_e32 v145, v197, v145, vcc
	v_bfi_b32 v210, s22, v139, v214
	v_pk_mul_f32 v[210:211], v[210:211], v[196:197] op_sel_hi:[1,0]
	v_permlane32_swap_b32_e32 v120, v104
	v_cmp_lt_f32_e64 vcc, |v213|, 4.0
	v_and_b32_e32 v143, 0x7fffffff, v213
	v_sub_u32_e32 v147, 0x7f000000, v145
	v_mul_f32_e64 v139, |v212|, v147
	v_cndmask_b32_e32 v147, 0.5, v185, vcc
	v_cmp_nlt_f32_e64 vcc, |v213|, 2.0
	v_rndne_f32_e32 v139, v139
	v_mul_f32_e32 v139, v145, v139
	v_cndmask_b32_e32 v147, v197, v147, vcc
	v_min_f32_e32 v139, 0x40f00000, v139
	v_sub_u32_e32 v145, 0x7f000000, v147
	v_mul_f32_e64 v143, |v213|, v145
	v_rndne_f32_e32 v143, v143
	v_mul_f32_e32 v143, v147, v143
	v_min_f32_e32 v143, 0x40f00000, v143
	v_pk_fma_f32 v[32:33], v[32:33], 2.0, v[210:211] op_sel_hi:[1,0,1] neg_lo:[0,0,1] neg_hi:[0,0,1]
	v_bfi_b32 v211, s22, v143, v213
	v_bfi_b32 v210, s22, v139, v212
	v_max_f32_e64 v139, |v18|, |v2|
	v_max_f32_e64 v143, |v19|, |v3|
	v_max3_f32 v139, v139, 0, v143
	v_max_f32_e64 v143, |v20|, |v4|
	v_max_f32_e64 v145, |v21|, |v5|
	v_max3_f32 v139, v139, v143, v145
	v_max_f32_e64 v143, |v22|, |v6|
	v_max_f32_e64 v145, |v23|, |v7|
	v_max3_f32 v139, v139, v143, v145
	v_max_f32_e64 v143, |v24|, |v8|
	v_max_f32_e64 v145, |v25|, |v9|
	v_max3_f32 v139, v139, v143, v145
	v_max_f32_e64 v143, |v26|, |v10|
	v_max_f32_e64 v145, |v27|, |v11|
	v_pk_mul_f32 v[210:211], v[210:211], v[196:197] op_sel_hi:[1,0]
	v_max3_f32 v139, v139, v143, v145
	v_max_f32_e64 v143, |v28|, |v12|
	v_max_f32_e64 v145, |v29|, |v13|
	v_pk_fma_f32 v[16:17], v[16:17], 2.0, v[210:211] op_sel_hi:[1,0,1] neg_lo:[0,0,1] neg_hi:[0,0,1]
	v_max3_f32 v139, v139, v143, v145
	v_max_f32_e64 v143, |v30|, |v14|
	v_max_f32_e64 v145, |v31|, |v15|
	v_max3_f32 v139, v139, v143, v145
	v_max_f32_e64 v143, |v32|, |v16|
	v_max_f32_e64 v145, |v33|, |v17|
	v_max3_f32 v139, v139, v143, v145
	v_bfe_u32 v143, v139, 23, 8
	v_and_b32_e32 v139, 0x7fffff, v139
	v_cmp_gt_u32_e32 vcc, s11, v139
	v_permlane32_swap_b32_e32 v121, v105
	s_nop 0
	v_cndmask_b32_e64 v139, -2, -3, vcc
	v_add3_u32 v139, v143, v139, s0
	v_max_i32_e32 v139, 0xffffff88, v139
	v_add_u32_e32 v139, 0x7f, v139
	v_lshlrev_b32_e32 v143, 23, v139
	v_cvt_scalef32_2xpk16_fp6_f32 v[210:215], v[18:33], v[2:17], v143
	v_lshl_add_u64 v[2:3], v[194:195], 0, v[190:191]
	v_permlane32_swap_b32_e32 v122, v106
	v_permlane32_swap_b32_e32 v123, v107
	v_permlane32_swap_b32_e32 v124, v108
	v_permlane32_swap_b32_e32 v125, v109
	v_permlane32_swap_b32_e32 v126, v110
	v_permlane32_swap_b32_e32 v127, v111
	v_permlane32_swap_b32_e32 v128, v112
	v_permlane32_swap_b32_e32 v129, v113
	v_permlane32_swap_b32_e32 v130, v114
	v_permlane32_swap_b32_e32 v131, v115
	v_lshl_add_u64 v[2:3], v[2:3], 0, v[188:189]
	v_permlane16_swap_b32_e32 v116, v124
	v_permlane16_swap_b32_e32 v117, v125
	v_permlane16_swap_b32_e32 v118, v126
	v_permlane16_swap_b32_e32 v119, v127
	v_permlane16_swap_b32_e32 v120, v128
	v_permlane16_swap_b32_e32 v121, v129
	v_permlane16_swap_b32_e32 v122, v130
	v_permlane16_swap_b32_e32 v123, v131
	v_permlane16_swap_b32_e32 v100, v108
	v_permlane16_swap_b32_e32 v101, v109
	v_permlane16_swap_b32_e32 v102, v110
	v_permlane16_swap_b32_e32 v103, v111
	v_permlane16_swap_b32_e32 v104, v112
	v_permlane16_swap_b32_e32 v105, v113
	v_permlane16_swap_b32_e32 v106, v114
	v_permlane16_swap_b32_e32 v107, v115
	v_cmp_lt_i32_e32 vcc, 1, v199
	v_mul_lo_u32 v216, v139, s1
	global_store_dwordx4 v[2:3], v[210:213], off
	global_store_dwordx4 v[2:3], v[214:217], off offset:16
	s_and_saveexec_b64 s[4:5], vcc
	s_xor_b64 s[4:5], exec, s[4:5]
	s_cbranch_execz .LBB0_588
	v_cmp_gt_i32_e32 vcc, 3, v199
	v_mov_b32_e32 v2, v207
	s_and_saveexec_b64 s[58:59], vcc
	v_mov_b32_e32 v2, v204
	s_or_b64 exec, exec, s[58:59]

.LBB0_592:
	s_or_b64 exec, exec, s[58:59]
	v_mul_f32_e32 v2, 0x3dd53b94, v2
	v_pk_mul_f32 v[32:33], v[2:3], v[130:131] op_sel_hi:[0,1]
	v_pk_mul_f32 v[30:31], v[2:3], v[128:129] op_sel_hi:[0,1]
	v_pk_mul_f32 v[28:29], v[2:3], v[126:127] op_sel_hi:[0,1]
	v_pk_mul_f32 v[26:27], v[2:3], v[124:125] op_sel_hi:[0,1]
	v_pk_mul_f32 v[24:25], v[2:3], v[122:123] op_sel_hi:[0,1]
	v_pk_mul_f32 v[22:23], v[2:3], v[120:121] op_sel_hi:[0,1]
	v_pk_mul_f32 v[20:21], v[2:3], v[118:119] op_sel_hi:[0,1]
	v_pk_mul_f32 v[18:19], v[2:3], v[116:117] op_sel_hi:[0,1]
	v_pk_mul_f32 v[16:17], v[2:3], v[114:115] op_sel_hi:[0,1]
	v_pk_mul_f32 v[14:15], v[2:3], v[112:113] op_sel_hi:[0,1]
	v_pk_mul_f32 v[12:13], v[2:3], v[110:111] op_sel_hi:[0,1]
	v_pk_mul_f32 v[10:11], v[2:3], v[108:109] op_sel_hi:[0,1]
	v_pk_mul_f32 v[8:9], v[2:3], v[106:107] op_sel_hi:[0,1]
	v_pk_mul_f32 v[6:7], v[2:3], v[104:105] op_sel_hi:[0,1]
	v_pk_mul_f32 v[4:5], v[2:3], v[102:103] op_sel_hi:[0,1]
	v_pk_mul_f32 v[2:3], v[2:3], v[100:101] op_sel_hi:[0,1]
	v_max_f32_e64 v100, |v18|, |v2|
	v_max_f32_e64 v101, |v19|, |v3|
	v_max3_f32 v100, v100, 0, v101
	v_max_f32_e64 v101, |v20|, |v4|
	v_max_f32_e64 v102, |v21|, |v5|
	v_max3_f32 v100, v100, v101, v102
	v_max_f32_e64 v101, |v22|, |v6|
	v_max_f32_e64 v102, |v23|, |v7|
	v_max3_f32 v100, v100, v101, v102
	v_max_f32_e64 v101, |v24|, |v8|
	v_max_f32_e64 v102, |v25|, |v9|
	v_max3_f32 v100, v100, v101, v102
	v_max_f32_e64 v101, |v26|, |v10|
	v_max_f32_e64 v102, |v27|, |v11|
	v_max3_f32 v100, v100, v101, v102
	v_max_f32_e64 v101, |v28|, |v12|
	v_max_f32_e64 v102, |v29|, |v13|
	v_max3_f32 v100, v100, v101, v102
	v_max_f32_e64 v101, |v30|, |v14|
	v_max_f32_e64 v102, |v31|, |v15|
	v_max3_f32 v100, v100, v101, v102
	v_max_f32_e64 v101, |v32|, |v16|
	v_max_f32_e64 v102, |v33|, |v17|
	v_max3_f32 v100, v100, v101, v102
	v_bfe_u32 v101, v100, 23, 8
	v_and_b32_e32 v100, 0x7fffff, v100
	v_cmp_gt_u32_e32 vcc, s11, v100
	v_add_u32_e32 v103, 0x80, v141
	v_mov_b32_e32 v113, v35
	v_cndmask_b32_e64 v100, -2, -3, vcc
	v_add3_u32 v100, v101, v100, s0
	v_max_i32_e32 v100, 0xffffff88, v100
	v_add_u32_e32 v100, 0x7f, v100
	v_lshlrev_b32_e32 v102, 23, v100
	v_mul_lo_u32 v112, v100, s1
	v_mov_b64_e32 v[100:101], s[26:27]
	v_mad_i64_i32 v[100:101], s[4:5], v103, s10, v[100:101]
	v_lshl_add_u64 v[100:101], v[192:193], 1, v[100:101]
	v_lshl_add_u64 v[114:115], v[100:101], 0, v[34:35]
	v_cvt_scalef32_2xpk16_fp6_f32 v[106:111], v[18:33], v[2:17], v102
	v_sub_u32_e32 v104, 0x7f000000, v102
	v_lshl_add_u64 v[114:115], v[114:115], 0, v[188:189]
	global_store_dwordx4 v[114:115], v[106:109], off
	global_store_dwordx4 v[114:115], v[110:113], off offset:16
	v_mov_b32_e32 v139, v102
	v_pk_mul_f32 v[106:107], v[18:19], v[104:105] op_sel_hi:[1,0]
	s_nop 0
	v_cmp_lt_f32_e64 vcc, |v106|, 4.0
	v_and_b32_e32 v34, 0x7fffffff, v106
	s_nop 0
	v_cndmask_b32_e32 v103, 0.5, v185, vcc
	v_cmp_nlt_f32_e64 vcc, |v106|, 2.0
	s_nop 1
	v_cndmask_b32_e32 v103, v197, v103, vcc
	v_cmp_lt_f32_e64 vcc, |v107|, 4.0
	v_and_b32_e32 v105, 0x7fffffff, v107
	v_sub_u32_e32 v108, 0x7f000000, v103
	v_mul_f32_e64 v34, |v106|, v108
	v_cndmask_b32_e32 v108, 0.5, v185, vcc
	v_cmp_nlt_f32_e64 vcc, |v107|, 2.0
	v_rndne_f32_e32 v34, v34
	v_mul_f32_e32 v34, v103, v34
	v_cndmask_b32_e32 v108, v197, v108, vcc
	v_min_f32_e32 v34, 0x40f00000, v34
	v_bfi_b32 v106, s22, v34, v106
	v_sub_u32_e32 v105, 0x7f000000, v108
	v_mul_f32_e64 v103, |v107|, v105
	v_rndne_f32_e32 v103, v103
	v_mul_f32_e32 v103, v108, v103
	v_pk_mul_f32 v[108:109], v[2:3], v[104:105] op_sel_hi:[1,0]
	v_min_f32_e32 v103, 0x40f00000, v103
	v_cmp_lt_f32_e64 vcc, |v108|, 4.0
	v_bfi_b32 v107, s22, v103, v107
	v_and_b32_e32 v103, 0x7fffffff, v108
	v_cndmask_b32_e32 v105, 0.5, v185, vcc
	v_cmp_nlt_f32_e64 vcc, |v108|, 2.0
	v_pk_mul_f32 v[106:107], v[106:107], v[102:103] op_sel_hi:[1,0]
	s_nop 0
	v_cndmask_b32_e32 v105, v197, v105, vcc
	v_pk_fma_f32 v[18:19], v[18:19], 2.0, v[106:107] op_sel_hi:[1,0,1] neg_lo:[0,0,1] neg_hi:[0,0,1]
	v_cmp_lt_f32_e64 vcc, |v109|, 4.0
	v_and_b32_e32 v103, 0x7fffffff, v109
	v_sub_u32_e32 v106, 0x7f000000, v105
	v_mul_f32_e64 v34, |v108|, v106
	v_cndmask_b32_e32 v106, 0.5, v185, vcc
	v_cmp_nlt_f32_e64 vcc, |v109|, 2.0
	v_rndne_f32_e32 v34, v34
	v_mul_f32_e32 v34, v105, v34
	v_cndmask_b32_e32 v106, v197, v106, vcc
	v_min_f32_e32 v34, 0x40f00000, v34
	v_sub_u32_e32 v105, 0x7f000000, v106
	v_mul_f32_e64 v103, |v109|, v105
	v_rndne_f32_e32 v103, v103
	v_pk_mul_f32 v[110:111], v[20:21], v[104:105] op_sel_hi:[1,0]
	v_mul_f32_e32 v103, v106, v103
	v_cmp_lt_f32_e64 vcc, |v110|, 4.0
	v_min_f32_e32 v103, 0x40f00000, v103
	v_bfi_b32 v107, s22, v103, v109
	v_cndmask_b32_e32 v105, 0.5, v185, vcc
	v_cmp_nlt_f32_e64 vcc, |v110|, 2.0
	v_and_b32_e32 v103, 0x7fffffff, v110
	v_bfi_b32 v106, s22, v34, v108
	v_cndmask_b32_e32 v105, v197, v105, vcc
	v_pk_mul_f32 v[106:107], v[106:107], v[102:103] op_sel_hi:[1,0]
	v_pk_fma_f32 v[2:3], v[2:3], 2.0, v[106:107] op_sel_hi:[1,0,1] neg_lo:[0,0,1] neg_hi:[0,0,1]
	v_cmp_lt_f32_e64 vcc, |v111|, 4.0
	v_and_b32_e32 v103, 0x7fffffff, v111
	v_sub_u32_e32 v106, 0x7f000000, v105
	v_mul_f32_e64 v34, |v110|, v106
	v_cndmask_b32_e32 v106, 0.5, v185, vcc
	v_cmp_nlt_f32_e64 vcc, |v111|, 2.0
	v_rndne_f32_e32 v34, v34
	v_mul_f32_e32 v34, v105, v34
	v_cndmask_b32_e32 v106, v197, v106, vcc
	v_min_f32_e32 v34, 0x40f00000, v34
	v_sub_u32_e32 v105, 0x7f000000, v106
	v_mul_f32_e64 v103, |v111|, v105
	v_rndne_f32_e32 v103, v103
	v_pk_mul_f32 v[108:109], v[4:5], v[104:105] op_sel_hi:[1,0]
	v_mul_f32_e32 v103, v106, v103
	v_cmp_lt_f32_e64 vcc, |v108|, 4.0
	v_min_f32_e32 v103, 0x40f00000, v103
	v_bfi_b32 v107, s22, v103, v111
	v_cndmask_b32_e32 v105, 0.5, v185, vcc
	v_cmp_nlt_f32_e64 vcc, |v108|, 2.0
	v_and_b32_e32 v103, 0x7fffffff, v108
	v_bfi_b32 v106, s22, v34, v110
	v_cndmask_b32_e32 v105, v197, v105, vcc
	v_pk_mul_f32 v[106:107], v[106:107], v[102:103] op_sel_hi:[1,0]
	v_pk_fma_f32 v[20:21], v[20:21], 2.0, v[106:107] op_sel_hi:[1,0,1] neg_lo:[0,0,1] neg_hi:[0,0,1]
	v_cmp_lt_f32_e64 vcc, |v109|, 4.0
	v_and_b32_e32 v103, 0x7fffffff, v109
	v_sub_u32_e32 v106, 0x7f000000, v105
	v_mul_f32_e64 v34, |v108|, v106
	v_cndmask_b32_e32 v106, 0.5, v185, vcc
	v_cmp_nlt_f32_e64 vcc, |v109|, 2.0
	v_rndne_f32_e32 v34, v34
	v_mul_f32_e32 v34, v105, v34
	v_cndmask_b32_e32 v106, v197, v106, vcc
	v_min_f32_e32 v34, 0x40f00000, v34
	v_sub_u32_e32 v105, 0x7f000000, v106
	v_mul_f32_e64 v103, |v109|, v105
	v_rndne_f32_e32 v103, v103
	v_pk_mul_f32 v[110:111], v[22:23], v[104:105] op_sel_hi:[1,0]
	v_mul_f32_e32 v103, v106, v103
	v_cmp_lt_f32_e64 vcc, |v110|, 4.0
	v_min_f32_e32 v103, 0x40f00000, v103
	v_bfi_b32 v107, s22, v103, v109
	v_cndmask_b32_e32 v105, 0.5, v185, vcc
	v_cmp_nlt_f32_e64 vcc, |v110|, 2.0
	v_and_b32_e32 v103, 0x7fffffff, v110
	v_bfi_b32 v106, s22, v34, v108
	v_cndmask_b32_e32 v105, v197, v105, vcc
	v_pk_mul_f32 v[106:107], v[106:107], v[102:103] op_sel_hi:[1,0]
	v_pk_fma_f32 v[4:5], v[4:5], 2.0, v[106:107] op_sel_hi:[1,0,1] neg_lo:[0,0,1] neg_hi:[0,0,1]
	v_cmp_lt_f32_e64 vcc, |v111|, 4.0
	v_and_b32_e32 v103, 0x7fffffff, v111
	v_sub_u32_e32 v106, 0x7f000000, v105
	v_mul_f32_e64 v34, |v110|, v106
	v_cndmask_b32_e32 v106, 0.5, v185, vcc
	v_cmp_nlt_f32_e64 vcc, |v111|, 2.0
	v_rndne_f32_e32 v34, v34
	v_mul_f32_e32 v34, v105, v34
	v_cndmask_b32_e32 v106, v197, v106, vcc
	v_min_f32_e32 v34, 0x40f00000, v34
	v_sub_u32_e32 v105, 0x7f000000, v106
	v_mul_f32_e64 v103, |v111|, v105
	v_rndne_f32_e32 v103, v103
	v_pk_mul_f32 v[108:109], v[6:7], v[104:105] op_sel_hi:[1,0]
	v_mul_f32_e32 v103, v106, v103
	v_cmp_lt_f32_e64 vcc, |v108|, 4.0
	v_min_f32_e32 v103, 0x40f00000, v103
	v_bfi_b32 v107, s22, v103, v111
	v_cndmask_b32_e32 v105, 0.5, v185, vcc
	v_cmp_nlt_f32_e64 vcc, |v108|, 2.0
	v_and_b32_e32 v103, 0x7fffffff, v108
	v_bfi_b32 v106, s22, v34, v110
	v_cndmask_b32_e32 v105, v197, v105, vcc
	v_pk_mul_f32 v[106:107], v[106:107], v[102:103] op_sel_hi:[1,0]
	v_pk_fma_f32 v[22:23], v[22:23], 2.0, v[106:107] op_sel_hi:[1,0,1] neg_lo:[0,0,1] neg_hi:[0,0,1]
	v_cmp_lt_f32_e64 vcc, |v109|, 4.0
	v_and_b32_e32 v103, 0x7fffffff, v109
	v_sub_u32_e32 v106, 0x7f000000, v105
	v_mul_f32_e64 v34, |v108|, v106
	v_cndmask_b32_e32 v106, 0.5, v185, vcc
	v_cmp_nlt_f32_e64 vcc, |v109|, 2.0
	v_rndne_f32_e32 v34, v34
	v_mul_f32_e32 v34, v105, v34
	v_cndmask_b32_e32 v106, v197, v106, vcc
	v_min_f32_e32 v34, 0x40f00000, v34
	v_sub_u32_e32 v105, 0x7f000000, v106
	v_mul_f32_e64 v103, |v109|, v105
	v_rndne_f32_e32 v103, v103
	v_pk_mul_f32 v[110:111], v[24:25], v[104:105] op_sel_hi:[1,0]
	v_mul_f32_e32 v103, v106, v103
	v_cmp_lt_f32_e64 vcc, |v110|, 4.0
	v_min_f32_e32 v103, 0x40f00000, v103
	v_bfi_b32 v107, s22, v103, v109
	v_cndmask_b32_e32 v105, 0.5, v185, vcc
	v_cmp_nlt_f32_e64 vcc, |v110|, 2.0
	v_and_b32_e32 v103, 0x7fffffff, v110
	v_bfi_b32 v106, s22, v34, v108
	v_cndmask_b32_e32 v105, v197, v105, vcc
	v_pk_mul_f32 v[106:107], v[106:107], v[102:103] op_sel_hi:[1,0]
	v_pk_fma_f32 v[6:7], v[6:7], 2.0, v[106:107] op_sel_hi:[1,0,1] neg_lo:[0,0,1] neg_hi:[0,0,1]
	v_cmp_lt_f32_e64 vcc, |v111|, 4.0
	v_and_b32_e32 v103, 0x7fffffff, v111
	v_sub_u32_e32 v106, 0x7f000000, v105
	v_mul_f32_e64 v34, |v110|, v106
	v_cndmask_b32_e32 v106, 0.5, v185, vcc
	v_cmp_nlt_f32_e64 vcc, |v111|, 2.0
	v_rndne_f32_e32 v34, v34
	v_mul_f32_e32 v34, v105, v34
	v_cndmask_b32_e32 v106, v197, v106, vcc
	v_min_f32_e32 v34, 0x40f00000, v34
	v_sub_u32_e32 v105, 0x7f000000, v106
	v_mul_f32_e64 v103, |v111|, v105
	v_rndne_f32_e32 v103, v103
	v_pk_mul_f32 v[108:109], v[8:9], v[104:105] op_sel_hi:[1,0]
	v_mul_f32_e32 v103, v106, v103
	v_cmp_lt_f32_e64 vcc, |v108|, 4.0
	v_min_f32_e32 v103, 0x40f00000, v103
	v_bfi_b32 v107, s22, v103, v111
	v_cndmask_b32_e32 v105, 0.5, v185, vcc
	v_cmp_nlt_f32_e64 vcc, |v108|, 2.0
	v_and_b32_e32 v103, 0x7fffffff, v108
	v_bfi_b32 v106, s22, v34, v110
	v_cndmask_b32_e32 v105, v197, v105, vcc
	v_pk_mul_f32 v[106:107], v[106:107], v[102:103] op_sel_hi:[1,0]
	v_pk_fma_f32 v[24:25], v[24:25], 2.0, v[106:107] op_sel_hi:[1,0,1] neg_lo:[0,0,1] neg_hi:[0,0,1]
	v_cmp_lt_f32_e64 vcc, |v109|, 4.0
	v_and_b32_e32 v103, 0x7fffffff, v109
	v_sub_u32_e32 v106, 0x7f000000, v105
	v_mul_f32_e64 v34, |v108|, v106
	v_cndmask_b32_e32 v106, 0.5, v185, vcc
	v_cmp_nlt_f32_e64 vcc, |v109|, 2.0
	v_rndne_f32_e32 v34, v34
	v_mul_f32_e32 v34, v105, v34
	v_cndmask_b32_e32 v106, v197, v106, vcc
	v_min_f32_e32 v34, 0x40f00000, v34
	v_sub_u32_e32 v105, 0x7f000000, v106
	v_mul_f32_e64 v103, |v109|, v105
	v_rndne_f32_e32 v103, v103
	v_pk_mul_f32 v[110:111], v[26:27], v[104:105] op_sel_hi:[1,0]
	v_mul_f32_e32 v103, v106, v103
	v_cmp_lt_f32_e64 vcc, |v110|, 4.0
	v_min_f32_e32 v103, 0x40f00000, v103
	v_bfi_b32 v107, s22, v103, v109
	v_cndmask_b32_e32 v105, 0.5, v185, vcc
	v_cmp_nlt_f32_e64 vcc, |v110|, 2.0
	v_and_b32_e32 v103, 0x7fffffff, v110
	v_bfi_b32 v106, s22, v34, v108
	v_cndmask_b32_e32 v105, v197, v105, vcc
	v_pk_mul_f32 v[106:107], v[106:107], v[102:103] op_sel_hi:[1,0]
	v_pk_fma_f32 v[8:9], v[8:9], 2.0, v[106:107] op_sel_hi:[1,0,1] neg_lo:[0,0,1] neg_hi:[0,0,1]
	v_cmp_lt_f32_e64 vcc, |v111|, 4.0
	v_and_b32_e32 v103, 0x7fffffff, v111
	v_sub_u32_e32 v106, 0x7f000000, v105
	v_mul_f32_e64 v34, |v110|, v106
	v_cndmask_b32_e32 v106, 0.5, v185, vcc
	v_cmp_nlt_f32_e64 vcc, |v111|, 2.0
	v_rndne_f32_e32 v34, v34
	v_mul_f32_e32 v34, v105, v34
	v_cndmask_b32_e32 v106, v197, v106, vcc
	v_min_f32_e32 v34, 0x40f00000, v34
	v_sub_u32_e32 v105, 0x7f000000, v106
	v_mul_f32_e64 v103, |v111|, v105
	v_rndne_f32_e32 v103, v103
	v_pk_mul_f32 v[108:109], v[10:11], v[104:105] op_sel_hi:[1,0]
	v_mul_f32_e32 v103, v106, v103
	v_cmp_lt_f32_e64 vcc, |v108|, 4.0
	v_min_f32_e32 v103, 0x40f00000, v103
	v_bfi_b32 v107, s22, v103, v111
	v_cndmask_b32_e32 v105, 0.5, v185, vcc
	v_cmp_nlt_f32_e64 vcc, |v108|, 2.0
	v_and_b32_e32 v103, 0x7fffffff, v108
	v_bfi_b32 v106, s22, v34, v110
	v_cndmask_b32_e32 v105, v197, v105, vcc
	v_pk_mul_f32 v[106:107], v[106:107], v[102:103] op_sel_hi:[1,0]
	v_pk_fma_f32 v[26:27], v[26:27], 2.0, v[106:107] op_sel_hi:[1,0,1] neg_lo:[0,0,1] neg_hi:[0,0,1]
	v_cmp_lt_f32_e64 vcc, |v109|, 4.0
	v_and_b32_e32 v103, 0x7fffffff, v109
	v_sub_u32_e32 v106, 0x7f000000, v105
	v_mul_f32_e64 v34, |v108|, v106
	v_cndmask_b32_e32 v106, 0.5, v185, vcc
	v_cmp_nlt_f32_e64 vcc, |v109|, 2.0
	v_rndne_f32_e32 v34, v34
	v_mul_f32_e32 v34, v105, v34
	v_cndmask_b32_e32 v106, v197, v106, vcc
	v_min_f32_e32 v34, 0x40f00000, v34
	v_sub_u32_e32 v105, 0x7f000000, v106
	v_mul_f32_e64 v103, |v109|, v105
	v_rndne_f32_e32 v103, v103
	v_pk_mul_f32 v[110:111], v[28:29], v[104:105] op_sel_hi:[1,0]
	v_mul_f32_e32 v103, v106, v103
	v_cmp_lt_f32_e64 vcc, |v110|, 4.0
	v_min_f32_e32 v103, 0x40f00000, v103
	v_bfi_b32 v107, s22, v103, v109
	v_cndmask_b32_e32 v105, 0.5, v185, vcc
	v_cmp_nlt_f32_e64 vcc, |v110|, 2.0
	v_and_b32_e32 v103, 0x7fffffff, v110
	v_bfi_b32 v106, s22, v34, v108
	v_cndmask_b32_e32 v105, v197, v105, vcc
	v_pk_mul_f32 v[106:107], v[106:107], v[102:103] op_sel_hi:[1,0]
	v_pk_fma_f32 v[10:11], v[10:11], 2.0, v[106:107] op_sel_hi:[1,0,1] neg_lo:[0,0,1] neg_hi:[0,0,1]
	v_cmp_lt_f32_e64 vcc, |v111|, 4.0
	v_and_b32_e32 v103, 0x7fffffff, v111
	v_sub_u32_e32 v106, 0x7f000000, v105
	v_mul_f32_e64 v34, |v110|, v106
	v_cndmask_b32_e32 v106, 0.5, v185, vcc
	v_cmp_nlt_f32_e64 vcc, |v111|, 2.0
	v_rndne_f32_e32 v34, v34
	v_mul_f32_e32 v34, v105, v34
	v_cndmask_b32_e32 v106, v197, v106, vcc
	v_min_f32_e32 v34, 0x40f00000, v34
	v_sub_u32_e32 v105, 0x7f000000, v106
	v_mul_f32_e64 v103, |v111|, v105
	v_rndne_f32_e32 v103, v103
	v_pk_mul_f32 v[108:109], v[12:13], v[104:105] op_sel_hi:[1,0]
	v_mul_f32_e32 v103, v106, v103
	v_cmp_lt_f32_e64 vcc, |v108|, 4.0
	v_min_f32_e32 v103, 0x40f00000, v103
	v_bfi_b32 v107, s22, v103, v111
	v_cndmask_b32_e32 v105, 0.5, v185, vcc
	v_cmp_nlt_f32_e64 vcc, |v108|, 2.0
	v_and_b32_e32 v103, 0x7fffffff, v108
	v_bfi_b32 v106, s22, v34, v110
	v_cndmask_b32_e32 v105, v197, v105, vcc
	v_pk_mul_f32 v[106:107], v[106:107], v[102:103] op_sel_hi:[1,0]
	v_pk_fma_f32 v[28:29], v[28:29], 2.0, v[106:107] op_sel_hi:[1,0,1] neg_lo:[0,0,1] neg_hi:[0,0,1]
	v_cmp_lt_f32_e64 vcc, |v109|, 4.0
	v_and_b32_e32 v103, 0x7fffffff, v109
	v_sub_u32_e32 v106, 0x7f000000, v105
	v_mul_f32_e64 v34, |v108|, v106
	v_cndmask_b32_e32 v106, 0.5, v185, vcc
	v_cmp_nlt_f32_e64 vcc, |v109|, 2.0
	v_rndne_f32_e32 v34, v34
	v_mul_f32_e32 v34, v105, v34
	v_cndmask_b32_e32 v106, v197, v106, vcc
	v_min_f32_e32 v34, 0x40f00000, v34
	v_sub_u32_e32 v105, 0x7f000000, v106
	v_mul_f32_e64 v103, |v109|, v105
	v_rndne_f32_e32 v103, v103
	v_pk_mul_f32 v[110:111], v[30:31], v[104:105] op_sel_hi:[1,0]
	v_mul_f32_e32 v103, v106, v103
	v_cmp_lt_f32_e64 vcc, |v110|, 4.0
	v_min_f32_e32 v103, 0x40f00000, v103
	v_bfi_b32 v107, s22, v103, v109
	v_cndmask_b32_e32 v105, 0.5, v185, vcc
	v_cmp_nlt_f32_e64 vcc, |v110|, 2.0
	v_and_b32_e32 v103, 0x7fffffff, v110
	v_bfi_b32 v106, s22, v34, v108
	v_cndmask_b32_e32 v105, v197, v105, vcc
	v_pk_mul_f32 v[106:107], v[106:107], v[102:103] op_sel_hi:[1,0]
	v_pk_fma_f32 v[12:13], v[12:13], 2.0, v[106:107] op_sel_hi:[1,0,1] neg_lo:[0,0,1] neg_hi:[0,0,1]
	v_cmp_lt_f32_e64 vcc, |v111|, 4.0
	v_and_b32_e32 v103, 0x7fffffff, v111
	v_sub_u32_e32 v106, 0x7f000000, v105
	v_mul_f32_e64 v34, |v110|, v106
	v_cndmask_b32_e32 v106, 0.5, v185, vcc
	v_cmp_nlt_f32_e64 vcc, |v111|, 2.0
	v_rndne_f32_e32 v34, v34
	v_mul_f32_e32 v34, v105, v34
	v_cndmask_b32_e32 v106, v197, v106, vcc
	v_min_f32_e32 v34, 0x40f00000, v34
	v_sub_u32_e32 v105, 0x7f000000, v106
	v_mul_f32_e64 v103, |v111|, v105
	v_rndne_f32_e32 v103, v103
	v_pk_mul_f32 v[108:109], v[14:15], v[104:105] op_sel_hi:[1,0]
	v_mul_f32_e32 v103, v106, v103
	v_cmp_lt_f32_e64 vcc, |v108|, 4.0
	v_min_f32_e32 v103, 0x40f00000, v103
	v_bfi_b32 v107, s22, v103, v111
	v_cndmask_b32_e32 v105, 0.5, v185, vcc
	v_cmp_nlt_f32_e64 vcc, |v108|, 2.0
	v_and_b32_e32 v103, 0x7fffffff, v108
	v_bfi_b32 v106, s22, v34, v110
	v_cndmask_b32_e32 v105, v197, v105, vcc
	v_pk_mul_f32 v[106:107], v[106:107], v[102:103] op_sel_hi:[1,0]
	v_pk_fma_f32 v[30:31], v[30:31], 2.0, v[106:107] op_sel_hi:[1,0,1] neg_lo:[0,0,1] neg_hi:[0,0,1]
	v_cmp_lt_f32_e64 vcc, |v109|, 4.0
	v_and_b32_e32 v103, 0x7fffffff, v109
	v_sub_u32_e32 v106, 0x7f000000, v105
	v_mul_f32_e64 v34, |v108|, v106
	v_cndmask_b32_e32 v106, 0.5, v185, vcc
	v_cmp_nlt_f32_e64 vcc, |v109|, 2.0
	v_rndne_f32_e32 v34, v34
	v_mul_f32_e32 v34, v105, v34
	v_cndmask_b32_e32 v106, v197, v106, vcc
	v_min_f32_e32 v34, 0x40f00000, v34
	v_sub_u32_e32 v105, 0x7f000000, v106
	v_mul_f32_e64 v103, |v109|, v105
	v_rndne_f32_e32 v103, v103
	v_mul_f32_e32 v103, v106, v103
	v_bfi_b32 v106, s22, v34, v108
	v_mul_f32_e32 v34, v32, v104
	v_cmp_lt_f32_e64 vcc, |v34|, 4.0
	v_min_f32_e32 v103, 0x40f00000, v103
	v_bfi_b32 v107, s22, v103, v109
	v_cndmask_b32_e32 v105, 0.5, v185, vcc
	v_cmp_nlt_f32_e64 vcc, |v34|, 2.0
	v_and_b32_e32 v103, 0x7fffffff, v34
	v_pk_mul_f32 v[106:107], v[106:107], v[102:103] op_sel_hi:[1,0]
	v_cndmask_b32_e32 v105, v197, v105, vcc
	v_pk_fma_f32 v[14:15], v[14:15], 2.0, v[106:107] op_sel_hi:[1,0,1] neg_lo:[0,0,1] neg_hi:[0,0,1]
	v_sub_u32_e32 v106, 0x7f000000, v105
	v_mul_f32_e64 v103, |v34|, v106
	v_rndne_f32_e32 v103, v103
	v_mul_f32_e32 v103, v105, v103
	v_mul_f32_e32 v105, v16, v104
	v_cmp_lt_f32_e64 vcc, |v105|, 4.0
	v_and_b32_e32 v107, 0x7fffffff, v105
	v_min_f32_e32 v103, 0x40f00000, v103
	v_cndmask_b32_e32 v106, 0.5, v185, vcc
	v_cmp_nlt_f32_e64 vcc, |v105|, 2.0
	v_bfi_b32 v34, s22, v103, v34
	v_add_f32_e32 v32, v32, v32
	v_cndmask_b32_e32 v108, v197, v106, vcc
	v_mul_f32_e32 v106, v34, v102
	v_add_f32_e32 v16, v16, v16
	v_sub_u32_e32 v103, 0x7f000000, v108
	v_mul_f32_e64 v34, |v105|, v103
	v_mul_f32_e32 v103, v33, v104
	v_rndne_f32_e32 v34, v34
	v_cmp_lt_f32_e64 vcc, |v103|, 4.0
	v_mul_f32_e32 v34, v108, v34
	v_and_b32_e32 v107, 0x7fffffff, v103
	v_cndmask_b32_e32 v108, 0.5, v185, vcc
	v_cmp_nlt_f32_e64 vcc, |v103|, 2.0
	v_min_f32_e32 v34, 0x40f00000, v34
	v_bfi_b32 v34, s22, v34, v105
	v_cndmask_b32_e32 v109, v197, v108, vcc
	v_mul_f32_e32 v108, v34, v102
	v_sub_u32_e32 v105, 0x7f000000, v109
	v_mul_f32_e64 v34, |v103|, v105
	v_rndne_f32_e32 v34, v34
	v_mul_f32_e32 v34, v109, v34
	v_min_f32_e32 v34, 0x40f00000, v34
	v_bfi_b32 v111, s22, v34, v103
	v_mul_f32_e32 v34, v17, v104
	v_cmp_lt_f32_e64 vcc, |v34|, 4.0
	v_mov_b32_e32 v110, v33
	v_and_b32_e32 v104, 0x7fffffff, v34
	v_cndmask_b32_e32 v33, 0.5, v185, vcc
	v_cmp_nlt_f32_e64 vcc, |v34|, 2.0
	v_pk_mul_f32 v[102:103], v[110:111], v[138:139]
	s_nop 0
	v_cndmask_b32_e32 v105, v197, v33, vcc
	v_mov_b32_e32 v33, v102
	v_mov_b32_e32 v107, v103
	v_pk_add_f32 v[32:33], v[32:33], v[106:107] neg_lo:[0,1] neg_hi:[0,1]
	v_sub_u32_e32 v103, 0x7f000000, v105
	v_mul_f32_e64 v102, |v34|, v103
	v_rndne_f32_e32 v102, v102
	v_mul_f32_e32 v102, v105, v102
	v_min_f32_e32 v102, 0x40f00000, v102
	v_bfi_b32 v103, s22, v102, v34
	v_mov_b32_e32 v102, v17
	v_pk_mul_f32 v[102:103], v[102:103], v[138:139]
	v_max_f32_e64 v34, |v18|, |v2|
	v_mov_b32_e32 v17, v102
	v_max_f32_e64 v102, |v19|, |v3|
	v_mov_b32_e32 v109, v103
	v_max3_f32 v34, v34, 0, v102
	v_max_f32_e64 v102, |v20|, |v4|
	v_max_f32_e64 v103, |v21|, |v5|
	v_max3_f32 v34, v34, v102, v103
	v_max_f32_e64 v102, |v22|, |v6|
	v_max_f32_e64 v103, |v23|, |v7|
	v_max3_f32 v34, v34, v102, v103
	v_max_f32_e64 v102, |v24|, |v8|
	v_max_f32_e64 v103, |v25|, |v9|
	v_max3_f32 v34, v34, v102, v103
	v_max_f32_e64 v102, |v26|, |v10|
	v_max_f32_e64 v103, |v27|, |v11|
	v_max3_f32 v34, v34, v102, v103
	v_max_f32_e64 v102, |v28|, |v12|
	v_max_f32_e64 v103, |v29|, |v13|
	v_pk_add_f32 v[16:17], v[16:17], v[108:109] neg_lo:[0,1] neg_hi:[0,1]
	v_max3_f32 v34, v34, v102, v103
	v_max_f32_e64 v102, |v30|, |v14|
	v_max_f32_e64 v103, |v31|, |v15|
	v_max3_f32 v34, v34, v102, v103
	v_max_f32_e64 v102, |v32|, |v16|
	v_max_f32_e64 v103, |v33|, |v17|
	v_max3_f32 v34, v34, v102, v103
	v_bfe_u32 v102, v34, 23, 8
	v_and_b32_e32 v34, 0x7fffff, v34
	v_cmp_gt_u32_e32 vcc, s11, v34
	s_nop 1
	v_cndmask_b32_e64 v34, -2, -3, vcc
	v_add3_u32 v34, v102, v34, s0
	v_max_i32_e32 v34, 0xffffff88, v34
	v_add_u32_e32 v34, 0x7f, v34
	v_lshlrev_b32_e32 v108, 23, v34
	v_cvt_scalef32_2xpk16_fp6_f32 v[102:107], v[18:33], v[2:17], v108
	v_lshl_add_u64 v[2:3], v[100:101], 0, v[190:191]
	v_mul_lo_u32 v34, v34, s1
	v_lshl_add_u64 v[2:3], v[2:3], 0, v[188:189]
	v_mov_b32_e32 v32, v106
	v_mov_b32_e32 v33, v107
	global_store_dwordx4 v[2:3], v[102:105], off
	global_store_dwordx4 v[2:3], v[32:35], off offset:16

.LBB0_607:
	s_or_b64 exec, exec, s[58:59]
	v_mul_f32_e32 v2, 0x3dd53b94, v206
	v_pk_mul_f32 v[32:33], v[2:3], v[98:99] op_sel_hi:[0,1]
	v_pk_mul_f32 v[30:31], v[2:3], v[96:97] op_sel_hi:[0,1]
	v_pk_mul_f32 v[28:29], v[2:3], v[94:95] op_sel_hi:[0,1]
	v_pk_mul_f32 v[26:27], v[2:3], v[92:93] op_sel_hi:[0,1]
	v_pk_mul_f32 v[24:25], v[2:3], v[90:91] op_sel_hi:[0,1]
	v_pk_mul_f32 v[22:23], v[2:3], v[88:89] op_sel_hi:[0,1]
	v_pk_mul_f32 v[20:21], v[2:3], v[86:87] op_sel_hi:[0,1]
	v_pk_mul_f32 v[18:19], v[2:3], v[84:85] op_sel_hi:[0,1]
	v_pk_mul_f32 v[16:17], v[2:3], v[82:83] op_sel_hi:[0,1]
	v_pk_mul_f32 v[14:15], v[2:3], v[80:81] op_sel_hi:[0,1]
	v_pk_mul_f32 v[12:13], v[2:3], v[78:79] op_sel_hi:[0,1]
	v_pk_mul_f32 v[10:11], v[2:3], v[76:77] op_sel_hi:[0,1]
	v_pk_mul_f32 v[8:9], v[2:3], v[74:75] op_sel_hi:[0,1]
	v_pk_mul_f32 v[6:7], v[2:3], v[72:73] op_sel_hi:[0,1]
	v_pk_mul_f32 v[4:5], v[2:3], v[70:71] op_sel_hi:[0,1]
	v_pk_mul_f32 v[2:3], v[2:3], v[68:69] op_sel_hi:[0,1]
	v_max_f32_e64 v68, |v18|, |v2|
	v_max_f32_e64 v69, |v19|, |v3|
	v_max3_f32 v68, v68, 0, v69
	v_max_f32_e64 v69, |v20|, |v4|
	v_max_f32_e64 v70, |v21|, |v5|
	v_max3_f32 v68, v68, v69, v70
	v_max_f32_e64 v69, |v22|, |v6|
	v_max_f32_e64 v70, |v23|, |v7|
	v_max3_f32 v68, v68, v69, v70
	v_max_f32_e64 v69, |v24|, |v8|
	v_max_f32_e64 v70, |v25|, |v9|
	v_max3_f32 v68, v68, v69, v70
	v_max_f32_e64 v69, |v26|, |v10|
	v_max_f32_e64 v70, |v27|, |v11|
	v_max3_f32 v68, v68, v69, v70
	v_max_f32_e64 v69, |v28|, |v12|
	v_max_f32_e64 v70, |v29|, |v13|
	v_max3_f32 v68, v68, v69, v70
	v_max_f32_e64 v69, |v30|, |v14|
	v_max_f32_e64 v70, |v31|, |v15|
	v_max3_f32 v68, v68, v69, v70
	v_max_f32_e64 v69, |v32|, |v16|
	v_max_f32_e64 v70, |v33|, |v17|
	v_max3_f32 v68, v68, v69, v70
	v_cmp_gt_u32_e32 vcc, 64, v104
	v_bfe_u32 v69, v68, 23, 8
	v_and_b32_e32 v68, 0x7fffff, v68
	v_cndmask_b32_e32 v34, v177, v181, vcc
	v_cndmask_b32_e64 v102, 64, 0, vcc
	v_cmp_gt_u32_e32 vcc, s11, v68
	v_ashrrev_i32_e32 v73, 31, v208
	v_and_b32_e32 v100, 32, v104
	v_cndmask_b32_e64 v68, -2, -3, vcc
	v_add3_u32 v68, v69, v68, s0
	v_max_i32_e32 v68, 0xffffff88, v68
	v_add_u32_e32 v68, 0x7f, v68
	v_lshlrev_b32_e32 v72, 23, v68
	v_mul_lo_u32 v82, v68, s1
	v_mov_b64_e32 v[68:69], s[26:27]
	v_mad_i64_i32 v[70:71], s[4:5], v141, s10, v[68:69]
	v_ashrrev_i32_e32 v69, 31, v104
	v_sub_co_u32_e32 v68, vcc, v208, v104
	v_mov_b32_e32 v101, v35
	s_nop 0
	v_subb_co_u32_e32 v69, vcc, v73, v69, vcc
	v_lshl_add_u64 v[70:71], v[68:69], 1, v[70:71]
	v_lshl_add_u64 v[84:85], v[70:71], 0, v[34:35]
	v_cvt_scalef32_2xpk16_fp6_f32 v[76:81], v[18:33], v[2:17], v72
	v_sub_u32_e32 v74, 0x7f000000, v72
	v_lshl_add_u64 v[84:85], v[84:85], 0, v[100:101]
	global_store_dwordx4 v[84:85], v[76:79], off offset:256
	v_mov_b32_e32 v83, v35
	global_store_dwordx4 v[84:85], v[80:83], off offset:272
	v_pk_mul_f32 v[76:77], v[18:19], v[74:75] op_sel_hi:[1,0]
	v_mov_b32_e32 v103, v35
	v_cmp_lt_f32_e64 vcc, |v76|, 4.0
	v_and_b32_e32 v73, 0x7fffffff, v76
	v_permlane32_swap_b32_e32 v52, v36
	v_cndmask_b32_e32 v75, 0.5, v185, vcc
	v_cmp_nlt_f32_e64 vcc, |v76|, 2.0
	v_permlane32_swap_b32_e32 v53, v37
	s_nop 0
	v_cndmask_b32_e32 v75, v197, v75, vcc
	v_permlane32_swap_b32_e32 v54, v38
	v_cmp_lt_f32_e64 vcc, |v77|, 4.0
	v_and_b32_e32 v78, 0x7fffffff, v77
	v_sub_u32_e32 v79, 0x7f000000, v75
	v_mul_f32_e64 v73, |v76|, v79
	v_cndmask_b32_e32 v79, 0.5, v185, vcc
	v_cmp_nlt_f32_e64 vcc, |v77|, 2.0
	v_rndne_f32_e32 v73, v73
	v_mul_f32_e32 v73, v75, v73
	v_cndmask_b32_e32 v79, v197, v79, vcc
	v_min_f32_e32 v73, 0x40f00000, v73
	v_bfi_b32 v76, s22, v73, v76
	v_permlane32_swap_b32_e32 v55, v39
	v_sub_u32_e32 v78, 0x7f000000, v79
	v_mul_f32_e64 v75, |v77|, v78
	v_rndne_f32_e32 v75, v75
	v_mul_f32_e32 v75, v79, v75
	v_min_f32_e32 v75, 0x40f00000, v75
	v_pk_mul_f32 v[78:79], v[2:3], v[74:75] op_sel_hi:[1,0]
	v_bfi_b32 v77, s22, v75, v77
	v_cmp_lt_f32_e64 vcc, |v78|, 4.0
	v_and_b32_e32 v75, 0x7fffffff, v78
	v_pk_mul_f32 v[76:77], v[76:77], v[72:73] op_sel_hi:[1,0]
	v_cndmask_b32_e32 v80, 0.5, v185, vcc
	v_cmp_nlt_f32_e64 vcc, |v78|, 2.0
	v_pk_fma_f32 v[18:19], v[18:19], 2.0, v[76:77] op_sel_hi:[1,0,1] neg_lo:[0,0,1] neg_hi:[0,0,1]
	v_permlane32_swap_b32_e32 v56, v44
	v_cndmask_b32_e32 v80, v197, v80, vcc
	v_permlane32_swap_b32_e32 v57, v45
	v_permlane32_swap_b32_e32 v58, v46
	v_cmp_lt_f32_e64 vcc, |v79|, 4.0
	v_and_b32_e32 v75, 0x7fffffff, v79
	v_sub_u32_e32 v76, 0x7f000000, v80
	v_mul_f32_e64 v73, |v78|, v76
	v_cndmask_b32_e32 v76, 0.5, v185, vcc
	v_cmp_nlt_f32_e64 vcc, |v79|, 2.0
	v_rndne_f32_e32 v73, v73
	v_mul_f32_e32 v73, v80, v73
	v_cndmask_b32_e32 v76, v197, v76, vcc
	v_min_f32_e32 v73, 0x40f00000, v73
	v_sub_u32_e32 v77, 0x7f000000, v76
	v_mul_f32_e64 v75, |v79|, v77
	v_rndne_f32_e32 v75, v75
	v_mul_f32_e32 v75, v76, v75
	v_min_f32_e32 v75, 0x40f00000, v75
	v_pk_mul_f32 v[80:81], v[20:21], v[74:75] op_sel_hi:[1,0]
	v_bfi_b32 v77, s22, v75, v79
	v_cmp_lt_f32_e64 vcc, |v80|, 4.0
	v_and_b32_e32 v75, 0x7fffffff, v80
	v_permlane32_swap_b32_e32 v59, v47
	v_cndmask_b32_e32 v76, 0.5, v185, vcc
	v_cmp_nlt_f32_e64 vcc, |v80|, 2.0
	v_permlane32_swap_b32_e32 v60, v48
	s_nop 0
	v_cndmask_b32_e32 v79, v197, v76, vcc
	v_bfi_b32 v76, s22, v73, v78
	v_pk_mul_f32 v[76:77], v[76:77], v[72:73] op_sel_hi:[1,0]
	v_permlane32_swap_b32_e32 v61, v49
	v_pk_fma_f32 v[2:3], v[2:3], 2.0, v[76:77] op_sel_hi:[1,0,1] neg_lo:[0,0,1] neg_hi:[0,0,1]
	v_cmp_lt_f32_e64 vcc, |v81|, 4.0
	v_and_b32_e32 v75, 0x7fffffff, v81
	v_sub_u32_e32 v76, 0x7f000000, v79
	v_mul_f32_e64 v73, |v80|, v76
	v_cndmask_b32_e32 v76, 0.5, v185, vcc
	v_cmp_nlt_f32_e64 vcc, |v81|, 2.0
	v_rndne_f32_e32 v73, v73
	v_mul_f32_e32 v73, v79, v73
	v_cndmask_b32_e32 v76, v197, v76, vcc
	v_min_f32_e32 v73, 0x40f00000, v73
	v_sub_u32_e32 v77, 0x7f000000, v76
	v_mul_f32_e64 v75, |v81|, v77
	v_rndne_f32_e32 v75, v75
	v_mul_f32_e32 v75, v76, v75
	v_min_f32_e32 v75, 0x40f00000, v75
	v_pk_mul_f32 v[78:79], v[4:5], v[74:75] op_sel_hi:[1,0]
	v_bfi_b32 v77, s22, v75, v81
	v_cmp_lt_f32_e64 vcc, |v78|, 4.0
	v_and_b32_e32 v75, 0x7fffffff, v78
	v_permlane32_swap_b32_e32 v62, v50
	v_cndmask_b32_e32 v76, 0.5, v185, vcc
	v_cmp_nlt_f32_e64 vcc, |v78|, 2.0
	v_permlane32_swap_b32_e32 v63, v51
	s_nop 0
	v_cndmask_b32_e32 v81, v197, v76, vcc
	v_bfi_b32 v76, s22, v73, v80
	v_pk_mul_f32 v[76:77], v[76:77], v[72:73] op_sel_hi:[1,0]
	v_permlane32_swap_b32_e32 v64, v40
	v_pk_fma_f32 v[20:21], v[20:21], 2.0, v[76:77] op_sel_hi:[1,0,1] neg_lo:[0,0,1] neg_hi:[0,0,1]
	v_cmp_lt_f32_e64 vcc, |v79|, 4.0
	v_and_b32_e32 v75, 0x7fffffff, v79
	v_sub_u32_e32 v76, 0x7f000000, v81
	v_mul_f32_e64 v73, |v78|, v76
	v_cndmask_b32_e32 v76, 0.5, v185, vcc
	v_cmp_nlt_f32_e64 vcc, |v79|, 2.0
	v_rndne_f32_e32 v73, v73
	v_mul_f32_e32 v73, v81, v73
	v_cndmask_b32_e32 v76, v197, v76, vcc
	v_min_f32_e32 v73, 0x40f00000, v73
	v_sub_u32_e32 v77, 0x7f000000, v76
	v_mul_f32_e64 v75, |v79|, v77
	v_rndne_f32_e32 v75, v75
	v_mul_f32_e32 v75, v76, v75
	v_min_f32_e32 v75, 0x40f00000, v75
	v_pk_mul_f32 v[80:81], v[22:23], v[74:75] op_sel_hi:[1,0]
	v_bfi_b32 v77, s22, v75, v79
	v_cmp_lt_f32_e64 vcc, |v80|, 4.0
	v_and_b32_e32 v75, 0x7fffffff, v80
	v_permlane32_swap_b32_e32 v65, v41
	v_cndmask_b32_e32 v76, 0.5, v185, vcc
	v_cmp_nlt_f32_e64 vcc, |v80|, 2.0
	v_permlane32_swap_b32_e32 v66, v42
	s_nop 0
	v_cndmask_b32_e32 v79, v197, v76, vcc
	v_bfi_b32 v76, s22, v73, v78
	v_pk_mul_f32 v[76:77], v[76:77], v[72:73] op_sel_hi:[1,0]
	v_permlane32_swap_b32_e32 v67, v43
	v_pk_fma_f32 v[4:5], v[4:5], 2.0, v[76:77] op_sel_hi:[1,0,1] neg_lo:[0,0,1] neg_hi:[0,0,1]
	v_cmp_lt_f32_e64 vcc, |v81|, 4.0
	v_and_b32_e32 v75, 0x7fffffff, v81
	v_sub_u32_e32 v76, 0x7f000000, v79
	v_mul_f32_e64 v73, |v80|, v76
	v_cndmask_b32_e32 v76, 0.5, v185, vcc
	v_cmp_nlt_f32_e64 vcc, |v81|, 2.0
	v_rndne_f32_e32 v73, v73
	v_mul_f32_e32 v73, v79, v73
	v_cndmask_b32_e32 v76, v197, v76, vcc
	v_min_f32_e32 v73, 0x40f00000, v73
	v_sub_u32_e32 v77, 0x7f000000, v76
	v_mul_f32_e64 v75, |v81|, v77
	v_rndne_f32_e32 v75, v75
	v_mul_f32_e32 v75, v76, v75
	v_min_f32_e32 v75, 0x40f00000, v75
	v_pk_mul_f32 v[78:79], v[6:7], v[74:75] op_sel_hi:[1,0]
	v_bfi_b32 v77, s22, v75, v81
	v_cmp_lt_f32_e64 vcc, |v78|, 4.0
	v_and_b32_e32 v75, 0x7fffffff, v78
	v_permlane16_swap_b32_e32 v52, v60
	v_cndmask_b32_e32 v76, 0.5, v185, vcc
	v_cmp_nlt_f32_e64 vcc, |v78|, 2.0
	v_permlane16_swap_b32_e32 v53, v61
	s_nop 0
	v_cndmask_b32_e32 v81, v197, v76, vcc
	v_bfi_b32 v76, s22, v73, v80
	v_pk_mul_f32 v[76:77], v[76:77], v[72:73] op_sel_hi:[1,0]
	v_permlane16_swap_b32_e32 v54, v62
	v_pk_fma_f32 v[22:23], v[22:23], 2.0, v[76:77] op_sel_hi:[1,0,1] neg_lo:[0,0,1] neg_hi:[0,0,1]
	v_cmp_lt_f32_e64 vcc, |v79|, 4.0
	v_and_b32_e32 v75, 0x7fffffff, v79
	v_sub_u32_e32 v76, 0x7f000000, v81
	v_mul_f32_e64 v73, |v78|, v76
	v_cndmask_b32_e32 v76, 0.5, v185, vcc
	v_cmp_nlt_f32_e64 vcc, |v79|, 2.0
	v_rndne_f32_e32 v73, v73
	v_mul_f32_e32 v73, v81, v73
	v_cndmask_b32_e32 v76, v197, v76, vcc
	v_min_f32_e32 v73, 0x40f00000, v73
	v_sub_u32_e32 v77, 0x7f000000, v76
	v_mul_f32_e64 v75, |v79|, v77
	v_rndne_f32_e32 v75, v75
	v_mul_f32_e32 v75, v76, v75
	v_min_f32_e32 v75, 0x40f00000, v75
	v_pk_mul_f32 v[80:81], v[24:25], v[74:75] op_sel_hi:[1,0]
	v_bfi_b32 v77, s22, v75, v79
	v_cmp_lt_f32_e64 vcc, |v80|, 4.0
	v_and_b32_e32 v75, 0x7fffffff, v80
	v_permlane16_swap_b32_e32 v55, v63
	v_cndmask_b32_e32 v76, 0.5, v185, vcc
	v_cmp_nlt_f32_e64 vcc, |v80|, 2.0
	v_permlane16_swap_b32_e32 v56, v64
	s_nop 0
	v_cndmask_b32_e32 v79, v197, v76, vcc
	v_bfi_b32 v76, s22, v73, v78
	v_pk_mul_f32 v[76:77], v[76:77], v[72:73] op_sel_hi:[1,0]
	v_permlane16_swap_b32_e32 v57, v65
	v_pk_fma_f32 v[6:7], v[6:7], 2.0, v[76:77] op_sel_hi:[1,0,1] neg_lo:[0,0,1] neg_hi:[0,0,1]
	v_cmp_lt_f32_e64 vcc, |v81|, 4.0
	v_and_b32_e32 v75, 0x7fffffff, v81
	v_sub_u32_e32 v76, 0x7f000000, v79
	v_mul_f32_e64 v73, |v80|, v76
	v_cndmask_b32_e32 v76, 0.5, v185, vcc
	v_cmp_nlt_f32_e64 vcc, |v81|, 2.0
	v_rndne_f32_e32 v73, v73
	v_mul_f32_e32 v73, v79, v73
	v_cndmask_b32_e32 v76, v197, v76, vcc
	v_min_f32_e32 v73, 0x40f00000, v73
	v_sub_u32_e32 v77, 0x7f000000, v76
	v_mul_f32_e64 v75, |v81|, v77
	v_rndne_f32_e32 v75, v75
	v_mul_f32_e32 v75, v76, v75
	v_min_f32_e32 v75, 0x40f00000, v75
	v_pk_mul_f32 v[78:79], v[8:9], v[74:75] op_sel_hi:[1,0]
	v_bfi_b32 v77, s22, v75, v81
	v_cmp_lt_f32_e64 vcc, |v78|, 4.0
	v_and_b32_e32 v75, 0x7fffffff, v78
	v_permlane16_swap_b32_e32 v58, v66
	v_cndmask_b32_e32 v76, 0.5, v185, vcc
	v_cmp_nlt_f32_e64 vcc, |v78|, 2.0
	v_permlane16_swap_b32_e32 v59, v67
	s_nop 0
	v_cndmask_b32_e32 v81, v197, v76, vcc
	v_bfi_b32 v76, s22, v73, v80
	v_pk_mul_f32 v[76:77], v[76:77], v[72:73] op_sel_hi:[1,0]
	v_permlane16_swap_b32_e32 v36, v48
	v_pk_fma_f32 v[24:25], v[24:25], 2.0, v[76:77] op_sel_hi:[1,0,1] neg_lo:[0,0,1] neg_hi:[0,0,1]
	v_cmp_lt_f32_e64 vcc, |v79|, 4.0
	v_and_b32_e32 v75, 0x7fffffff, v79
	v_sub_u32_e32 v76, 0x7f000000, v81
	v_mul_f32_e64 v73, |v78|, v76
	v_cndmask_b32_e32 v76, 0.5, v185, vcc
	v_cmp_nlt_f32_e64 vcc, |v79|, 2.0
	v_rndne_f32_e32 v73, v73
	v_mul_f32_e32 v73, v81, v73
	v_cndmask_b32_e32 v76, v197, v76, vcc
	v_min_f32_e32 v73, 0x40f00000, v73
	v_sub_u32_e32 v77, 0x7f000000, v76
	v_mul_f32_e64 v75, |v79|, v77
	v_rndne_f32_e32 v75, v75
	v_mul_f32_e32 v75, v76, v75
	v_min_f32_e32 v75, 0x40f00000, v75
	v_pk_mul_f32 v[80:81], v[26:27], v[74:75] op_sel_hi:[1,0]
	v_bfi_b32 v77, s22, v75, v79
	v_cmp_lt_f32_e64 vcc, |v80|, 4.0
	v_and_b32_e32 v75, 0x7fffffff, v80
	v_permlane16_swap_b32_e32 v37, v49
	v_cndmask_b32_e32 v76, 0.5, v185, vcc
	v_cmp_nlt_f32_e64 vcc, |v80|, 2.0
	v_permlane16_swap_b32_e32 v38, v50
	s_nop 0
	v_cndmask_b32_e32 v79, v197, v76, vcc
	v_bfi_b32 v76, s22, v73, v78
	v_pk_mul_f32 v[76:77], v[76:77], v[72:73] op_sel_hi:[1,0]
	v_permlane16_swap_b32_e32 v39, v51
	v_pk_fma_f32 v[8:9], v[8:9], 2.0, v[76:77] op_sel_hi:[1,0,1] neg_lo:[0,0,1] neg_hi:[0,0,1]
	v_cmp_lt_f32_e64 vcc, |v81|, 4.0
	v_and_b32_e32 v75, 0x7fffffff, v81
	v_sub_u32_e32 v76, 0x7f000000, v79
	v_mul_f32_e64 v73, |v80|, v76
	v_cndmask_b32_e32 v76, 0.5, v185, vcc
	v_cmp_nlt_f32_e64 vcc, |v81|, 2.0
	v_rndne_f32_e32 v73, v73
	v_mul_f32_e32 v73, v79, v73
	v_cndmask_b32_e32 v76, v197, v76, vcc
	v_min_f32_e32 v73, 0x40f00000, v73
	v_sub_u32_e32 v77, 0x7f000000, v76
	v_mul_f32_e64 v75, |v81|, v77
	v_rndne_f32_e32 v75, v75
	v_mul_f32_e32 v75, v76, v75
	v_min_f32_e32 v75, 0x40f00000, v75
	v_pk_mul_f32 v[78:79], v[10:11], v[74:75] op_sel_hi:[1,0]
	v_bfi_b32 v77, s22, v75, v81
	v_cmp_lt_f32_e64 vcc, |v78|, 4.0
	v_and_b32_e32 v75, 0x7fffffff, v78
	v_permlane16_swap_b32_e32 v44, v40
	v_cndmask_b32_e32 v76, 0.5, v185, vcc
	v_cmp_nlt_f32_e64 vcc, |v78|, 2.0
	v_permlane16_swap_b32_e32 v45, v41
	s_nop 0
	v_cndmask_b32_e32 v81, v197, v76, vcc
	v_bfi_b32 v76, s22, v73, v80
	v_pk_mul_f32 v[76:77], v[76:77], v[72:73] op_sel_hi:[1,0]
	v_permlane16_swap_b32_e32 v46, v42
	v_pk_fma_f32 v[26:27], v[26:27], 2.0, v[76:77] op_sel_hi:[1,0,1] neg_lo:[0,0,1] neg_hi:[0,0,1]
	v_cmp_lt_f32_e64 vcc, |v79|, 4.0
	v_and_b32_e32 v75, 0x7fffffff, v79
	v_sub_u32_e32 v76, 0x7f000000, v81
	v_mul_f32_e64 v73, |v78|, v76
	v_cndmask_b32_e32 v76, 0.5, v185, vcc
	v_cmp_nlt_f32_e64 vcc, |v79|, 2.0
	v_rndne_f32_e32 v73, v73
	v_mul_f32_e32 v73, v81, v73
	v_cndmask_b32_e32 v76, v197, v76, vcc
	v_min_f32_e32 v73, 0x40f00000, v73
	v_sub_u32_e32 v77, 0x7f000000, v76
	v_mul_f32_e64 v75, |v79|, v77
	v_rndne_f32_e32 v75, v75
	v_mul_f32_e32 v75, v76, v75
	v_min_f32_e32 v75, 0x40f00000, v75
	v_pk_mul_f32 v[80:81], v[28:29], v[74:75] op_sel_hi:[1,0]
	v_bfi_b32 v77, s22, v75, v79
	v_cmp_lt_f32_e64 vcc, |v80|, 4.0
	v_and_b32_e32 v75, 0x7fffffff, v80
	v_permlane16_swap_b32_e32 v47, v43
	v_cndmask_b32_e32 v76, 0.5, v185, vcc
	v_cmp_nlt_f32_e64 vcc, |v80|, 2.0
	s_nop 1
	v_cndmask_b32_e32 v79, v197, v76, vcc
	v_bfi_b32 v76, s22, v73, v78
	v_pk_mul_f32 v[76:77], v[76:77], v[72:73] op_sel_hi:[1,0]
	v_pk_fma_f32 v[10:11], v[10:11], 2.0, v[76:77] op_sel_hi:[1,0,1] neg_lo:[0,0,1] neg_hi:[0,0,1]
	v_cmp_lt_f32_e64 vcc, |v81|, 4.0
	v_and_b32_e32 v75, 0x7fffffff, v81
	v_sub_u32_e32 v76, 0x7f000000, v79
	v_mul_f32_e64 v73, |v80|, v76
	v_cndmask_b32_e32 v76, 0.5, v185, vcc
	v_cmp_nlt_f32_e64 vcc, |v81|, 2.0
	v_rndne_f32_e32 v73, v73
	v_mul_f32_e32 v73, v79, v73
	v_cndmask_b32_e32 v76, v197, v76, vcc
	v_min_f32_e32 v73, 0x40f00000, v73
	v_sub_u32_e32 v77, 0x7f000000, v76
	v_mul_f32_e64 v75, |v81|, v77
	v_rndne_f32_e32 v75, v75
	v_mul_f32_e32 v75, v76, v75
	v_min_f32_e32 v75, 0x40f00000, v75
	v_pk_mul_f32 v[78:79], v[12:13], v[74:75] op_sel_hi:[1,0]
	v_bfi_b32 v77, s22, v75, v81
	v_cmp_lt_f32_e64 vcc, |v78|, 4.0
	v_and_b32_e32 v75, 0x7fffffff, v78
	s_nop 0
	v_cndmask_b32_e32 v76, 0.5, v185, vcc
	v_cmp_nlt_f32_e64 vcc, |v78|, 2.0
	s_nop 1
	v_cndmask_b32_e32 v81, v197, v76, vcc
	v_bfi_b32 v76, s22, v73, v80
	v_pk_mul_f32 v[76:77], v[76:77], v[72:73] op_sel_hi:[1,0]
	v_pk_fma_f32 v[28:29], v[28:29], 2.0, v[76:77] op_sel_hi:[1,0,1] neg_lo:[0,0,1] neg_hi:[0,0,1]
	v_cmp_lt_f32_e64 vcc, |v79|, 4.0
	v_and_b32_e32 v75, 0x7fffffff, v79
	v_sub_u32_e32 v76, 0x7f000000, v81
	v_mul_f32_e64 v73, |v78|, v76
	v_cndmask_b32_e32 v76, 0.5, v185, vcc
	v_cmp_nlt_f32_e64 vcc, |v79|, 2.0
	v_rndne_f32_e32 v73, v73
	v_mul_f32_e32 v73, v81, v73
	v_cndmask_b32_e32 v76, v197, v76, vcc
	v_min_f32_e32 v73, 0x40f00000, v73
	v_sub_u32_e32 v77, 0x7f000000, v76
	v_mul_f32_e64 v75, |v79|, v77
	v_rndne_f32_e32 v75, v75
	v_mul_f32_e32 v75, v76, v75
	v_min_f32_e32 v75, 0x40f00000, v75
	v_pk_mul_f32 v[80:81], v[30:31], v[74:75] op_sel_hi:[1,0]
	v_bfi_b32 v77, s22, v75, v79
	v_cmp_lt_f32_e64 vcc, |v80|, 4.0
	v_and_b32_e32 v75, 0x7fffffff, v80
	s_nop 0
	v_cndmask_b32_e32 v76, 0.5, v185, vcc
	v_cmp_nlt_f32_e64 vcc, |v80|, 2.0
	s_nop 1
	v_cndmask_b32_e32 v79, v197, v76, vcc
	v_bfi_b32 v76, s22, v73, v78
	v_pk_mul_f32 v[76:77], v[76:77], v[72:73] op_sel_hi:[1,0]
	v_pk_fma_f32 v[12:13], v[12:13], 2.0, v[76:77] op_sel_hi:[1,0,1] neg_lo:[0,0,1] neg_hi:[0,0,1]
	v_cmp_lt_f32_e64 vcc, |v81|, 4.0
	v_and_b32_e32 v75, 0x7fffffff, v81
	v_sub_u32_e32 v76, 0x7f000000, v79
	v_mul_f32_e64 v73, |v80|, v76
	v_cndmask_b32_e32 v76, 0.5, v185, vcc
	v_cmp_nlt_f32_e64 vcc, |v81|, 2.0
	v_rndne_f32_e32 v73, v73
	v_mul_f32_e32 v73, v79, v73
	v_cndmask_b32_e32 v76, v197, v76, vcc
	v_min_f32_e32 v73, 0x40f00000, v73
	v_sub_u32_e32 v77, 0x7f000000, v76
	v_mul_f32_e64 v75, |v81|, v77
	v_rndne_f32_e32 v75, v75
	v_mul_f32_e32 v75, v76, v75
	v_min_f32_e32 v75, 0x40f00000, v75
	v_pk_mul_f32 v[78:79], v[14:15], v[74:75] op_sel_hi:[1,0]
	v_bfi_b32 v77, s22, v75, v81
	v_cmp_lt_f32_e64 vcc, |v78|, 4.0
	v_and_b32_e32 v75, 0x7fffffff, v78
	s_nop 0
	v_cndmask_b32_e32 v76, 0.5, v185, vcc
	v_cmp_nlt_f32_e64 vcc, |v78|, 2.0
	s_nop 1
	v_cndmask_b32_e32 v81, v197, v76, vcc
	v_bfi_b32 v76, s22, v73, v80
	v_pk_mul_f32 v[76:77], v[76:77], v[72:73] op_sel_hi:[1,0]
	v_pk_fma_f32 v[30:31], v[30:31], 2.0, v[76:77] op_sel_hi:[1,0,1] neg_lo:[0,0,1] neg_hi:[0,0,1]
	v_cmp_lt_f32_e64 vcc, |v79|, 4.0
	v_and_b32_e32 v75, 0x7fffffff, v79
	v_sub_u32_e32 v76, 0x7f000000, v81
	v_mul_f32_e64 v73, |v78|, v76
	v_cndmask_b32_e32 v76, 0.5, v185, vcc
	v_cmp_nlt_f32_e64 vcc, |v79|, 2.0
	v_rndne_f32_e32 v73, v73
	v_mul_f32_e32 v73, v81, v73
	v_cndmask_b32_e32 v76, v197, v76, vcc
	v_min_f32_e32 v73, 0x40f00000, v73
	v_sub_u32_e32 v77, 0x7f000000, v76
	v_mul_f32_e64 v75, |v79|, v77
	v_rndne_f32_e32 v75, v75
	v_mul_f32_e32 v75, v76, v75
	v_min_f32_e32 v75, 0x40f00000, v75
	v_pk_mul_f32 v[80:81], v[32:33], v[74:75] op_sel_hi:[1,0]
	v_bfi_b32 v77, s22, v75, v79
	v_cmp_lt_f32_e64 vcc, |v80|, 4.0
	v_and_b32_e32 v75, 0x7fffffff, v80
	s_nop 0
	v_cndmask_b32_e32 v76, 0.5, v185, vcc
	v_cmp_nlt_f32_e64 vcc, |v80|, 2.0
	s_nop 1
	v_cndmask_b32_e32 v79, v197, v76, vcc
	v_bfi_b32 v76, s22, v73, v78
	v_pk_mul_f32 v[76:77], v[76:77], v[72:73] op_sel_hi:[1,0]
	v_pk_fma_f32 v[14:15], v[14:15], 2.0, v[76:77] op_sel_hi:[1,0,1] neg_lo:[0,0,1] neg_hi:[0,0,1]
	v_cmp_lt_f32_e64 vcc, |v81|, 4.0
	v_and_b32_e32 v75, 0x7fffffff, v81
	v_sub_u32_e32 v76, 0x7f000000, v79
	v_mul_f32_e64 v73, |v80|, v76
	v_cndmask_b32_e32 v76, 0.5, v185, vcc
	v_cmp_nlt_f32_e64 vcc, |v81|, 2.0
	v_rndne_f32_e32 v73, v73
	v_mul_f32_e32 v73, v79, v73
	v_cndmask_b32_e32 v76, v197, v76, vcc
	v_min_f32_e32 v73, 0x40f00000, v73
	v_sub_u32_e32 v77, 0x7f000000, v76
	v_mul_f32_e64 v75, |v81|, v77
	v_rndne_f32_e32 v75, v75
	v_mul_f32_e32 v75, v76, v75
	v_min_f32_e32 v75, 0x40f00000, v75
	v_bfi_b32 v75, s22, v75, v81
	v_pk_mul_f32 v[76:77], v[16:17], v[74:75] op_sel_hi:[1,0]
	s_nop 0
	v_cmp_lt_f32_e64 vcc, |v76|, 4.0
	v_and_b32_e32 v78, 0x7fffffff, v76
	s_nop 0
	v_cndmask_b32_e32 v74, 0.5, v185, vcc
	v_cmp_nlt_f32_e64 vcc, |v76|, 2.0
	s_nop 1
	v_cndmask_b32_e32 v79, v197, v74, vcc
	v_bfi_b32 v74, s22, v73, v80
	v_pk_mul_f32 v[74:75], v[74:75], v[72:73] op_sel_hi:[1,0]
	v_pk_fma_f32 v[32:33], v[32:33], 2.0, v[74:75] op_sel_hi:[1,0,1] neg_lo:[0,0,1] neg_hi:[0,0,1]
	v_cmp_lt_f32_e64 vcc, |v77|, 4.0
	v_and_b32_e32 v74, 0x7fffffff, v77
	v_sub_u32_e32 v75, 0x7f000000, v79
	v_mul_f32_e64 v73, |v76|, v75
	v_cndmask_b32_e32 v75, 0.5, v185, vcc
	v_cmp_nlt_f32_e64 vcc, |v77|, 2.0
	v_rndne_f32_e32 v73, v73
	v_mul_f32_e32 v73, v79, v73
	v_cndmask_b32_e32 v75, v197, v75, vcc
	v_min_f32_e32 v73, 0x40f00000, v73
	v_sub_u32_e32 v78, 0x7f000000, v75
	v_mul_f32_e64 v74, |v77|, v78
	v_rndne_f32_e32 v74, v74
	v_mul_f32_e32 v74, v75, v74
	v_min_f32_e32 v74, 0x40f00000, v74
	v_bfi_b32 v75, s22, v74, v77
	v_bfi_b32 v74, s22, v73, v76
	v_pk_mul_f32 v[72:73], v[74:75], v[72:73] op_sel_hi:[1,0]
	v_max_f32_e64 v74, |v21|, |v5|
	v_pk_fma_f32 v[16:17], v[16:17], 2.0, v[72:73] op_sel_hi:[1,0,1] neg_lo:[0,0,1] neg_hi:[0,0,1]
	v_max_f32_e64 v72, |v18|, |v2|
	v_max_f32_e64 v73, |v19|, |v3|
	v_max3_f32 v72, v72, 0, v73
	v_max_f32_e64 v73, |v20|, |v4|
	v_max3_f32 v72, v72, v73, v74
	v_max_f32_e64 v73, |v22|, |v6|
	v_max_f32_e64 v74, |v23|, |v7|
	v_max3_f32 v72, v72, v73, v74
	v_max_f32_e64 v73, |v24|, |v8|
	v_max_f32_e64 v74, |v25|, |v9|
	v_max3_f32 v72, v72, v73, v74
	v_max_f32_e64 v73, |v26|, |v10|
	v_max_f32_e64 v74, |v27|, |v11|
	v_max3_f32 v72, v72, v73, v74
	v_max_f32_e64 v73, |v28|, |v12|
	v_max_f32_e64 v74, |v29|, |v13|
	v_max3_f32 v72, v72, v73, v74
	v_max_f32_e64 v73, |v30|, |v14|
	v_max_f32_e64 v74, |v31|, |v15|
	v_max3_f32 v72, v72, v73, v74
	v_max_f32_e64 v73, |v32|, |v16|
	v_max_f32_e64 v74, |v33|, |v17|
	v_max3_f32 v72, v72, v73, v74
	v_bfe_u32 v73, v72, 23, 8
	v_and_b32_e32 v72, 0x7fffff, v72
	v_cmp_gt_u32_e32 vcc, s11, v72
	s_nop 1
	v_cndmask_b32_e64 v72, -2, -3, vcc
	v_add3_u32 v72, v73, v72, s0
	v_max_i32_e32 v72, 0xffffff88, v72
	v_add_u32_e32 v72, 0x7f, v72
	v_lshlrev_b32_e32 v79, 23, v72
	v_mul_lo_u32 v78, v72, s1
	v_cvt_scalef32_2xpk16_fp6_f32 v[72:77], v[18:33], v[2:17], v79
	v_lshl_add_u64 v[2:3], v[70:71], 0, v[102:103]
	v_lshl_add_u64 v[2:3], v[2:3], 0, v[100:101]
	v_mov_b32_e32 v79, v35
	v_cmp_lt_i32_e32 vcc, 1, v199
	global_store_dwordx4 v[2:3], v[72:75], off offset:256
	global_store_dwordx4 v[2:3], v[76:79], off offset:272
	s_and_saveexec_b64 s[4:5], vcc
	s_xor_b64 s[4:5], exec, s[4:5]
	s_cbranch_execz .LBB0_611
	v_cmp_gt_i32_e32 vcc, 3, v199
	s_and_saveexec_b64 s[58:59], vcc
	v_mov_b32_e32 v207, v204
	s_or_b64 exec, exec, s[58:59]

.LBB0_617:
	s_or_b64 exec, exec, s[58:59]
	v_mul_f32_e32 v2, 0x3dd53b94, v207
	v_pk_mul_f32 v[32:33], v[2:3], v[66:67] op_sel_hi:[0,1]
	v_pk_mul_f32 v[30:31], v[2:3], v[64:65] op_sel_hi:[0,1]
	v_pk_mul_f32 v[28:29], v[2:3], v[62:63] op_sel_hi:[0,1]
	v_pk_mul_f32 v[26:27], v[2:3], v[60:61] op_sel_hi:[0,1]
	v_pk_mul_f32 v[24:25], v[2:3], v[58:59] op_sel_hi:[0,1]
	v_pk_mul_f32 v[22:23], v[2:3], v[56:57] op_sel_hi:[0,1]
	v_pk_mul_f32 v[20:21], v[2:3], v[54:55] op_sel_hi:[0,1]
	v_pk_mul_f32 v[18:19], v[2:3], v[52:53] op_sel_hi:[0,1]
	v_pk_mul_f32 v[16:17], v[2:3], v[42:43] op_sel_hi:[0,1]
	v_pk_mul_f32 v[14:15], v[2:3], v[40:41] op_sel_hi:[0,1]
	v_pk_mul_f32 v[12:13], v[2:3], v[50:51] op_sel_hi:[0,1]
	v_pk_mul_f32 v[10:11], v[2:3], v[48:49] op_sel_hi:[0,1]
	v_pk_mul_f32 v[8:9], v[2:3], v[46:47] op_sel_hi:[0,1]
	v_pk_mul_f32 v[6:7], v[2:3], v[44:45] op_sel_hi:[0,1]
	v_pk_mul_f32 v[4:5], v[2:3], v[38:39] op_sel_hi:[0,1]
	v_pk_mul_f32 v[2:3], v[2:3], v[36:37] op_sel_hi:[0,1]
	v_max_f32_e64 v36, |v18|, |v2|
	v_max_f32_e64 v37, |v19|, |v3|
	v_max3_f32 v36, v36, 0, v37
	v_max_f32_e64 v37, |v20|, |v4|
	v_max_f32_e64 v38, |v21|, |v5|
	v_max3_f32 v36, v36, v37, v38
	v_max_f32_e64 v37, |v22|, |v6|
	v_max_f32_e64 v38, |v23|, |v7|
	v_max3_f32 v36, v36, v37, v38
	v_max_f32_e64 v37, |v24|, |v8|
	v_max_f32_e64 v38, |v25|, |v9|
	v_max3_f32 v36, v36, v37, v38
	v_max_f32_e64 v37, |v26|, |v10|
	v_max_f32_e64 v38, |v27|, |v11|
	v_max3_f32 v36, v36, v37, v38
	v_max_f32_e64 v37, |v28|, |v12|
	v_max_f32_e64 v38, |v29|, |v13|
	v_max3_f32 v36, v36, v37, v38
	v_max_f32_e64 v37, |v30|, |v14|
	v_max_f32_e64 v38, |v31|, |v15|
	v_max3_f32 v36, v36, v37, v38
	v_max_f32_e64 v37, |v32|, |v16|
	v_max_f32_e64 v38, |v33|, |v17|
	v_max3_f32 v36, v36, v37, v38
	v_bfe_u32 v37, v36, 23, 8
	v_and_b32_e32 v36, 0x7fffff, v36
	v_cmp_gt_u32_e32 vcc, s11, v36
	v_add_u32_e32 v39, 0x80, v141
	v_mov_b32_e32 v49, v35
	v_cndmask_b32_e64 v36, -2, -3, vcc
	v_add3_u32 v36, v37, v36, s0
	v_max_i32_e32 v36, 0xffffff88, v36
	v_add_u32_e32 v36, 0x7f, v36
	v_lshlrev_b32_e32 v38, 23, v36
	v_mul_lo_u32 v48, v36, s1
	v_mov_b64_e32 v[36:37], s[26:27]
	v_mad_i64_i32 v[36:37], s[4:5], v39, s10, v[36:37]
	v_lshl_add_u64 v[36:37], v[68:69], 1, v[36:37]
	v_lshl_add_u64 v[50:51], v[36:37], 0, v[34:35]
	v_cvt_scalef32_2xpk16_fp6_f32 v[42:47], v[18:33], v[2:17], v38
	v_sub_u32_e32 v40, 0x7f000000, v38
	v_lshl_add_u64 v[50:51], v[50:51], 0, v[100:101]
	global_store_dwordx4 v[50:51], v[42:45], off offset:256
	global_store_dwordx4 v[50:51], v[46:49], off offset:272
	s_nop 0
	v_pk_mul_f32 v[42:43], v[18:19], v[40:41] op_sel_hi:[1,0]
	s_nop 0
	v_cmp_lt_f32_e64 vcc, |v42|, 4.0
	v_and_b32_e32 v34, 0x7fffffff, v42
	s_nop 0
	v_cndmask_b32_e32 v39, 0.5, v185, vcc
	v_cmp_nlt_f32_e64 vcc, |v42|, 2.0
	s_nop 1
	v_cndmask_b32_e32 v39, v197, v39, vcc
	v_cmp_lt_f32_e64 vcc, |v43|, 4.0
	v_and_b32_e32 v41, 0x7fffffff, v43
	v_sub_u32_e32 v44, 0x7f000000, v39
	v_mul_f32_e64 v34, |v42|, v44
	v_cndmask_b32_e32 v44, 0.5, v185, vcc
	v_cmp_nlt_f32_e64 vcc, |v43|, 2.0
	v_rndne_f32_e32 v34, v34
	v_mul_f32_e32 v34, v39, v34
	v_cndmask_b32_e32 v44, v197, v44, vcc
	v_min_f32_e32 v34, 0x40f00000, v34
	v_bfi_b32 v42, s22, v34, v42
	v_sub_u32_e32 v41, 0x7f000000, v44
	v_mul_f32_e64 v39, |v43|, v41
	v_rndne_f32_e32 v39, v39
	v_mul_f32_e32 v39, v44, v39
	v_pk_mul_f32 v[44:45], v[2:3], v[40:41] op_sel_hi:[1,0]
	v_min_f32_e32 v39, 0x40f00000, v39
	v_cmp_lt_f32_e64 vcc, |v44|, 4.0
	v_bfi_b32 v43, s22, v39, v43
	v_and_b32_e32 v39, 0x7fffffff, v44
	v_cndmask_b32_e32 v41, 0.5, v185, vcc
	v_cmp_nlt_f32_e64 vcc, |v44|, 2.0
	v_pk_mul_f32 v[42:43], v[42:43], v[38:39] op_sel_hi:[1,0]
	s_nop 0
	v_cndmask_b32_e32 v41, v197, v41, vcc
	v_pk_fma_f32 v[18:19], v[18:19], 2.0, v[42:43] op_sel_hi:[1,0,1] neg_lo:[0,0,1] neg_hi:[0,0,1]
	v_cmp_lt_f32_e64 vcc, |v45|, 4.0
	v_and_b32_e32 v39, 0x7fffffff, v45
	v_sub_u32_e32 v42, 0x7f000000, v41
	v_mul_f32_e64 v34, |v44|, v42
	v_cndmask_b32_e32 v42, 0.5, v185, vcc
	v_cmp_nlt_f32_e64 vcc, |v45|, 2.0
	v_rndne_f32_e32 v34, v34
	v_mul_f32_e32 v34, v41, v34
	v_cndmask_b32_e32 v42, v197, v42, vcc
	v_min_f32_e32 v34, 0x40f00000, v34
	v_sub_u32_e32 v41, 0x7f000000, v42
	v_mul_f32_e64 v39, |v45|, v41
	v_rndne_f32_e32 v39, v39
	v_pk_mul_f32 v[46:47], v[20:21], v[40:41] op_sel_hi:[1,0]
	v_mul_f32_e32 v39, v42, v39
	v_cmp_lt_f32_e64 vcc, |v46|, 4.0
	v_min_f32_e32 v39, 0x40f00000, v39
	v_bfi_b32 v43, s22, v39, v45
	v_cndmask_b32_e32 v41, 0.5, v185, vcc
	v_cmp_nlt_f32_e64 vcc, |v46|, 2.0
	v_and_b32_e32 v39, 0x7fffffff, v46
	v_bfi_b32 v42, s22, v34, v44
	v_cndmask_b32_e32 v41, v197, v41, vcc
	v_pk_mul_f32 v[42:43], v[42:43], v[38:39] op_sel_hi:[1,0]
	v_pk_fma_f32 v[2:3], v[2:3], 2.0, v[42:43] op_sel_hi:[1,0,1] neg_lo:[0,0,1] neg_hi:[0,0,1]
	v_cmp_lt_f32_e64 vcc, |v47|, 4.0
	v_and_b32_e32 v39, 0x7fffffff, v47
	v_sub_u32_e32 v42, 0x7f000000, v41
	v_mul_f32_e64 v34, |v46|, v42
	v_cndmask_b32_e32 v42, 0.5, v185, vcc
	v_cmp_nlt_f32_e64 vcc, |v47|, 2.0
	v_rndne_f32_e32 v34, v34
	v_mul_f32_e32 v34, v41, v34
	v_cndmask_b32_e32 v42, v197, v42, vcc
	v_min_f32_e32 v34, 0x40f00000, v34
	v_sub_u32_e32 v41, 0x7f000000, v42
	v_mul_f32_e64 v39, |v47|, v41
	v_rndne_f32_e32 v39, v39
	v_pk_mul_f32 v[44:45], v[4:5], v[40:41] op_sel_hi:[1,0]
	v_mul_f32_e32 v39, v42, v39
	v_cmp_lt_f32_e64 vcc, |v44|, 4.0
	v_min_f32_e32 v39, 0x40f00000, v39
	v_bfi_b32 v43, s22, v39, v47
	v_cndmask_b32_e32 v41, 0.5, v185, vcc
	v_cmp_nlt_f32_e64 vcc, |v44|, 2.0
	v_and_b32_e32 v39, 0x7fffffff, v44
	v_bfi_b32 v42, s22, v34, v46
	v_cndmask_b32_e32 v41, v197, v41, vcc
	v_pk_mul_f32 v[42:43], v[42:43], v[38:39] op_sel_hi:[1,0]
	v_pk_fma_f32 v[20:21], v[20:21], 2.0, v[42:43] op_sel_hi:[1,0,1] neg_lo:[0,0,1] neg_hi:[0,0,1]
	v_cmp_lt_f32_e64 vcc, |v45|, 4.0
	v_and_b32_e32 v39, 0x7fffffff, v45
	v_sub_u32_e32 v42, 0x7f000000, v41
	v_mul_f32_e64 v34, |v44|, v42
	v_cndmask_b32_e32 v42, 0.5, v185, vcc
	v_cmp_nlt_f32_e64 vcc, |v45|, 2.0
	v_rndne_f32_e32 v34, v34
	v_mul_f32_e32 v34, v41, v34
	v_cndmask_b32_e32 v42, v197, v42, vcc
	v_min_f32_e32 v34, 0x40f00000, v34
	v_sub_u32_e32 v41, 0x7f000000, v42
	v_mul_f32_e64 v39, |v45|, v41
	v_rndne_f32_e32 v39, v39
	v_pk_mul_f32 v[46:47], v[22:23], v[40:41] op_sel_hi:[1,0]
	v_mul_f32_e32 v39, v42, v39
	v_cmp_lt_f32_e64 vcc, |v46|, 4.0
	v_min_f32_e32 v39, 0x40f00000, v39
	v_bfi_b32 v43, s22, v39, v45
	v_cndmask_b32_e32 v41, 0.5, v185, vcc
	v_cmp_nlt_f32_e64 vcc, |v46|, 2.0
	v_and_b32_e32 v39, 0x7fffffff, v46
	v_bfi_b32 v42, s22, v34, v44
	v_cndmask_b32_e32 v41, v197, v41, vcc
	v_pk_mul_f32 v[42:43], v[42:43], v[38:39] op_sel_hi:[1,0]
	v_pk_fma_f32 v[4:5], v[4:5], 2.0, v[42:43] op_sel_hi:[1,0,1] neg_lo:[0,0,1] neg_hi:[0,0,1]
	v_cmp_lt_f32_e64 vcc, |v47|, 4.0
	v_and_b32_e32 v39, 0x7fffffff, v47
	v_sub_u32_e32 v42, 0x7f000000, v41
	v_mul_f32_e64 v34, |v46|, v42
	v_cndmask_b32_e32 v42, 0.5, v185, vcc
	v_cmp_nlt_f32_e64 vcc, |v47|, 2.0
	v_rndne_f32_e32 v34, v34
	v_mul_f32_e32 v34, v41, v34
	v_cndmask_b32_e32 v42, v197, v42, vcc
	v_min_f32_e32 v34, 0x40f00000, v34
	v_sub_u32_e32 v41, 0x7f000000, v42
	v_mul_f32_e64 v39, |v47|, v41
	v_rndne_f32_e32 v39, v39
	v_pk_mul_f32 v[44:45], v[6:7], v[40:41] op_sel_hi:[1,0]
	v_mul_f32_e32 v39, v42, v39
	v_cmp_lt_f32_e64 vcc, |v44|, 4.0
	v_min_f32_e32 v39, 0x40f00000, v39
	v_bfi_b32 v43, s22, v39, v47
	v_cndmask_b32_e32 v41, 0.5, v185, vcc
	v_cmp_nlt_f32_e64 vcc, |v44|, 2.0
	v_and_b32_e32 v39, 0x7fffffff, v44
	v_bfi_b32 v42, s22, v34, v46
	v_cndmask_b32_e32 v41, v197, v41, vcc
	v_pk_mul_f32 v[42:43], v[42:43], v[38:39] op_sel_hi:[1,0]
	v_pk_fma_f32 v[22:23], v[22:23], 2.0, v[42:43] op_sel_hi:[1,0,1] neg_lo:[0,0,1] neg_hi:[0,0,1]
	v_cmp_lt_f32_e64 vcc, |v45|, 4.0
	v_and_b32_e32 v39, 0x7fffffff, v45
	v_sub_u32_e32 v42, 0x7f000000, v41
	v_mul_f32_e64 v34, |v44|, v42
	v_cndmask_b32_e32 v42, 0.5, v185, vcc
	v_cmp_nlt_f32_e64 vcc, |v45|, 2.0
	v_rndne_f32_e32 v34, v34
	v_mul_f32_e32 v34, v41, v34
	v_cndmask_b32_e32 v42, v197, v42, vcc
	v_min_f32_e32 v34, 0x40f00000, v34
	v_sub_u32_e32 v41, 0x7f000000, v42
	v_mul_f32_e64 v39, |v45|, v41
	v_rndne_f32_e32 v39, v39
	v_pk_mul_f32 v[46:47], v[24:25], v[40:41] op_sel_hi:[1,0]
	v_mul_f32_e32 v39, v42, v39
	v_cmp_lt_f32_e64 vcc, |v46|, 4.0
	v_min_f32_e32 v39, 0x40f00000, v39
	v_bfi_b32 v43, s22, v39, v45
	v_cndmask_b32_e32 v41, 0.5, v185, vcc
	v_cmp_nlt_f32_e64 vcc, |v46|, 2.0
	v_and_b32_e32 v39, 0x7fffffff, v46
	v_bfi_b32 v42, s22, v34, v44
	v_cndmask_b32_e32 v41, v197, v41, vcc
	v_pk_mul_f32 v[42:43], v[42:43], v[38:39] op_sel_hi:[1,0]
	v_pk_fma_f32 v[6:7], v[6:7], 2.0, v[42:43] op_sel_hi:[1,0,1] neg_lo:[0,0,1] neg_hi:[0,0,1]
	v_cmp_lt_f32_e64 vcc, |v47|, 4.0
	v_and_b32_e32 v39, 0x7fffffff, v47
	v_sub_u32_e32 v42, 0x7f000000, v41
	v_mul_f32_e64 v34, |v46|, v42
	v_cndmask_b32_e32 v42, 0.5, v185, vcc
	v_cmp_nlt_f32_e64 vcc, |v47|, 2.0
	v_rndne_f32_e32 v34, v34
	v_mul_f32_e32 v34, v41, v34
	v_cndmask_b32_e32 v42, v197, v42, vcc
	v_min_f32_e32 v34, 0x40f00000, v34
	v_sub_u32_e32 v41, 0x7f000000, v42
	v_mul_f32_e64 v39, |v47|, v41
	v_rndne_f32_e32 v39, v39
	v_pk_mul_f32 v[44:45], v[8:9], v[40:41] op_sel_hi:[1,0]
	v_mul_f32_e32 v39, v42, v39
	v_cmp_lt_f32_e64 vcc, |v44|, 4.0
	v_min_f32_e32 v39, 0x40f00000, v39
	v_bfi_b32 v43, s22, v39, v47
	v_cndmask_b32_e32 v41, 0.5, v185, vcc
	v_cmp_nlt_f32_e64 vcc, |v44|, 2.0
	v_and_b32_e32 v39, 0x7fffffff, v44
	v_bfi_b32 v42, s22, v34, v46
	v_cndmask_b32_e32 v41, v197, v41, vcc
	v_pk_mul_f32 v[42:43], v[42:43], v[38:39] op_sel_hi:[1,0]
	v_pk_fma_f32 v[24:25], v[24:25], 2.0, v[42:43] op_sel_hi:[1,0,1] neg_lo:[0,0,1] neg_hi:[0,0,1]
	v_cmp_lt_f32_e64 vcc, |v45|, 4.0
	v_and_b32_e32 v39, 0x7fffffff, v45
	v_sub_u32_e32 v42, 0x7f000000, v41
	v_mul_f32_e64 v34, |v44|, v42
	v_cndmask_b32_e32 v42, 0.5, v185, vcc
	v_cmp_nlt_f32_e64 vcc, |v45|, 2.0
	v_rndne_f32_e32 v34, v34
	v_mul_f32_e32 v34, v41, v34
	v_cndmask_b32_e32 v42, v197, v42, vcc
	v_min_f32_e32 v34, 0x40f00000, v34
	v_sub_u32_e32 v41, 0x7f000000, v42
	v_mul_f32_e64 v39, |v45|, v41
	v_rndne_f32_e32 v39, v39
	v_pk_mul_f32 v[46:47], v[26:27], v[40:41] op_sel_hi:[1,0]
	v_mul_f32_e32 v39, v42, v39
	v_cmp_lt_f32_e64 vcc, |v46|, 4.0
	v_min_f32_e32 v39, 0x40f00000, v39
	v_bfi_b32 v43, s22, v39, v45
	v_cndmask_b32_e32 v41, 0.5, v185, vcc
	v_cmp_nlt_f32_e64 vcc, |v46|, 2.0
	v_and_b32_e32 v39, 0x7fffffff, v46
	v_bfi_b32 v42, s22, v34, v44
	v_cndmask_b32_e32 v41, v197, v41, vcc
	v_pk_mul_f32 v[42:43], v[42:43], v[38:39] op_sel_hi:[1,0]
	v_pk_fma_f32 v[8:9], v[8:9], 2.0, v[42:43] op_sel_hi:[1,0,1] neg_lo:[0,0,1] neg_hi:[0,0,1]
	v_cmp_lt_f32_e64 vcc, |v47|, 4.0
	v_and_b32_e32 v39, 0x7fffffff, v47
	v_sub_u32_e32 v42, 0x7f000000, v41
	v_mul_f32_e64 v34, |v46|, v42
	v_cndmask_b32_e32 v42, 0.5, v185, vcc
	v_cmp_nlt_f32_e64 vcc, |v47|, 2.0
	v_rndne_f32_e32 v34, v34
	v_mul_f32_e32 v34, v41, v34
	v_cndmask_b32_e32 v42, v197, v42, vcc
	v_min_f32_e32 v34, 0x40f00000, v34
	v_sub_u32_e32 v41, 0x7f000000, v42
	v_mul_f32_e64 v39, |v47|, v41
	v_rndne_f32_e32 v39, v39
	v_pk_mul_f32 v[44:45], v[10:11], v[40:41] op_sel_hi:[1,0]
	v_mul_f32_e32 v39, v42, v39
	v_cmp_lt_f32_e64 vcc, |v44|, 4.0
	v_min_f32_e32 v39, 0x40f00000, v39
	v_bfi_b32 v43, s22, v39, v47
	v_cndmask_b32_e32 v41, 0.5, v185, vcc
	v_cmp_nlt_f32_e64 vcc, |v44|, 2.0
	v_and_b32_e32 v39, 0x7fffffff, v44
	v_bfi_b32 v42, s22, v34, v46
	v_cndmask_b32_e32 v41, v197, v41, vcc
	v_pk_mul_f32 v[42:43], v[42:43], v[38:39] op_sel_hi:[1,0]
	v_pk_fma_f32 v[26:27], v[26:27], 2.0, v[42:43] op_sel_hi:[1,0,1] neg_lo:[0,0,1] neg_hi:[0,0,1]
	v_cmp_lt_f32_e64 vcc, |v45|, 4.0
	v_and_b32_e32 v39, 0x7fffffff, v45
	v_sub_u32_e32 v42, 0x7f000000, v41
	v_mul_f32_e64 v34, |v44|, v42
	v_cndmask_b32_e32 v42, 0.5, v185, vcc
	v_cmp_nlt_f32_e64 vcc, |v45|, 2.0
	v_rndne_f32_e32 v34, v34
	v_mul_f32_e32 v34, v41, v34
	v_cndmask_b32_e32 v42, v197, v42, vcc
	v_min_f32_e32 v34, 0x40f00000, v34
	v_sub_u32_e32 v41, 0x7f000000, v42
	v_mul_f32_e64 v39, |v45|, v41
	v_rndne_f32_e32 v39, v39
	v_pk_mul_f32 v[46:47], v[28:29], v[40:41] op_sel_hi:[1,0]
	v_mul_f32_e32 v39, v42, v39
	v_cmp_lt_f32_e64 vcc, |v46|, 4.0
	v_min_f32_e32 v39, 0x40f00000, v39
	v_bfi_b32 v43, s22, v39, v45
	v_cndmask_b32_e32 v41, 0.5, v185, vcc
	v_cmp_nlt_f32_e64 vcc, |v46|, 2.0
	v_and_b32_e32 v39, 0x7fffffff, v46
	v_bfi_b32 v42, s22, v34, v44
	v_cndmask_b32_e32 v41, v197, v41, vcc
	v_pk_mul_f32 v[42:43], v[42:43], v[38:39] op_sel_hi:[1,0]
	v_pk_fma_f32 v[10:11], v[10:11], 2.0, v[42:43] op_sel_hi:[1,0,1] neg_lo:[0,0,1] neg_hi:[0,0,1]
	v_cmp_lt_f32_e64 vcc, |v47|, 4.0
	v_and_b32_e32 v39, 0x7fffffff, v47
	v_sub_u32_e32 v42, 0x7f000000, v41
	v_mul_f32_e64 v34, |v46|, v42
	v_cndmask_b32_e32 v42, 0.5, v185, vcc
	v_cmp_nlt_f32_e64 vcc, |v47|, 2.0
	v_rndne_f32_e32 v34, v34
	v_mul_f32_e32 v34, v41, v34
	v_cndmask_b32_e32 v42, v197, v42, vcc
	v_min_f32_e32 v34, 0x40f00000, v34
	v_sub_u32_e32 v41, 0x7f000000, v42
	v_mul_f32_e64 v39, |v47|, v41
	v_rndne_f32_e32 v39, v39
	v_pk_mul_f32 v[44:45], v[12:13], v[40:41] op_sel_hi:[1,0]
	v_mul_f32_e32 v39, v42, v39
	v_cmp_lt_f32_e64 vcc, |v44|, 4.0
	v_min_f32_e32 v39, 0x40f00000, v39
	v_bfi_b32 v43, s22, v39, v47
	v_cndmask_b32_e32 v41, 0.5, v185, vcc
	v_cmp_nlt_f32_e64 vcc, |v44|, 2.0
	v_and_b32_e32 v39, 0x7fffffff, v44
	v_bfi_b32 v42, s22, v34, v46
	v_cndmask_b32_e32 v41, v197, v41, vcc
	v_pk_mul_f32 v[42:43], v[42:43], v[38:39] op_sel_hi:[1,0]
	v_pk_fma_f32 v[28:29], v[28:29], 2.0, v[42:43] op_sel_hi:[1,0,1] neg_lo:[0,0,1] neg_hi:[0,0,1]
	v_cmp_lt_f32_e64 vcc, |v45|, 4.0
	v_and_b32_e32 v39, 0x7fffffff, v45
	v_sub_u32_e32 v42, 0x7f000000, v41
	v_mul_f32_e64 v34, |v44|, v42
	v_cndmask_b32_e32 v42, 0.5, v185, vcc
	v_cmp_nlt_f32_e64 vcc, |v45|, 2.0
	v_rndne_f32_e32 v34, v34
	v_mul_f32_e32 v34, v41, v34
	v_cndmask_b32_e32 v42, v197, v42, vcc
	v_min_f32_e32 v34, 0x40f00000, v34
	v_sub_u32_e32 v41, 0x7f000000, v42
	v_mul_f32_e64 v39, |v45|, v41
	v_rndne_f32_e32 v39, v39
	v_pk_mul_f32 v[46:47], v[30:31], v[40:41] op_sel_hi:[1,0]
	v_mul_f32_e32 v39, v42, v39
	v_cmp_lt_f32_e64 vcc, |v46|, 4.0
	v_min_f32_e32 v39, 0x40f00000, v39
	v_bfi_b32 v43, s22, v39, v45
	v_cndmask_b32_e32 v41, 0.5, v185, vcc
	v_cmp_nlt_f32_e64 vcc, |v46|, 2.0
	v_and_b32_e32 v39, 0x7fffffff, v46
	v_bfi_b32 v42, s22, v34, v44
	v_cndmask_b32_e32 v41, v197, v41, vcc
	v_pk_mul_f32 v[42:43], v[42:43], v[38:39] op_sel_hi:[1,0]
	v_pk_fma_f32 v[12:13], v[12:13], 2.0, v[42:43] op_sel_hi:[1,0,1] neg_lo:[0,0,1] neg_hi:[0,0,1]
	v_cmp_lt_f32_e64 vcc, |v47|, 4.0
	v_and_b32_e32 v39, 0x7fffffff, v47
	v_sub_u32_e32 v42, 0x7f000000, v41
	v_mul_f32_e64 v34, |v46|, v42
	v_cndmask_b32_e32 v42, 0.5, v185, vcc
	v_cmp_nlt_f32_e64 vcc, |v47|, 2.0
	v_rndne_f32_e32 v34, v34
	v_mul_f32_e32 v34, v41, v34
	v_cndmask_b32_e32 v42, v197, v42, vcc
	v_min_f32_e32 v34, 0x40f00000, v34
	v_sub_u32_e32 v41, 0x7f000000, v42
	v_mul_f32_e64 v39, |v47|, v41
	v_rndne_f32_e32 v39, v39
	v_pk_mul_f32 v[44:45], v[14:15], v[40:41] op_sel_hi:[1,0]
	v_mul_f32_e32 v39, v42, v39
	v_cmp_lt_f32_e64 vcc, |v44|, 4.0
	v_min_f32_e32 v39, 0x40f00000, v39
	v_bfi_b32 v43, s22, v39, v47
	v_cndmask_b32_e32 v41, 0.5, v185, vcc
	v_cmp_nlt_f32_e64 vcc, |v44|, 2.0
	v_and_b32_e32 v39, 0x7fffffff, v44
	v_bfi_b32 v42, s22, v34, v46
	v_cndmask_b32_e32 v41, v197, v41, vcc
	v_pk_mul_f32 v[42:43], v[42:43], v[38:39] op_sel_hi:[1,0]
	v_pk_fma_f32 v[30:31], v[30:31], 2.0, v[42:43] op_sel_hi:[1,0,1] neg_lo:[0,0,1] neg_hi:[0,0,1]
	v_cmp_lt_f32_e64 vcc, |v45|, 4.0
	v_and_b32_e32 v39, 0x7fffffff, v45
	v_sub_u32_e32 v42, 0x7f000000, v41
	v_mul_f32_e64 v34, |v44|, v42
	v_cndmask_b32_e32 v42, 0.5, v185, vcc
	v_cmp_nlt_f32_e64 vcc, |v45|, 2.0
	v_rndne_f32_e32 v34, v34
	v_mul_f32_e32 v34, v41, v34
	v_cndmask_b32_e32 v42, v197, v42, vcc
	v_min_f32_e32 v34, 0x40f00000, v34
	v_sub_u32_e32 v41, 0x7f000000, v42
	v_mul_f32_e64 v39, |v45|, v41
	v_rndne_f32_e32 v39, v39
	v_pk_mul_f32 v[46:47], v[32:33], v[40:41] op_sel_hi:[1,0]
	v_mul_f32_e32 v39, v42, v39
	v_cmp_lt_f32_e64 vcc, |v46|, 4.0
	v_min_f32_e32 v39, 0x40f00000, v39
	v_bfi_b32 v43, s22, v39, v45
	v_cndmask_b32_e32 v41, 0.5, v185, vcc
	v_cmp_nlt_f32_e64 vcc, |v46|, 2.0
	v_and_b32_e32 v39, 0x7fffffff, v46
	v_bfi_b32 v42, s22, v34, v44
	v_cndmask_b32_e32 v41, v197, v41, vcc
	v_pk_mul_f32 v[42:43], v[42:43], v[38:39] op_sel_hi:[1,0]
	v_pk_fma_f32 v[14:15], v[14:15], 2.0, v[42:43] op_sel_hi:[1,0,1] neg_lo:[0,0,1] neg_hi:[0,0,1]
	v_cmp_lt_f32_e64 vcc, |v47|, 4.0
	v_and_b32_e32 v39, 0x7fffffff, v47
	v_sub_u32_e32 v42, 0x7f000000, v41
	v_mul_f32_e64 v34, |v46|, v42
	v_cndmask_b32_e32 v42, 0.5, v185, vcc
	v_cmp_nlt_f32_e64 vcc, |v47|, 2.0
	v_rndne_f32_e32 v34, v34
	v_mul_f32_e32 v34, v41, v34
	v_cndmask_b32_e32 v42, v197, v42, vcc
	v_min_f32_e32 v34, 0x40f00000, v34
	v_sub_u32_e32 v41, 0x7f000000, v42
	v_mul_f32_e64 v39, |v47|, v41
	v_rndne_f32_e32 v39, v39
	v_mul_f32_e32 v39, v42, v39
	v_min_f32_e32 v39, 0x40f00000, v39
	v_bfi_b32 v41, s22, v39, v47
	v_pk_mul_f32 v[42:43], v[16:17], v[40:41] op_sel_hi:[1,0]
	s_nop 0
	v_cmp_lt_f32_e64 vcc, |v42|, 4.0
	v_and_b32_e32 v39, 0x7fffffff, v42
	s_nop 0
	v_cndmask_b32_e32 v40, 0.5, v185, vcc
	v_cmp_nlt_f32_e64 vcc, |v42|, 2.0
	s_nop 1
	v_cndmask_b32_e32 v44, v197, v40, vcc
	v_bfi_b32 v40, s22, v34, v46
	v_pk_mul_f32 v[40:41], v[40:41], v[38:39] op_sel_hi:[1,0]
	v_pk_fma_f32 v[32:33], v[32:33], 2.0, v[40:41] op_sel_hi:[1,0,1] neg_lo:[0,0,1] neg_hi:[0,0,1]
	v_cmp_lt_f32_e64 vcc, |v43|, 4.0
	v_and_b32_e32 v39, 0x7fffffff, v43
	v_sub_u32_e32 v40, 0x7f000000, v44
	v_mul_f32_e64 v34, |v42|, v40
	v_cndmask_b32_e32 v40, 0.5, v185, vcc
	v_cmp_nlt_f32_e64 vcc, |v43|, 2.0
	v_rndne_f32_e32 v34, v34
	v_mul_f32_e32 v34, v44, v34
	v_cndmask_b32_e32 v40, v197, v40, vcc
	v_min_f32_e32 v34, 0x40f00000, v34
	v_sub_u32_e32 v41, 0x7f000000, v40
	v_mul_f32_e64 v39, |v43|, v41
	v_rndne_f32_e32 v39, v39
	v_mul_f32_e32 v39, v40, v39
	v_min_f32_e32 v39, 0x40f00000, v39
	v_bfi_b32 v41, s22, v39, v43
	v_bfi_b32 v40, s22, v34, v42
	v_pk_mul_f32 v[38:39], v[40:41], v[38:39] op_sel_hi:[1,0]
	v_max_f32_e64 v34, |v18|, |v2|
	v_pk_fma_f32 v[16:17], v[16:17], 2.0, v[38:39] op_sel_hi:[1,0,1] neg_lo:[0,0,1] neg_hi:[0,0,1]
	v_max_f32_e64 v38, |v19|, |v3|
	v_max3_f32 v34, v34, 0, v38
	v_max_f32_e64 v38, |v20|, |v4|
	v_max_f32_e64 v39, |v21|, |v5|
	v_max3_f32 v34, v34, v38, v39
	v_max_f32_e64 v38, |v22|, |v6|
	v_max_f32_e64 v39, |v23|, |v7|
	v_max3_f32 v34, v34, v38, v39
	v_max_f32_e64 v38, |v24|, |v8|
	v_max_f32_e64 v39, |v25|, |v9|
	v_max3_f32 v34, v34, v38, v39
	v_max_f32_e64 v38, |v26|, |v10|
	v_max_f32_e64 v39, |v27|, |v11|
	v_max3_f32 v34, v34, v38, v39
	v_max_f32_e64 v38, |v28|, |v12|
	v_max_f32_e64 v39, |v29|, |v13|
	v_max3_f32 v34, v34, v38, v39
	v_max_f32_e64 v38, |v30|, |v14|
	v_max_f32_e64 v39, |v31|, |v15|
	v_max3_f32 v34, v34, v38, v39
	v_max_f32_e64 v38, |v32|, |v16|
	v_max_f32_e64 v39, |v33|, |v17|
	v_max3_f32 v34, v34, v38, v39
	v_bfe_u32 v38, v34, 23, 8
	v_and_b32_e32 v34, 0x7fffff, v34
	v_cmp_gt_u32_e32 vcc, s11, v34
	s_nop 1
	v_cndmask_b32_e64 v34, -2, -3, vcc
	v_add3_u32 v34, v38, v34, s0
	v_max_i32_e32 v34, 0xffffff88, v34
	v_add_u32_e32 v34, 0x7f, v34
	v_lshlrev_b32_e32 v44, 23, v34
	v_cvt_scalef32_2xpk16_fp6_f32 v[38:43], v[18:33], v[2:17], v44
	v_lshl_add_u64 v[2:3], v[36:37], 0, v[102:103]
	v_mul_lo_u32 v34, v34, s1
	v_lshl_add_u64 v[2:3], v[2:3], 0, v[100:101]
	v_mov_b32_e32 v32, v42
	v_mov_b32_e32 v33, v43
	global_store_dwordx4 v[2:3], v[38:41], off offset:256
	global_store_dwordx4 v[2:3], v[32:35], off offset:272
	s_or_b64 exec, exec, s[6:7]
	s_cmp_eq_u32 s88, s93
	s_mov_b64 s[4:5], -1
	s_cbranch_scc1 .LBB0_566

.LBB0_1607:
	s_or_b64 exec, exec, s[4:5]
	v_mul_f32_e32 v194, 0x3dd53b94, v139
	v_pk_mul_f32 v[18:19], v[194:195], v[18:19] op_sel_hi:[0,1]
	v_pk_mul_f32 v[2:3], v[194:195], v[2:3] op_sel_hi:[0,1]
	v_pk_mul_f32 v[20:21], v[194:195], v[20:21] op_sel_hi:[0,1]
	v_pk_mul_f32 v[4:5], v[194:195], v[4:5] op_sel_hi:[0,1]
	v_max_f32_e64 v139, |v18|, |v2|
	v_max_f32_e64 v143, |v19|, |v3|
	v_pk_mul_f32 v[22:23], v[194:195], v[22:23] op_sel_hi:[0,1]
	v_pk_mul_f32 v[6:7], v[194:195], v[6:7] op_sel_hi:[0,1]
	v_max3_f32 v139, v139, 0, v143
	v_max_f32_e64 v143, |v20|, |v4|
	v_max_f32_e64 v145, |v21|, |v5|
	v_pk_mul_f32 v[24:25], v[194:195], v[24:25] op_sel_hi:[0,1]
	v_pk_mul_f32 v[8:9], v[194:195], v[8:9] op_sel_hi:[0,1]
	v_max3_f32 v139, v139, v143, v145
	v_max_f32_e64 v143, |v22|, |v6|
	v_max_f32_e64 v145, |v23|, |v7|
	v_pk_mul_f32 v[26:27], v[194:195], v[26:27] op_sel_hi:[0,1]
	v_pk_mul_f32 v[10:11], v[194:195], v[10:11] op_sel_hi:[0,1]
	v_max3_f32 v139, v139, v143, v145
	v_max_f32_e64 v143, |v24|, |v8|
	v_max_f32_e64 v145, |v25|, |v9|
	v_pk_mul_f32 v[28:29], v[194:195], v[28:29] op_sel_hi:[0,1]
	v_pk_mul_f32 v[12:13], v[194:195], v[12:13] op_sel_hi:[0,1]
	v_max3_f32 v139, v139, v143, v145
	v_max_f32_e64 v143, |v26|, |v10|
	v_max_f32_e64 v145, |v27|, |v11|
	v_pk_mul_f32 v[30:31], v[194:195], v[30:31] op_sel_hi:[0,1]
	v_pk_mul_f32 v[14:15], v[194:195], v[14:15] op_sel_hi:[0,1]
	v_max3_f32 v139, v139, v143, v145
	v_max_f32_e64 v143, |v28|, |v12|
	v_max_f32_e64 v145, |v29|, |v13|
	v_pk_mul_f32 v[32:33], v[194:195], v[32:33] op_sel_hi:[0,1]
	v_pk_mul_f32 v[16:17], v[194:195], v[16:17] op_sel_hi:[0,1]
	v_max3_f32 v139, v139, v143, v145
	v_max_f32_e64 v143, |v30|, |v14|
	v_max_f32_e64 v145, |v31|, |v15|
	v_max3_f32 v139, v139, v143, v145
	v_max_f32_e64 v143, |v32|, |v16|
	v_max_f32_e64 v145, |v33|, |v17|
	v_max3_f32 v139, v139, v143, v145
	v_cmp_gt_u32_e32 vcc, 64, v188
	v_bfe_u32 v143, v139, 23, 8
	v_and_b32_e32 v139, 0x7fffff, v139
	v_cndmask_b32_e32 v34, v177, v181, vcc
	v_cndmask_b32_e64 v190, 64, 0, vcc
	v_cmp_gt_u32_e32 vcc, s1, v139
	v_mov_b64_e32 v[194:195], s[22:23]
	v_mad_i64_i32 v[194:195], s[4:5], v141, s0, v[194:195]
	v_cndmask_b32_e64 v139, -2, -3, vcc
	v_add3_u32 v139, v143, v139, s97
	v_max_i32_e32 v139, 0xffffff88, v139
	v_add_u32_e32 v139, 0x7f, v139
	v_lshl_add_u64 v[194:195], v[192:193], 1, v[194:195]
	v_and_b32_e32 v188, 32, v188
	v_mov_b32_e32 v189, v35
	v_lshlrev_b32_e32 v196, 23, v139
	v_lshl_add_u64 v[218:219], v[194:195], 0, v[34:35]
	v_cvt_scalef32_2xpk16_fp6_f32 v[210:215], v[18:33], v[2:17], v196
	v_sub_u32_e32 v198, 0x7f000000, v196
	v_lshl_add_u64 v[218:219], v[218:219], 0, v[188:189]
	global_store_dwordx4 v[218:219], v[210:213], off
	v_mul_lo_u32 v216, v139, s3
	v_mov_b32_e32 v217, v35
	v_pk_mul_f32 v[210:211], v[18:19], v[198:199] op_sel_hi:[1,0]
	v_pk_mul_f32 v[212:213], v[2:3], v[198:199] op_sel_hi:[1,0]
	v_cmp_lt_f32_e64 vcc, |v210|, 4.0
	v_and_b32_e32 v139, 0x7fffffff, v210
	global_store_dwordx4 v[218:219], v[214:217], off offset:16
	v_cndmask_b32_e32 v143, 0.5, v185, vcc
	v_cmp_nlt_f32_e64 vcc, |v210|, 2.0
	v_pk_mul_f32 v[214:215], v[20:21], v[198:199] op_sel_hi:[1,0]
	v_mov_b32_e32 v191, v35
	v_cndmask_b32_e32 v143, v197, v143, vcc
	v_permlane32_swap_b32_e32 v116, v100
	v_cmp_lt_f32_e64 vcc, |v211|, 4.0
	v_and_b32_e32 v145, 0x7fffffff, v211
	v_sub_u32_e32 v147, 0x7f000000, v143
	v_mul_f32_e64 v139, |v210|, v147
	v_cndmask_b32_e32 v147, 0.5, v185, vcc
	v_cmp_nlt_f32_e64 vcc, |v211|, 2.0
	v_rndne_f32_e32 v139, v139
	v_mul_f32_e32 v139, v143, v139
	v_cndmask_b32_e32 v147, v197, v147, vcc
	v_min_f32_e32 v139, 0x40f00000, v139
	v_bfi_b32 v210, s10, v139, v210
	v_permlane32_swap_b32_e32 v117, v101
	v_sub_u32_e32 v145, 0x7f000000, v147
	v_mul_f32_e64 v143, |v211|, v145
	v_rndne_f32_e32 v143, v143
	v_mul_f32_e32 v143, v147, v143
	v_cmp_lt_f32_e64 vcc, |v212|, 4.0
	v_min_f32_e32 v143, 0x40f00000, v143
	v_bfi_b32 v211, s10, v143, v211
	v_cndmask_b32_e32 v145, 0.5, v185, vcc
	v_cmp_nlt_f32_e64 vcc, |v212|, 2.0
	v_and_b32_e32 v143, 0x7fffffff, v212
	v_pk_mul_f32 v[210:211], v[210:211], v[196:197] op_sel_hi:[1,0]
	v_cndmask_b32_e32 v145, v197, v145, vcc
	v_pk_fma_f32 v[18:19], v[18:19], 2.0, v[210:211] op_sel_hi:[1,0,1] neg_lo:[0,0,1] neg_hi:[0,0,1]
	v_permlane32_swap_b32_e32 v118, v102
	v_cmp_lt_f32_e64 vcc, |v213|, 4.0
	v_and_b32_e32 v143, 0x7fffffff, v213
	v_sub_u32_e32 v147, 0x7f000000, v145
	v_mul_f32_e64 v139, |v212|, v147
	v_cndmask_b32_e32 v147, 0.5, v185, vcc
	v_cmp_nlt_f32_e64 vcc, |v213|, 2.0
	v_rndne_f32_e32 v139, v139
	v_mul_f32_e32 v139, v145, v139
	v_cndmask_b32_e32 v147, v197, v147, vcc
	v_min_f32_e32 v139, 0x40f00000, v139
	v_sub_u32_e32 v145, 0x7f000000, v147
	v_mul_f32_e64 v143, |v213|, v145
	v_rndne_f32_e32 v143, v143
	v_mul_f32_e32 v143, v147, v143
	v_cmp_lt_f32_e64 vcc, |v214|, 4.0
	v_min_f32_e32 v143, 0x40f00000, v143
	v_bfi_b32 v211, s10, v143, v213
	v_cndmask_b32_e32 v145, 0.5, v185, vcc
	v_cmp_nlt_f32_e64 vcc, |v214|, 2.0
	v_and_b32_e32 v143, 0x7fffffff, v214
	v_bfi_b32 v210, s10, v139, v212
	v_cndmask_b32_e32 v145, v197, v145, vcc
	v_pk_mul_f32 v[212:213], v[4:5], v[198:199] op_sel_hi:[1,0]
	v_pk_mul_f32 v[210:211], v[210:211], v[196:197] op_sel_hi:[1,0]
	v_permlane32_swap_b32_e32 v119, v103
	v_cmp_lt_f32_e64 vcc, |v215|, 4.0
	v_and_b32_e32 v143, 0x7fffffff, v215
	v_sub_u32_e32 v147, 0x7f000000, v145
	v_mul_f32_e64 v139, |v214|, v147
	v_cndmask_b32_e32 v147, 0.5, v185, vcc
	v_cmp_nlt_f32_e64 vcc, |v215|, 2.0
	v_rndne_f32_e32 v139, v139
	v_mul_f32_e32 v139, v145, v139
	v_cndmask_b32_e32 v147, v197, v147, vcc
	v_pk_fma_f32 v[2:3], v[2:3], 2.0, v[210:211] op_sel_hi:[1,0,1] neg_lo:[0,0,1] neg_hi:[0,0,1]
	v_sub_u32_e32 v145, 0x7f000000, v147
	v_mul_f32_e64 v143, |v215|, v145
	v_rndne_f32_e32 v143, v143
	v_mul_f32_e32 v143, v147, v143
	v_cmp_lt_f32_e64 vcc, |v212|, 4.0
	v_min_f32_e32 v143, 0x40f00000, v143
	v_bfi_b32 v211, s10, v143, v215
	v_cndmask_b32_e32 v145, 0.5, v185, vcc
	v_cmp_nlt_f32_e64 vcc, |v212|, 2.0
	v_and_b32_e32 v143, 0x7fffffff, v212
	v_min_f32_e32 v139, 0x40f00000, v139
	v_cndmask_b32_e32 v145, v197, v145, vcc
	v_bfi_b32 v210, s10, v139, v214
	v_pk_mul_f32 v[214:215], v[22:23], v[198:199] op_sel_hi:[1,0]
	v_pk_mul_f32 v[210:211], v[210:211], v[196:197] op_sel_hi:[1,0]
	v_cmp_lt_f32_e64 vcc, |v213|, 4.0
	v_and_b32_e32 v143, 0x7fffffff, v213
	v_sub_u32_e32 v147, 0x7f000000, v145
	v_mul_f32_e64 v139, |v212|, v147
	v_cndmask_b32_e32 v147, 0.5, v185, vcc
	v_cmp_nlt_f32_e64 vcc, |v213|, 2.0
	v_rndne_f32_e32 v139, v139
	v_mul_f32_e32 v139, v145, v139
	v_cndmask_b32_e32 v147, v197, v147, vcc
	v_pk_fma_f32 v[20:21], v[20:21], 2.0, v[210:211] op_sel_hi:[1,0,1] neg_lo:[0,0,1] neg_hi:[0,0,1]
	v_sub_u32_e32 v145, 0x7f000000, v147
	v_mul_f32_e64 v143, |v213|, v145
	v_rndne_f32_e32 v143, v143
	v_mul_f32_e32 v143, v147, v143
	v_cmp_lt_f32_e64 vcc, |v214|, 4.0
	v_min_f32_e32 v143, 0x40f00000, v143
	v_bfi_b32 v211, s10, v143, v213
	v_cndmask_b32_e32 v145, 0.5, v185, vcc
	v_cmp_nlt_f32_e64 vcc, |v214|, 2.0
	v_and_b32_e32 v143, 0x7fffffff, v214
	v_min_f32_e32 v139, 0x40f00000, v139
	v_cndmask_b32_e32 v145, v197, v145, vcc
	v_bfi_b32 v210, s10, v139, v212
	v_pk_mul_f32 v[212:213], v[6:7], v[198:199] op_sel_hi:[1,0]
	v_pk_mul_f32 v[210:211], v[210:211], v[196:197] op_sel_hi:[1,0]
	v_cmp_lt_f32_e64 vcc, |v215|, 4.0
	v_and_b32_e32 v143, 0x7fffffff, v215
	v_sub_u32_e32 v147, 0x7f000000, v145
	v_mul_f32_e64 v139, |v214|, v147
	v_cndmask_b32_e32 v147, 0.5, v185, vcc
	v_cmp_nlt_f32_e64 vcc, |v215|, 2.0
	v_rndne_f32_e32 v139, v139
	v_mul_f32_e32 v139, v145, v139
	v_cndmask_b32_e32 v147, v197, v147, vcc
	v_pk_fma_f32 v[4:5], v[4:5], 2.0, v[210:211] op_sel_hi:[1,0,1] neg_lo:[0,0,1] neg_hi:[0,0,1]
	v_sub_u32_e32 v145, 0x7f000000, v147
	v_mul_f32_e64 v143, |v215|, v145
	v_rndne_f32_e32 v143, v143
	v_mul_f32_e32 v143, v147, v143
	v_cmp_lt_f32_e64 vcc, |v212|, 4.0
	v_min_f32_e32 v143, 0x40f00000, v143
	v_bfi_b32 v211, s10, v143, v215
	v_cndmask_b32_e32 v145, 0.5, v185, vcc
	v_cmp_nlt_f32_e64 vcc, |v212|, 2.0
	v_and_b32_e32 v143, 0x7fffffff, v212
	v_min_f32_e32 v139, 0x40f00000, v139
	v_cndmask_b32_e32 v145, v197, v145, vcc
	v_bfi_b32 v210, s10, v139, v214
	v_pk_mul_f32 v[214:215], v[24:25], v[198:199] op_sel_hi:[1,0]
	v_pk_mul_f32 v[210:211], v[210:211], v[196:197] op_sel_hi:[1,0]
	v_cmp_lt_f32_e64 vcc, |v213|, 4.0
	v_and_b32_e32 v143, 0x7fffffff, v213
	v_sub_u32_e32 v147, 0x7f000000, v145
	v_mul_f32_e64 v139, |v212|, v147
	v_cndmask_b32_e32 v147, 0.5, v185, vcc
	v_cmp_nlt_f32_e64 vcc, |v213|, 2.0
	v_rndne_f32_e32 v139, v139
	v_mul_f32_e32 v139, v145, v139
	v_cndmask_b32_e32 v147, v197, v147, vcc
	v_pk_fma_f32 v[22:23], v[22:23], 2.0, v[210:211] op_sel_hi:[1,0,1] neg_lo:[0,0,1] neg_hi:[0,0,1]
	v_sub_u32_e32 v145, 0x7f000000, v147
	v_mul_f32_e64 v143, |v213|, v145
	v_rndne_f32_e32 v143, v143
	v_mul_f32_e32 v143, v147, v143
	v_cmp_lt_f32_e64 vcc, |v214|, 4.0
	v_min_f32_e32 v143, 0x40f00000, v143
	v_bfi_b32 v211, s10, v143, v213
	v_cndmask_b32_e32 v145, 0.5, v185, vcc
	v_cmp_nlt_f32_e64 vcc, |v214|, 2.0
	v_and_b32_e32 v143, 0x7fffffff, v214
	v_min_f32_e32 v139, 0x40f00000, v139
	v_cndmask_b32_e32 v145, v197, v145, vcc
	v_bfi_b32 v210, s10, v139, v212
	v_pk_mul_f32 v[212:213], v[8:9], v[198:199] op_sel_hi:[1,0]
	v_pk_mul_f32 v[210:211], v[210:211], v[196:197] op_sel_hi:[1,0]
	v_cmp_lt_f32_e64 vcc, |v215|, 4.0
	v_and_b32_e32 v143, 0x7fffffff, v215
	v_sub_u32_e32 v147, 0x7f000000, v145
	v_mul_f32_e64 v139, |v214|, v147
	v_cndmask_b32_e32 v147, 0.5, v185, vcc
	v_cmp_nlt_f32_e64 vcc, |v215|, 2.0
	v_rndne_f32_e32 v139, v139
	v_mul_f32_e32 v139, v145, v139
	v_cndmask_b32_e32 v147, v197, v147, vcc
	v_pk_fma_f32 v[6:7], v[6:7], 2.0, v[210:211] op_sel_hi:[1,0,1] neg_lo:[0,0,1] neg_hi:[0,0,1]
	v_sub_u32_e32 v145, 0x7f000000, v147
	v_mul_f32_e64 v143, |v215|, v145
	v_rndne_f32_e32 v143, v143
	v_mul_f32_e32 v143, v147, v143
	v_cmp_lt_f32_e64 vcc, |v212|, 4.0
	v_min_f32_e32 v143, 0x40f00000, v143
	v_bfi_b32 v211, s10, v143, v215
	v_cndmask_b32_e32 v145, 0.5, v185, vcc
	v_cmp_nlt_f32_e64 vcc, |v212|, 2.0
	v_and_b32_e32 v143, 0x7fffffff, v212
	v_min_f32_e32 v139, 0x40f00000, v139
	v_cndmask_b32_e32 v145, v197, v145, vcc
	v_bfi_b32 v210, s10, v139, v214
	v_pk_mul_f32 v[214:215], v[26:27], v[198:199] op_sel_hi:[1,0]
	v_pk_mul_f32 v[210:211], v[210:211], v[196:197] op_sel_hi:[1,0]
	v_cmp_lt_f32_e64 vcc, |v213|, 4.0
	v_and_b32_e32 v143, 0x7fffffff, v213
	v_sub_u32_e32 v147, 0x7f000000, v145
	v_mul_f32_e64 v139, |v212|, v147
	v_cndmask_b32_e32 v147, 0.5, v185, vcc
	v_cmp_nlt_f32_e64 vcc, |v213|, 2.0
	v_rndne_f32_e32 v139, v139
	v_mul_f32_e32 v139, v145, v139
	v_cndmask_b32_e32 v147, v197, v147, vcc
	v_pk_fma_f32 v[24:25], v[24:25], 2.0, v[210:211] op_sel_hi:[1,0,1] neg_lo:[0,0,1] neg_hi:[0,0,1]
	v_sub_u32_e32 v145, 0x7f000000, v147
	v_mul_f32_e64 v143, |v213|, v145
	v_rndne_f32_e32 v143, v143
	v_mul_f32_e32 v143, v147, v143
	v_cmp_lt_f32_e64 vcc, |v214|, 4.0
	v_min_f32_e32 v143, 0x40f00000, v143
	v_bfi_b32 v211, s10, v143, v213
	v_cndmask_b32_e32 v145, 0.5, v185, vcc
	v_cmp_nlt_f32_e64 vcc, |v214|, 2.0
	v_and_b32_e32 v143, 0x7fffffff, v214
	v_min_f32_e32 v139, 0x40f00000, v139
	v_cndmask_b32_e32 v145, v197, v145, vcc
	v_bfi_b32 v210, s10, v139, v212
	v_pk_mul_f32 v[212:213], v[10:11], v[198:199] op_sel_hi:[1,0]
	v_pk_mul_f32 v[210:211], v[210:211], v[196:197] op_sel_hi:[1,0]
	v_cmp_lt_f32_e64 vcc, |v215|, 4.0
	v_and_b32_e32 v143, 0x7fffffff, v215
	v_sub_u32_e32 v147, 0x7f000000, v145
	v_mul_f32_e64 v139, |v214|, v147
	v_cndmask_b32_e32 v147, 0.5, v185, vcc
	v_cmp_nlt_f32_e64 vcc, |v215|, 2.0
	v_rndne_f32_e32 v139, v139
	v_mul_f32_e32 v139, v145, v139
	v_cndmask_b32_e32 v147, v197, v147, vcc
	v_pk_fma_f32 v[8:9], v[8:9], 2.0, v[210:211] op_sel_hi:[1,0,1] neg_lo:[0,0,1] neg_hi:[0,0,1]
	v_sub_u32_e32 v145, 0x7f000000, v147
	v_mul_f32_e64 v143, |v215|, v145
	v_rndne_f32_e32 v143, v143
	v_mul_f32_e32 v143, v147, v143
	v_cmp_lt_f32_e64 vcc, |v212|, 4.0
	v_min_f32_e32 v143, 0x40f00000, v143
	v_bfi_b32 v211, s10, v143, v215
	v_cndmask_b32_e32 v145, 0.5, v185, vcc
	v_cmp_nlt_f32_e64 vcc, |v212|, 2.0
	v_and_b32_e32 v143, 0x7fffffff, v212
	v_min_f32_e32 v139, 0x40f00000, v139
	v_cndmask_b32_e32 v145, v197, v145, vcc
	v_bfi_b32 v210, s10, v139, v214
	v_pk_mul_f32 v[214:215], v[28:29], v[198:199] op_sel_hi:[1,0]
	v_pk_mul_f32 v[210:211], v[210:211], v[196:197] op_sel_hi:[1,0]
	v_cmp_lt_f32_e64 vcc, |v213|, 4.0
	v_and_b32_e32 v143, 0x7fffffff, v213
	v_sub_u32_e32 v147, 0x7f000000, v145
	v_mul_f32_e64 v139, |v212|, v147
	v_cndmask_b32_e32 v147, 0.5, v185, vcc
	v_cmp_nlt_f32_e64 vcc, |v213|, 2.0
	v_rndne_f32_e32 v139, v139
	v_mul_f32_e32 v139, v145, v139
	v_cndmask_b32_e32 v147, v197, v147, vcc
	v_pk_fma_f32 v[26:27], v[26:27], 2.0, v[210:211] op_sel_hi:[1,0,1] neg_lo:[0,0,1] neg_hi:[0,0,1]
	v_sub_u32_e32 v145, 0x7f000000, v147
	v_mul_f32_e64 v143, |v213|, v145
	v_rndne_f32_e32 v143, v143
	v_mul_f32_e32 v143, v147, v143
	v_cmp_lt_f32_e64 vcc, |v214|, 4.0
	v_min_f32_e32 v143, 0x40f00000, v143
	v_bfi_b32 v211, s10, v143, v213
	v_cndmask_b32_e32 v145, 0.5, v185, vcc
	v_cmp_nlt_f32_e64 vcc, |v214|, 2.0
	v_and_b32_e32 v143, 0x7fffffff, v214
	v_min_f32_e32 v139, 0x40f00000, v139
	v_cndmask_b32_e32 v145, v197, v145, vcc
	v_bfi_b32 v210, s10, v139, v212
	v_pk_mul_f32 v[212:213], v[12:13], v[198:199] op_sel_hi:[1,0]
	v_pk_mul_f32 v[210:211], v[210:211], v[196:197] op_sel_hi:[1,0]
	v_cmp_lt_f32_e64 vcc, |v215|, 4.0
	v_and_b32_e32 v143, 0x7fffffff, v215
	v_sub_u32_e32 v147, 0x7f000000, v145
	v_mul_f32_e64 v139, |v214|, v147
	v_cndmask_b32_e32 v147, 0.5, v185, vcc
	v_cmp_nlt_f32_e64 vcc, |v215|, 2.0
	v_rndne_f32_e32 v139, v139
	v_mul_f32_e32 v139, v145, v139
	v_cndmask_b32_e32 v147, v197, v147, vcc
	v_pk_fma_f32 v[10:11], v[10:11], 2.0, v[210:211] op_sel_hi:[1,0,1] neg_lo:[0,0,1] neg_hi:[0,0,1]
	v_sub_u32_e32 v145, 0x7f000000, v147
	v_mul_f32_e64 v143, |v215|, v145
	v_rndne_f32_e32 v143, v143
	v_mul_f32_e32 v143, v147, v143
	v_cmp_lt_f32_e64 vcc, |v212|, 4.0
	v_min_f32_e32 v143, 0x40f00000, v143
	v_bfi_b32 v211, s10, v143, v215
	v_cndmask_b32_e32 v145, 0.5, v185, vcc
	v_cmp_nlt_f32_e64 vcc, |v212|, 2.0
	v_and_b32_e32 v143, 0x7fffffff, v212
	v_min_f32_e32 v139, 0x40f00000, v139
	v_cndmask_b32_e32 v145, v197, v145, vcc
	v_bfi_b32 v210, s10, v139, v214
	v_pk_mul_f32 v[214:215], v[30:31], v[198:199] op_sel_hi:[1,0]
	v_pk_mul_f32 v[210:211], v[210:211], v[196:197] op_sel_hi:[1,0]
	v_cmp_lt_f32_e64 vcc, |v213|, 4.0
	v_and_b32_e32 v143, 0x7fffffff, v213
	v_sub_u32_e32 v147, 0x7f000000, v145
	v_mul_f32_e64 v139, |v212|, v147
	v_cndmask_b32_e32 v147, 0.5, v185, vcc
	v_cmp_nlt_f32_e64 vcc, |v213|, 2.0
	v_rndne_f32_e32 v139, v139
	v_mul_f32_e32 v139, v145, v139
	v_cndmask_b32_e32 v147, v197, v147, vcc
	v_pk_fma_f32 v[28:29], v[28:29], 2.0, v[210:211] op_sel_hi:[1,0,1] neg_lo:[0,0,1] neg_hi:[0,0,1]
	v_sub_u32_e32 v145, 0x7f000000, v147
	v_mul_f32_e64 v143, |v213|, v145
	v_rndne_f32_e32 v143, v143
	v_mul_f32_e32 v143, v147, v143
	v_cmp_lt_f32_e64 vcc, |v214|, 4.0
	v_min_f32_e32 v143, 0x40f00000, v143
	v_bfi_b32 v211, s10, v143, v213
	v_cndmask_b32_e32 v145, 0.5, v185, vcc
	v_cmp_nlt_f32_e64 vcc, |v214|, 2.0
	v_and_b32_e32 v143, 0x7fffffff, v214
	v_min_f32_e32 v139, 0x40f00000, v139
	v_cndmask_b32_e32 v145, v197, v145, vcc
	v_bfi_b32 v210, s10, v139, v212
	v_pk_mul_f32 v[212:213], v[14:15], v[198:199] op_sel_hi:[1,0]
	v_pk_mul_f32 v[210:211], v[210:211], v[196:197] op_sel_hi:[1,0]
	v_cmp_lt_f32_e64 vcc, |v215|, 4.0
	v_and_b32_e32 v143, 0x7fffffff, v215
	v_sub_u32_e32 v147, 0x7f000000, v145
	v_mul_f32_e64 v139, |v214|, v147
	v_cndmask_b32_e32 v147, 0.5, v185, vcc
	v_cmp_nlt_f32_e64 vcc, |v215|, 2.0
	v_rndne_f32_e32 v139, v139
	v_mul_f32_e32 v139, v145, v139
	v_cndmask_b32_e32 v147, v197, v147, vcc
	v_pk_fma_f32 v[12:13], v[12:13], 2.0, v[210:211] op_sel_hi:[1,0,1] neg_lo:[0,0,1] neg_hi:[0,0,1]
	v_sub_u32_e32 v145, 0x7f000000, v147
	v_mul_f32_e64 v143, |v215|, v145
	v_rndne_f32_e32 v143, v143
	v_mul_f32_e32 v143, v147, v143
	v_cmp_lt_f32_e64 vcc, |v212|, 4.0
	v_min_f32_e32 v143, 0x40f00000, v143
	v_bfi_b32 v211, s10, v143, v215
	v_cndmask_b32_e32 v145, 0.5, v185, vcc
	v_cmp_nlt_f32_e64 vcc, |v212|, 2.0
	v_and_b32_e32 v143, 0x7fffffff, v212
	v_min_f32_e32 v139, 0x40f00000, v139
	v_cndmask_b32_e32 v145, v197, v145, vcc
	v_bfi_b32 v210, s10, v139, v214
	v_pk_mul_f32 v[214:215], v[32:33], v[198:199] op_sel_hi:[1,0]
	v_pk_mul_f32 v[210:211], v[210:211], v[196:197] op_sel_hi:[1,0]
	v_cmp_lt_f32_e64 vcc, |v213|, 4.0
	v_and_b32_e32 v143, 0x7fffffff, v213
	v_sub_u32_e32 v147, 0x7f000000, v145
	v_mul_f32_e64 v139, |v212|, v147
	v_cndmask_b32_e32 v147, 0.5, v185, vcc
	v_cmp_nlt_f32_e64 vcc, |v213|, 2.0
	v_rndne_f32_e32 v139, v139
	v_mul_f32_e32 v139, v145, v139
	v_cndmask_b32_e32 v147, v197, v147, vcc
	v_pk_fma_f32 v[30:31], v[30:31], 2.0, v[210:211] op_sel_hi:[1,0,1] neg_lo:[0,0,1] neg_hi:[0,0,1]
	v_sub_u32_e32 v145, 0x7f000000, v147
	v_mul_f32_e64 v143, |v213|, v145
	v_rndne_f32_e32 v143, v143
	v_mul_f32_e32 v143, v147, v143
	v_cmp_lt_f32_e64 vcc, |v214|, 4.0
	v_min_f32_e32 v143, 0x40f00000, v143
	v_bfi_b32 v211, s10, v143, v213
	v_cndmask_b32_e32 v145, 0.5, v185, vcc
	v_cmp_nlt_f32_e64 vcc, |v214|, 2.0
	v_and_b32_e32 v143, 0x7fffffff, v214
	v_min_f32_e32 v139, 0x40f00000, v139
	v_cndmask_b32_e32 v145, v197, v145, vcc
	v_bfi_b32 v210, s10, v139, v212
	v_pk_mul_f32 v[212:213], v[16:17], v[198:199] op_sel_hi:[1,0]
	v_pk_mul_f32 v[210:211], v[210:211], v[196:197] op_sel_hi:[1,0]
	v_cmp_lt_f32_e64 vcc, |v215|, 4.0
	v_and_b32_e32 v143, 0x7fffffff, v215
	v_sub_u32_e32 v147, 0x7f000000, v145
	v_mul_f32_e64 v139, |v214|, v147
	v_cndmask_b32_e32 v147, 0.5, v185, vcc
	v_cmp_nlt_f32_e64 vcc, |v215|, 2.0
	v_rndne_f32_e32 v139, v139
	v_mul_f32_e32 v139, v145, v139
	v_cndmask_b32_e32 v147, v197, v147, vcc
	v_pk_fma_f32 v[14:15], v[14:15], 2.0, v[210:211] op_sel_hi:[1,0,1] neg_lo:[0,0,1] neg_hi:[0,0,1]
	v_sub_u32_e32 v145, 0x7f000000, v147
	v_mul_f32_e64 v143, |v215|, v145
	v_rndne_f32_e32 v143, v143
	v_mul_f32_e32 v143, v147, v143
	v_cmp_lt_f32_e64 vcc, |v212|, 4.0
	v_min_f32_e32 v143, 0x40f00000, v143
	v_bfi_b32 v211, s10, v143, v215
	v_cndmask_b32_e32 v145, 0.5, v185, vcc
	v_cmp_nlt_f32_e64 vcc, |v212|, 2.0
	v_and_b32_e32 v143, 0x7fffffff, v212
	v_min_f32_e32 v139, 0x40f00000, v139
	v_cndmask_b32_e32 v145, v197, v145, vcc
	v_bfi_b32 v210, s10, v139, v214
	v_pk_mul_f32 v[210:211], v[210:211], v[196:197] op_sel_hi:[1,0]
	v_permlane32_swap_b32_e32 v120, v104
	v_cmp_lt_f32_e64 vcc, |v213|, 4.0
	v_and_b32_e32 v143, 0x7fffffff, v213
	v_sub_u32_e32 v147, 0x7f000000, v145
	v_mul_f32_e64 v139, |v212|, v147
	v_cndmask_b32_e32 v147, 0.5, v185, vcc
	v_cmp_nlt_f32_e64 vcc, |v213|, 2.0
	v_rndne_f32_e32 v139, v139
	v_mul_f32_e32 v139, v145, v139
	v_cndmask_b32_e32 v147, v197, v147, vcc
	v_min_f32_e32 v139, 0x40f00000, v139
	v_sub_u32_e32 v145, 0x7f000000, v147
	v_mul_f32_e64 v143, |v213|, v145
	v_rndne_f32_e32 v143, v143
	v_mul_f32_e32 v143, v147, v143
	v_min_f32_e32 v143, 0x40f00000, v143
	v_pk_fma_f32 v[32:33], v[32:33], 2.0, v[210:211] op_sel_hi:[1,0,1] neg_lo:[0,0,1] neg_hi:[0,0,1]
	v_bfi_b32 v211, s10, v143, v213
	v_bfi_b32 v210, s10, v139, v212
	v_max_f32_e64 v139, |v18|, |v2|
	v_max_f32_e64 v143, |v19|, |v3|
	v_max3_f32 v139, v139, 0, v143
	v_max_f32_e64 v143, |v20|, |v4|
	v_max_f32_e64 v145, |v21|, |v5|
	v_max3_f32 v139, v139, v143, v145
	v_max_f32_e64 v143, |v22|, |v6|
	v_max_f32_e64 v145, |v23|, |v7|
	v_max3_f32 v139, v139, v143, v145
	v_max_f32_e64 v143, |v24|, |v8|
	v_max_f32_e64 v145, |v25|, |v9|
	v_max3_f32 v139, v139, v143, v145
	v_max_f32_e64 v143, |v26|, |v10|
	v_max_f32_e64 v145, |v27|, |v11|
	v_pk_mul_f32 v[210:211], v[210:211], v[196:197] op_sel_hi:[1,0]
	v_max3_f32 v139, v139, v143, v145
	v_max_f32_e64 v143, |v28|, |v12|
	v_max_f32_e64 v145, |v29|, |v13|
	v_pk_fma_f32 v[16:17], v[16:17], 2.0, v[210:211] op_sel_hi:[1,0,1] neg_lo:[0,0,1] neg_hi:[0,0,1]
	v_max3_f32 v139, v139, v143, v145
	v_max_f32_e64 v143, |v30|, |v14|
	v_max_f32_e64 v145, |v31|, |v15|
	v_max3_f32 v139, v139, v143, v145
	v_max_f32_e64 v143, |v32|, |v16|
	v_max_f32_e64 v145, |v33|, |v17|
	v_max3_f32 v139, v139, v143, v145
	v_bfe_u32 v143, v139, 23, 8
	v_and_b32_e32 v139, 0x7fffff, v139
	v_cmp_gt_u32_e32 vcc, s1, v139
	v_permlane32_swap_b32_e32 v121, v105
	s_nop 0
	v_cndmask_b32_e64 v139, -2, -3, vcc
	v_add3_u32 v139, v143, v139, s97
	v_max_i32_e32 v139, 0xffffff88, v139
	v_add_u32_e32 v139, 0x7f, v139
	v_lshlrev_b32_e32 v143, 23, v139
	v_cvt_scalef32_2xpk16_fp6_f32 v[210:215], v[18:33], v[2:17], v143
	v_lshl_add_u64 v[2:3], v[194:195], 0, v[190:191]
	v_permlane32_swap_b32_e32 v122, v106
	v_permlane32_swap_b32_e32 v123, v107
	v_permlane32_swap_b32_e32 v124, v108
	v_permlane32_swap_b32_e32 v125, v109
	v_permlane32_swap_b32_e32 v126, v110
	v_permlane32_swap_b32_e32 v127, v111
	v_permlane32_swap_b32_e32 v128, v112
	v_permlane32_swap_b32_e32 v129, v113
	v_permlane32_swap_b32_e32 v130, v114
	v_permlane32_swap_b32_e32 v131, v115
	v_lshl_add_u64 v[2:3], v[2:3], 0, v[188:189]
	v_permlane16_swap_b32_e32 v116, v124
	v_permlane16_swap_b32_e32 v117, v125
	v_permlane16_swap_b32_e32 v118, v126
	v_permlane16_swap_b32_e32 v119, v127
	v_permlane16_swap_b32_e32 v120, v128
	v_permlane16_swap_b32_e32 v121, v129
	v_permlane16_swap_b32_e32 v122, v130
	v_permlane16_swap_b32_e32 v123, v131
	v_permlane16_swap_b32_e32 v100, v108
	v_permlane16_swap_b32_e32 v101, v109
	v_permlane16_swap_b32_e32 v102, v110
	v_permlane16_swap_b32_e32 v103, v111
	v_permlane16_swap_b32_e32 v104, v112
	v_permlane16_swap_b32_e32 v105, v113
	v_permlane16_swap_b32_e32 v106, v114
	v_permlane16_swap_b32_e32 v107, v115
	v_cmp_lt_i32_e32 vcc, 1, v199
	v_mul_lo_u32 v216, v139, s3
	global_store_dwordx4 v[2:3], v[210:213], off
	global_store_dwordx4 v[2:3], v[214:217], off offset:16
	s_and_saveexec_b64 s[4:5], vcc
	s_xor_b64 s[4:5], exec, s[4:5]
	s_cbranch_execz .LBB0_1611
	v_cmp_gt_i32_e32 vcc, 3, v199
	v_mov_b32_e32 v2, v207
	s_and_saveexec_b64 s[56:57], vcc
	v_mov_b32_e32 v2, v204
	s_or_b64 exec, exec, s[56:57]

.LBB0_1615:
	s_or_b64 exec, exec, s[56:57]
	v_mul_f32_e32 v2, 0x3dd53b94, v2
	v_pk_mul_f32 v[32:33], v[2:3], v[130:131] op_sel_hi:[0,1]
	v_pk_mul_f32 v[30:31], v[2:3], v[128:129] op_sel_hi:[0,1]
	v_pk_mul_f32 v[28:29], v[2:3], v[126:127] op_sel_hi:[0,1]
	v_pk_mul_f32 v[26:27], v[2:3], v[124:125] op_sel_hi:[0,1]
	v_pk_mul_f32 v[24:25], v[2:3], v[122:123] op_sel_hi:[0,1]
	v_pk_mul_f32 v[22:23], v[2:3], v[120:121] op_sel_hi:[0,1]
	v_pk_mul_f32 v[20:21], v[2:3], v[118:119] op_sel_hi:[0,1]
	v_pk_mul_f32 v[18:19], v[2:3], v[116:117] op_sel_hi:[0,1]
	v_pk_mul_f32 v[16:17], v[2:3], v[114:115] op_sel_hi:[0,1]
	v_pk_mul_f32 v[14:15], v[2:3], v[112:113] op_sel_hi:[0,1]
	v_pk_mul_f32 v[12:13], v[2:3], v[110:111] op_sel_hi:[0,1]
	v_pk_mul_f32 v[10:11], v[2:3], v[108:109] op_sel_hi:[0,1]
	v_pk_mul_f32 v[8:9], v[2:3], v[106:107] op_sel_hi:[0,1]
	v_pk_mul_f32 v[6:7], v[2:3], v[104:105] op_sel_hi:[0,1]
	v_pk_mul_f32 v[4:5], v[2:3], v[102:103] op_sel_hi:[0,1]
	v_pk_mul_f32 v[2:3], v[2:3], v[100:101] op_sel_hi:[0,1]
	v_max_f32_e64 v100, |v18|, |v2|
	v_max_f32_e64 v101, |v19|, |v3|
	v_max3_f32 v100, v100, 0, v101
	v_max_f32_e64 v101, |v20|, |v4|
	v_max_f32_e64 v102, |v21|, |v5|
	v_max3_f32 v100, v100, v101, v102
	v_max_f32_e64 v101, |v22|, |v6|
	v_max_f32_e64 v102, |v23|, |v7|
	v_max3_f32 v100, v100, v101, v102
	v_max_f32_e64 v101, |v24|, |v8|
	v_max_f32_e64 v102, |v25|, |v9|
	v_max3_f32 v100, v100, v101, v102
	v_max_f32_e64 v101, |v26|, |v10|
	v_max_f32_e64 v102, |v27|, |v11|
	v_max3_f32 v100, v100, v101, v102
	v_max_f32_e64 v101, |v28|, |v12|
	v_max_f32_e64 v102, |v29|, |v13|
	v_max3_f32 v100, v100, v101, v102
	v_max_f32_e64 v101, |v30|, |v14|
	v_max_f32_e64 v102, |v31|, |v15|
	v_max3_f32 v100, v100, v101, v102
	v_max_f32_e64 v101, |v32|, |v16|
	v_max_f32_e64 v102, |v33|, |v17|
	v_max3_f32 v100, v100, v101, v102
	v_bfe_u32 v101, v100, 23, 8
	v_and_b32_e32 v100, 0x7fffff, v100
	v_cmp_gt_u32_e32 vcc, s1, v100
	v_add_u32_e32 v103, 0x80, v141
	v_mov_b32_e32 v113, v35
	v_cndmask_b32_e64 v100, -2, -3, vcc
	v_add3_u32 v100, v101, v100, s97
	v_max_i32_e32 v100, 0xffffff88, v100
	v_add_u32_e32 v100, 0x7f, v100
	v_lshlrev_b32_e32 v102, 23, v100
	v_mul_lo_u32 v112, v100, s3
	v_mov_b64_e32 v[100:101], s[22:23]
	v_mad_i64_i32 v[100:101], s[4:5], v103, s0, v[100:101]
	v_lshl_add_u64 v[100:101], v[192:193], 1, v[100:101]
	v_lshl_add_u64 v[114:115], v[100:101], 0, v[34:35]
	v_cvt_scalef32_2xpk16_fp6_f32 v[106:111], v[18:33], v[2:17], v102
	v_sub_u32_e32 v104, 0x7f000000, v102
	v_lshl_add_u64 v[114:115], v[114:115], 0, v[188:189]
	global_store_dwordx4 v[114:115], v[106:109], off
	global_store_dwordx4 v[114:115], v[110:113], off offset:16
	v_mov_b32_e32 v139, v102
	v_pk_mul_f32 v[106:107], v[18:19], v[104:105] op_sel_hi:[1,0]
	s_nop 0
	v_cmp_lt_f32_e64 vcc, |v106|, 4.0
	v_and_b32_e32 v34, 0x7fffffff, v106
	s_nop 0
	v_cndmask_b32_e32 v103, 0.5, v185, vcc
	v_cmp_nlt_f32_e64 vcc, |v106|, 2.0
	s_nop 1
	v_cndmask_b32_e32 v103, v197, v103, vcc
	v_cmp_lt_f32_e64 vcc, |v107|, 4.0
	v_and_b32_e32 v105, 0x7fffffff, v107
	v_sub_u32_e32 v108, 0x7f000000, v103
	v_mul_f32_e64 v34, |v106|, v108
	v_cndmask_b32_e32 v108, 0.5, v185, vcc
	v_cmp_nlt_f32_e64 vcc, |v107|, 2.0
	v_rndne_f32_e32 v34, v34
	v_mul_f32_e32 v34, v103, v34
	v_cndmask_b32_e32 v108, v197, v108, vcc
	v_min_f32_e32 v34, 0x40f00000, v34
	v_bfi_b32 v106, s10, v34, v106
	v_sub_u32_e32 v105, 0x7f000000, v108
	v_mul_f32_e64 v103, |v107|, v105
	v_rndne_f32_e32 v103, v103
	v_mul_f32_e32 v103, v108, v103
	v_pk_mul_f32 v[108:109], v[2:3], v[104:105] op_sel_hi:[1,0]
	v_min_f32_e32 v103, 0x40f00000, v103
	v_cmp_lt_f32_e64 vcc, |v108|, 4.0
	v_bfi_b32 v107, s10, v103, v107
	v_and_b32_e32 v103, 0x7fffffff, v108
	v_cndmask_b32_e32 v105, 0.5, v185, vcc
	v_cmp_nlt_f32_e64 vcc, |v108|, 2.0
	v_pk_mul_f32 v[106:107], v[106:107], v[102:103] op_sel_hi:[1,0]
	s_nop 0
	v_cndmask_b32_e32 v105, v197, v105, vcc
	v_pk_fma_f32 v[18:19], v[18:19], 2.0, v[106:107] op_sel_hi:[1,0,1] neg_lo:[0,0,1] neg_hi:[0,0,1]
	v_cmp_lt_f32_e64 vcc, |v109|, 4.0
	v_and_b32_e32 v103, 0x7fffffff, v109
	v_sub_u32_e32 v106, 0x7f000000, v105
	v_mul_f32_e64 v34, |v108|, v106
	v_cndmask_b32_e32 v106, 0.5, v185, vcc
	v_cmp_nlt_f32_e64 vcc, |v109|, 2.0
	v_rndne_f32_e32 v34, v34
	v_mul_f32_e32 v34, v105, v34
	v_cndmask_b32_e32 v106, v197, v106, vcc
	v_min_f32_e32 v34, 0x40f00000, v34
	v_sub_u32_e32 v105, 0x7f000000, v106
	v_mul_f32_e64 v103, |v109|, v105
	v_rndne_f32_e32 v103, v103
	v_pk_mul_f32 v[110:111], v[20:21], v[104:105] op_sel_hi:[1,0]
	v_mul_f32_e32 v103, v106, v103
	v_cmp_lt_f32_e64 vcc, |v110|, 4.0
	v_min_f32_e32 v103, 0x40f00000, v103
	v_bfi_b32 v107, s10, v103, v109
	v_cndmask_b32_e32 v105, 0.5, v185, vcc
	v_cmp_nlt_f32_e64 vcc, |v110|, 2.0
	v_and_b32_e32 v103, 0x7fffffff, v110
	v_bfi_b32 v106, s10, v34, v108
	v_cndmask_b32_e32 v105, v197, v105, vcc
	v_pk_mul_f32 v[106:107], v[106:107], v[102:103] op_sel_hi:[1,0]
	v_pk_fma_f32 v[2:3], v[2:3], 2.0, v[106:107] op_sel_hi:[1,0,1] neg_lo:[0,0,1] neg_hi:[0,0,1]
	v_cmp_lt_f32_e64 vcc, |v111|, 4.0
	v_and_b32_e32 v103, 0x7fffffff, v111
	v_sub_u32_e32 v106, 0x7f000000, v105
	v_mul_f32_e64 v34, |v110|, v106
	v_cndmask_b32_e32 v106, 0.5, v185, vcc
	v_cmp_nlt_f32_e64 vcc, |v111|, 2.0
	v_rndne_f32_e32 v34, v34
	v_mul_f32_e32 v34, v105, v34
	v_cndmask_b32_e32 v106, v197, v106, vcc
	v_min_f32_e32 v34, 0x40f00000, v34
	v_sub_u32_e32 v105, 0x7f000000, v106
	v_mul_f32_e64 v103, |v111|, v105
	v_rndne_f32_e32 v103, v103
	v_pk_mul_f32 v[108:109], v[4:5], v[104:105] op_sel_hi:[1,0]
	v_mul_f32_e32 v103, v106, v103
	v_cmp_lt_f32_e64 vcc, |v108|, 4.0
	v_min_f32_e32 v103, 0x40f00000, v103
	v_bfi_b32 v107, s10, v103, v111
	v_cndmask_b32_e32 v105, 0.5, v185, vcc
	v_cmp_nlt_f32_e64 vcc, |v108|, 2.0
	v_and_b32_e32 v103, 0x7fffffff, v108
	v_bfi_b32 v106, s10, v34, v110
	v_cndmask_b32_e32 v105, v197, v105, vcc
	v_pk_mul_f32 v[106:107], v[106:107], v[102:103] op_sel_hi:[1,0]
	v_pk_fma_f32 v[20:21], v[20:21], 2.0, v[106:107] op_sel_hi:[1,0,1] neg_lo:[0,0,1] neg_hi:[0,0,1]
	v_cmp_lt_f32_e64 vcc, |v109|, 4.0
	v_and_b32_e32 v103, 0x7fffffff, v109
	v_sub_u32_e32 v106, 0x7f000000, v105
	v_mul_f32_e64 v34, |v108|, v106
	v_cndmask_b32_e32 v106, 0.5, v185, vcc
	v_cmp_nlt_f32_e64 vcc, |v109|, 2.0
	v_rndne_f32_e32 v34, v34
	v_mul_f32_e32 v34, v105, v34
	v_cndmask_b32_e32 v106, v197, v106, vcc
	v_min_f32_e32 v34, 0x40f00000, v34
	v_sub_u32_e32 v105, 0x7f000000, v106
	v_mul_f32_e64 v103, |v109|, v105
	v_rndne_f32_e32 v103, v103
	v_pk_mul_f32 v[110:111], v[22:23], v[104:105] op_sel_hi:[1,0]
	v_mul_f32_e32 v103, v106, v103
	v_cmp_lt_f32_e64 vcc, |v110|, 4.0
	v_min_f32_e32 v103, 0x40f00000, v103
	v_bfi_b32 v107, s10, v103, v109
	v_cndmask_b32_e32 v105, 0.5, v185, vcc
	v_cmp_nlt_f32_e64 vcc, |v110|, 2.0
	v_and_b32_e32 v103, 0x7fffffff, v110
	v_bfi_b32 v106, s10, v34, v108
	v_cndmask_b32_e32 v105, v197, v105, vcc
	v_pk_mul_f32 v[106:107], v[106:107], v[102:103] op_sel_hi:[1,0]
	v_pk_fma_f32 v[4:5], v[4:5], 2.0, v[106:107] op_sel_hi:[1,0,1] neg_lo:[0,0,1] neg_hi:[0,0,1]
	v_cmp_lt_f32_e64 vcc, |v111|, 4.0
	v_and_b32_e32 v103, 0x7fffffff, v111
	v_sub_u32_e32 v106, 0x7f000000, v105
	v_mul_f32_e64 v34, |v110|, v106
	v_cndmask_b32_e32 v106, 0.5, v185, vcc
	v_cmp_nlt_f32_e64 vcc, |v111|, 2.0
	v_rndne_f32_e32 v34, v34
	v_mul_f32_e32 v34, v105, v34
	v_cndmask_b32_e32 v106, v197, v106, vcc
	v_min_f32_e32 v34, 0x40f00000, v34
	v_sub_u32_e32 v105, 0x7f000000, v106
	v_mul_f32_e64 v103, |v111|, v105
	v_rndne_f32_e32 v103, v103
	v_pk_mul_f32 v[108:109], v[6:7], v[104:105] op_sel_hi:[1,0]
	v_mul_f32_e32 v103, v106, v103
	v_cmp_lt_f32_e64 vcc, |v108|, 4.0
	v_min_f32_e32 v103, 0x40f00000, v103
	v_bfi_b32 v107, s10, v103, v111
	v_cndmask_b32_e32 v105, 0.5, v185, vcc
	v_cmp_nlt_f32_e64 vcc, |v108|, 2.0
	v_and_b32_e32 v103, 0x7fffffff, v108
	v_bfi_b32 v106, s10, v34, v110
	v_cndmask_b32_e32 v105, v197, v105, vcc
	v_pk_mul_f32 v[106:107], v[106:107], v[102:103] op_sel_hi:[1,0]
	v_pk_fma_f32 v[22:23], v[22:23], 2.0, v[106:107] op_sel_hi:[1,0,1] neg_lo:[0,0,1] neg_hi:[0,0,1]
	v_cmp_lt_f32_e64 vcc, |v109|, 4.0
	v_and_b32_e32 v103, 0x7fffffff, v109
	v_sub_u32_e32 v106, 0x7f000000, v105
	v_mul_f32_e64 v34, |v108|, v106
	v_cndmask_b32_e32 v106, 0.5, v185, vcc
	v_cmp_nlt_f32_e64 vcc, |v109|, 2.0
	v_rndne_f32_e32 v34, v34
	v_mul_f32_e32 v34, v105, v34
	v_cndmask_b32_e32 v106, v197, v106, vcc
	v_min_f32_e32 v34, 0x40f00000, v34
	v_sub_u32_e32 v105, 0x7f000000, v106
	v_mul_f32_e64 v103, |v109|, v105
	v_rndne_f32_e32 v103, v103
	v_pk_mul_f32 v[110:111], v[24:25], v[104:105] op_sel_hi:[1,0]
	v_mul_f32_e32 v103, v106, v103
	v_cmp_lt_f32_e64 vcc, |v110|, 4.0
	v_min_f32_e32 v103, 0x40f00000, v103
	v_bfi_b32 v107, s10, v103, v109
	v_cndmask_b32_e32 v105, 0.5, v185, vcc
	v_cmp_nlt_f32_e64 vcc, |v110|, 2.0
	v_and_b32_e32 v103, 0x7fffffff, v110
	v_bfi_b32 v106, s10, v34, v108
	v_cndmask_b32_e32 v105, v197, v105, vcc
	v_pk_mul_f32 v[106:107], v[106:107], v[102:103] op_sel_hi:[1,0]
	v_pk_fma_f32 v[6:7], v[6:7], 2.0, v[106:107] op_sel_hi:[1,0,1] neg_lo:[0,0,1] neg_hi:[0,0,1]
	v_cmp_lt_f32_e64 vcc, |v111|, 4.0
	v_and_b32_e32 v103, 0x7fffffff, v111
	v_sub_u32_e32 v106, 0x7f000000, v105
	v_mul_f32_e64 v34, |v110|, v106
	v_cndmask_b32_e32 v106, 0.5, v185, vcc
	v_cmp_nlt_f32_e64 vcc, |v111|, 2.0
	v_rndne_f32_e32 v34, v34
	v_mul_f32_e32 v34, v105, v34
	v_cndmask_b32_e32 v106, v197, v106, vcc
	v_min_f32_e32 v34, 0x40f00000, v34
	v_sub_u32_e32 v105, 0x7f000000, v106
	v_mul_f32_e64 v103, |v111|, v105
	v_rndne_f32_e32 v103, v103
	v_pk_mul_f32 v[108:109], v[8:9], v[104:105] op_sel_hi:[1,0]
	v_mul_f32_e32 v103, v106, v103
	v_cmp_lt_f32_e64 vcc, |v108|, 4.0
	v_min_f32_e32 v103, 0x40f00000, v103
	v_bfi_b32 v107, s10, v103, v111
	v_cndmask_b32_e32 v105, 0.5, v185, vcc
	v_cmp_nlt_f32_e64 vcc, |v108|, 2.0
	v_and_b32_e32 v103, 0x7fffffff, v108
	v_bfi_b32 v106, s10, v34, v110
	v_cndmask_b32_e32 v105, v197, v105, vcc
	v_pk_mul_f32 v[106:107], v[106:107], v[102:103] op_sel_hi:[1,0]
	v_pk_fma_f32 v[24:25], v[24:25], 2.0, v[106:107] op_sel_hi:[1,0,1] neg_lo:[0,0,1] neg_hi:[0,0,1]
	v_cmp_lt_f32_e64 vcc, |v109|, 4.0
	v_and_b32_e32 v103, 0x7fffffff, v109
	v_sub_u32_e32 v106, 0x7f000000, v105
	v_mul_f32_e64 v34, |v108|, v106
	v_cndmask_b32_e32 v106, 0.5, v185, vcc
	v_cmp_nlt_f32_e64 vcc, |v109|, 2.0
	v_rndne_f32_e32 v34, v34
	v_mul_f32_e32 v34, v105, v34
	v_cndmask_b32_e32 v106, v197, v106, vcc
	v_min_f32_e32 v34, 0x40f00000, v34
	v_sub_u32_e32 v105, 0x7f000000, v106
	v_mul_f32_e64 v103, |v109|, v105
	v_rndne_f32_e32 v103, v103
	v_pk_mul_f32 v[110:111], v[26:27], v[104:105] op_sel_hi:[1,0]
	v_mul_f32_e32 v103, v106, v103
	v_cmp_lt_f32_e64 vcc, |v110|, 4.0
	v_min_f32_e32 v103, 0x40f00000, v103
	v_bfi_b32 v107, s10, v103, v109
	v_cndmask_b32_e32 v105, 0.5, v185, vcc
	v_cmp_nlt_f32_e64 vcc, |v110|, 2.0
	v_and_b32_e32 v103, 0x7fffffff, v110
	v_bfi_b32 v106, s10, v34, v108
	v_cndmask_b32_e32 v105, v197, v105, vcc
	v_pk_mul_f32 v[106:107], v[106:107], v[102:103] op_sel_hi:[1,0]
	v_pk_fma_f32 v[8:9], v[8:9], 2.0, v[106:107] op_sel_hi:[1,0,1] neg_lo:[0,0,1] neg_hi:[0,0,1]
	v_cmp_lt_f32_e64 vcc, |v111|, 4.0
	v_and_b32_e32 v103, 0x7fffffff, v111
	v_sub_u32_e32 v106, 0x7f000000, v105
	v_mul_f32_e64 v34, |v110|, v106
	v_cndmask_b32_e32 v106, 0.5, v185, vcc
	v_cmp_nlt_f32_e64 vcc, |v111|, 2.0
	v_rndne_f32_e32 v34, v34
	v_mul_f32_e32 v34, v105, v34
	v_cndmask_b32_e32 v106, v197, v106, vcc
	v_min_f32_e32 v34, 0x40f00000, v34
	v_sub_u32_e32 v105, 0x7f000000, v106
	v_mul_f32_e64 v103, |v111|, v105
	v_rndne_f32_e32 v103, v103
	v_pk_mul_f32 v[108:109], v[10:11], v[104:105] op_sel_hi:[1,0]
	v_mul_f32_e32 v103, v106, v103
	v_cmp_lt_f32_e64 vcc, |v108|, 4.0
	v_min_f32_e32 v103, 0x40f00000, v103
	v_bfi_b32 v107, s10, v103, v111
	v_cndmask_b32_e32 v105, 0.5, v185, vcc
	v_cmp_nlt_f32_e64 vcc, |v108|, 2.0
	v_and_b32_e32 v103, 0x7fffffff, v108
	v_bfi_b32 v106, s10, v34, v110
	v_cndmask_b32_e32 v105, v197, v105, vcc
	v_pk_mul_f32 v[106:107], v[106:107], v[102:103] op_sel_hi:[1,0]
	v_pk_fma_f32 v[26:27], v[26:27], 2.0, v[106:107] op_sel_hi:[1,0,1] neg_lo:[0,0,1] neg_hi:[0,0,1]
	v_cmp_lt_f32_e64 vcc, |v109|, 4.0
	v_and_b32_e32 v103, 0x7fffffff, v109
	v_sub_u32_e32 v106, 0x7f000000, v105
	v_mul_f32_e64 v34, |v108|, v106
	v_cndmask_b32_e32 v106, 0.5, v185, vcc
	v_cmp_nlt_f32_e64 vcc, |v109|, 2.0
	v_rndne_f32_e32 v34, v34
	v_mul_f32_e32 v34, v105, v34
	v_cndmask_b32_e32 v106, v197, v106, vcc
	v_min_f32_e32 v34, 0x40f00000, v34
	v_sub_u32_e32 v105, 0x7f000000, v106
	v_mul_f32_e64 v103, |v109|, v105
	v_rndne_f32_e32 v103, v103
	v_pk_mul_f32 v[110:111], v[28:29], v[104:105] op_sel_hi:[1,0]
	v_mul_f32_e32 v103, v106, v103
	v_cmp_lt_f32_e64 vcc, |v110|, 4.0
	v_min_f32_e32 v103, 0x40f00000, v103
	v_bfi_b32 v107, s10, v103, v109
	v_cndmask_b32_e32 v105, 0.5, v185, vcc
	v_cmp_nlt_f32_e64 vcc, |v110|, 2.0
	v_and_b32_e32 v103, 0x7fffffff, v110
	v_bfi_b32 v106, s10, v34, v108
	v_cndmask_b32_e32 v105, v197, v105, vcc
	v_pk_mul_f32 v[106:107], v[106:107], v[102:103] op_sel_hi:[1,0]
	v_pk_fma_f32 v[10:11], v[10:11], 2.0, v[106:107] op_sel_hi:[1,0,1] neg_lo:[0,0,1] neg_hi:[0,0,1]
	v_cmp_lt_f32_e64 vcc, |v111|, 4.0
	v_and_b32_e32 v103, 0x7fffffff, v111
	v_sub_u32_e32 v106, 0x7f000000, v105
	v_mul_f32_e64 v34, |v110|, v106
	v_cndmask_b32_e32 v106, 0.5, v185, vcc
	v_cmp_nlt_f32_e64 vcc, |v111|, 2.0
	v_rndne_f32_e32 v34, v34
	v_mul_f32_e32 v34, v105, v34
	v_cndmask_b32_e32 v106, v197, v106, vcc
	v_min_f32_e32 v34, 0x40f00000, v34
	v_sub_u32_e32 v105, 0x7f000000, v106
	v_mul_f32_e64 v103, |v111|, v105
	v_rndne_f32_e32 v103, v103
	v_pk_mul_f32 v[108:109], v[12:13], v[104:105] op_sel_hi:[1,0]
	v_mul_f32_e32 v103, v106, v103
	v_cmp_lt_f32_e64 vcc, |v108|, 4.0
	v_min_f32_e32 v103, 0x40f00000, v103
	v_bfi_b32 v107, s10, v103, v111
	v_cndmask_b32_e32 v105, 0.5, v185, vcc
	v_cmp_nlt_f32_e64 vcc, |v108|, 2.0
	v_and_b32_e32 v103, 0x7fffffff, v108
	v_bfi_b32 v106, s10, v34, v110
	v_cndmask_b32_e32 v105, v197, v105, vcc
	v_pk_mul_f32 v[106:107], v[106:107], v[102:103] op_sel_hi:[1,0]
	v_pk_fma_f32 v[28:29], v[28:29], 2.0, v[106:107] op_sel_hi:[1,0,1] neg_lo:[0,0,1] neg_hi:[0,0,1]
	v_cmp_lt_f32_e64 vcc, |v109|, 4.0
	v_and_b32_e32 v103, 0x7fffffff, v109
	v_sub_u32_e32 v106, 0x7f000000, v105
	v_mul_f32_e64 v34, |v108|, v106
	v_cndmask_b32_e32 v106, 0.5, v185, vcc
	v_cmp_nlt_f32_e64 vcc, |v109|, 2.0
	v_rndne_f32_e32 v34, v34
	v_mul_f32_e32 v34, v105, v34
	v_cndmask_b32_e32 v106, v197, v106, vcc
	v_min_f32_e32 v34, 0x40f00000, v34
	v_sub_u32_e32 v105, 0x7f000000, v106
	v_mul_f32_e64 v103, |v109|, v105
	v_rndne_f32_e32 v103, v103
	v_pk_mul_f32 v[110:111], v[30:31], v[104:105] op_sel_hi:[1,0]
	v_mul_f32_e32 v103, v106, v103
	v_cmp_lt_f32_e64 vcc, |v110|, 4.0
	v_min_f32_e32 v103, 0x40f00000, v103
	v_bfi_b32 v107, s10, v103, v109
	v_cndmask_b32_e32 v105, 0.5, v185, vcc
	v_cmp_nlt_f32_e64 vcc, |v110|, 2.0
	v_and_b32_e32 v103, 0x7fffffff, v110
	v_bfi_b32 v106, s10, v34, v108
	v_cndmask_b32_e32 v105, v197, v105, vcc
	v_pk_mul_f32 v[106:107], v[106:107], v[102:103] op_sel_hi:[1,0]
	v_pk_fma_f32 v[12:13], v[12:13], 2.0, v[106:107] op_sel_hi:[1,0,1] neg_lo:[0,0,1] neg_hi:[0,0,1]
	v_cmp_lt_f32_e64 vcc, |v111|, 4.0
	v_and_b32_e32 v103, 0x7fffffff, v111
	v_sub_u32_e32 v106, 0x7f000000, v105
	v_mul_f32_e64 v34, |v110|, v106
	v_cndmask_b32_e32 v106, 0.5, v185, vcc
	v_cmp_nlt_f32_e64 vcc, |v111|, 2.0
	v_rndne_f32_e32 v34, v34
	v_mul_f32_e32 v34, v105, v34
	v_cndmask_b32_e32 v106, v197, v106, vcc
	v_min_f32_e32 v34, 0x40f00000, v34
	v_sub_u32_e32 v105, 0x7f000000, v106
	v_mul_f32_e64 v103, |v111|, v105
	v_rndne_f32_e32 v103, v103
	v_pk_mul_f32 v[108:109], v[14:15], v[104:105] op_sel_hi:[1,0]
	v_mul_f32_e32 v103, v106, v103
	v_cmp_lt_f32_e64 vcc, |v108|, 4.0
	v_min_f32_e32 v103, 0x40f00000, v103
	v_bfi_b32 v107, s10, v103, v111
	v_cndmask_b32_e32 v105, 0.5, v185, vcc
	v_cmp_nlt_f32_e64 vcc, |v108|, 2.0
	v_and_b32_e32 v103, 0x7fffffff, v108
	v_bfi_b32 v106, s10, v34, v110
	v_cndmask_b32_e32 v105, v197, v105, vcc
	v_pk_mul_f32 v[106:107], v[106:107], v[102:103] op_sel_hi:[1,0]
	v_pk_fma_f32 v[30:31], v[30:31], 2.0, v[106:107] op_sel_hi:[1,0,1] neg_lo:[0,0,1] neg_hi:[0,0,1]
	v_cmp_lt_f32_e64 vcc, |v109|, 4.0
	v_and_b32_e32 v103, 0x7fffffff, v109
	v_sub_u32_e32 v106, 0x7f000000, v105
	v_mul_f32_e64 v34, |v108|, v106
	v_cndmask_b32_e32 v106, 0.5, v185, vcc
	v_cmp_nlt_f32_e64 vcc, |v109|, 2.0
	v_rndne_f32_e32 v34, v34
	v_mul_f32_e32 v34, v105, v34
	v_cndmask_b32_e32 v106, v197, v106, vcc
	v_min_f32_e32 v34, 0x40f00000, v34
	v_sub_u32_e32 v105, 0x7f000000, v106
	v_mul_f32_e64 v103, |v109|, v105
	v_rndne_f32_e32 v103, v103
	v_mul_f32_e32 v103, v106, v103
	v_bfi_b32 v106, s10, v34, v108
	v_mul_f32_e32 v34, v32, v104
	v_cmp_lt_f32_e64 vcc, |v34|, 4.0
	v_min_f32_e32 v103, 0x40f00000, v103
	v_bfi_b32 v107, s10, v103, v109
	v_cndmask_b32_e32 v105, 0.5, v185, vcc
	v_cmp_nlt_f32_e64 vcc, |v34|, 2.0
	v_and_b32_e32 v103, 0x7fffffff, v34
	v_pk_mul_f32 v[106:107], v[106:107], v[102:103] op_sel_hi:[1,0]
	v_cndmask_b32_e32 v105, v197, v105, vcc
	v_pk_fma_f32 v[14:15], v[14:15], 2.0, v[106:107] op_sel_hi:[1,0,1] neg_lo:[0,0,1] neg_hi:[0,0,1]
	v_sub_u32_e32 v106, 0x7f000000, v105
	v_mul_f32_e64 v103, |v34|, v106
	v_rndne_f32_e32 v103, v103
	v_mul_f32_e32 v103, v105, v103
	v_mul_f32_e32 v105, v16, v104
	v_cmp_lt_f32_e64 vcc, |v105|, 4.0
	v_and_b32_e32 v107, 0x7fffffff, v105
	v_min_f32_e32 v103, 0x40f00000, v103
	v_cndmask_b32_e32 v106, 0.5, v185, vcc
	v_cmp_nlt_f32_e64 vcc, |v105|, 2.0
	v_bfi_b32 v34, s10, v103, v34
	v_add_f32_e32 v32, v32, v32
	v_cndmask_b32_e32 v108, v197, v106, vcc
	v_mul_f32_e32 v106, v34, v102
	v_add_f32_e32 v16, v16, v16
	v_sub_u32_e32 v103, 0x7f000000, v108
	v_mul_f32_e64 v34, |v105|, v103
	v_mul_f32_e32 v103, v33, v104
	v_rndne_f32_e32 v34, v34
	v_cmp_lt_f32_e64 vcc, |v103|, 4.0
	v_mul_f32_e32 v34, v108, v34
	v_and_b32_e32 v107, 0x7fffffff, v103
	v_cndmask_b32_e32 v108, 0.5, v185, vcc
	v_cmp_nlt_f32_e64 vcc, |v103|, 2.0
	v_min_f32_e32 v34, 0x40f00000, v34
	v_bfi_b32 v34, s10, v34, v105
	v_cndmask_b32_e32 v109, v197, v108, vcc
	v_mul_f32_e32 v108, v34, v102
	v_sub_u32_e32 v105, 0x7f000000, v109
	v_mul_f32_e64 v34, |v103|, v105
	v_rndne_f32_e32 v34, v34
	v_mul_f32_e32 v34, v109, v34
	v_min_f32_e32 v34, 0x40f00000, v34
	v_bfi_b32 v111, s10, v34, v103
	v_mul_f32_e32 v34, v17, v104
	v_cmp_lt_f32_e64 vcc, |v34|, 4.0
	v_mov_b32_e32 v110, v33
	v_and_b32_e32 v104, 0x7fffffff, v34
	v_cndmask_b32_e32 v33, 0.5, v185, vcc
	v_cmp_nlt_f32_e64 vcc, |v34|, 2.0
	v_pk_mul_f32 v[102:103], v[110:111], v[138:139]
	s_nop 0
	v_cndmask_b32_e32 v105, v197, v33, vcc
	v_mov_b32_e32 v33, v102
	v_mov_b32_e32 v107, v103
	v_pk_add_f32 v[32:33], v[32:33], v[106:107] neg_lo:[0,1] neg_hi:[0,1]
	v_sub_u32_e32 v103, 0x7f000000, v105
	v_mul_f32_e64 v102, |v34|, v103
	v_rndne_f32_e32 v102, v102
	v_mul_f32_e32 v102, v105, v102
	v_min_f32_e32 v102, 0x40f00000, v102
	v_bfi_b32 v103, s10, v102, v34
	v_mov_b32_e32 v102, v17
	v_pk_mul_f32 v[102:103], v[102:103], v[138:139]
	v_max_f32_e64 v34, |v18|, |v2|
	v_mov_b32_e32 v17, v102
	v_max_f32_e64 v102, |v19|, |v3|
	v_mov_b32_e32 v109, v103
	v_max3_f32 v34, v34, 0, v102
	v_max_f32_e64 v102, |v20|, |v4|
	v_max_f32_e64 v103, |v21|, |v5|
	v_max3_f32 v34, v34, v102, v103
	v_max_f32_e64 v102, |v22|, |v6|
	v_max_f32_e64 v103, |v23|, |v7|
	v_max3_f32 v34, v34, v102, v103
	v_max_f32_e64 v102, |v24|, |v8|
	v_max_f32_e64 v103, |v25|, |v9|
	v_max3_f32 v34, v34, v102, v103
	v_max_f32_e64 v102, |v26|, |v10|
	v_max_f32_e64 v103, |v27|, |v11|
	v_max3_f32 v34, v34, v102, v103
	v_max_f32_e64 v102, |v28|, |v12|
	v_max_f32_e64 v103, |v29|, |v13|
	v_pk_add_f32 v[16:17], v[16:17], v[108:109] neg_lo:[0,1] neg_hi:[0,1]
	v_max3_f32 v34, v34, v102, v103
	v_max_f32_e64 v102, |v30|, |v14|
	v_max_f32_e64 v103, |v31|, |v15|
	v_max3_f32 v34, v34, v102, v103
	v_max_f32_e64 v102, |v32|, |v16|
	v_max_f32_e64 v103, |v33|, |v17|
	v_max3_f32 v34, v34, v102, v103
	v_bfe_u32 v102, v34, 23, 8
	v_and_b32_e32 v34, 0x7fffff, v34
	v_cmp_gt_u32_e32 vcc, s1, v34
	s_nop 1
	v_cndmask_b32_e64 v34, -2, -3, vcc
	v_add3_u32 v34, v102, v34, s97
	v_max_i32_e32 v34, 0xffffff88, v34
	v_add_u32_e32 v34, 0x7f, v34
	v_lshlrev_b32_e32 v108, 23, v34
	v_cvt_scalef32_2xpk16_fp6_f32 v[102:107], v[18:33], v[2:17], v108
	v_lshl_add_u64 v[2:3], v[100:101], 0, v[190:191]
	v_mul_lo_u32 v34, v34, s3
	v_lshl_add_u64 v[2:3], v[2:3], 0, v[188:189]
	v_mov_b32_e32 v32, v106
	v_mov_b32_e32 v33, v107
	global_store_dwordx4 v[2:3], v[102:105], off
	global_store_dwordx4 v[2:3], v[32:35], off offset:16

.LBB0_1630:
	s_or_b64 exec, exec, s[56:57]
	v_mul_f32_e32 v2, 0x3dd53b94, v206
	v_pk_mul_f32 v[32:33], v[2:3], v[98:99] op_sel_hi:[0,1]
	v_pk_mul_f32 v[30:31], v[2:3], v[96:97] op_sel_hi:[0,1]
	v_pk_mul_f32 v[28:29], v[2:3], v[94:95] op_sel_hi:[0,1]
	v_pk_mul_f32 v[26:27], v[2:3], v[92:93] op_sel_hi:[0,1]
	v_pk_mul_f32 v[24:25], v[2:3], v[90:91] op_sel_hi:[0,1]
	v_pk_mul_f32 v[22:23], v[2:3], v[88:89] op_sel_hi:[0,1]
	v_pk_mul_f32 v[20:21], v[2:3], v[86:87] op_sel_hi:[0,1]
	v_pk_mul_f32 v[18:19], v[2:3], v[84:85] op_sel_hi:[0,1]
	v_pk_mul_f32 v[16:17], v[2:3], v[82:83] op_sel_hi:[0,1]
	v_pk_mul_f32 v[14:15], v[2:3], v[80:81] op_sel_hi:[0,1]
	v_pk_mul_f32 v[12:13], v[2:3], v[78:79] op_sel_hi:[0,1]
	v_pk_mul_f32 v[10:11], v[2:3], v[76:77] op_sel_hi:[0,1]
	v_pk_mul_f32 v[8:9], v[2:3], v[74:75] op_sel_hi:[0,1]
	v_pk_mul_f32 v[6:7], v[2:3], v[72:73] op_sel_hi:[0,1]
	v_pk_mul_f32 v[4:5], v[2:3], v[70:71] op_sel_hi:[0,1]
	v_pk_mul_f32 v[2:3], v[2:3], v[68:69] op_sel_hi:[0,1]
	v_max_f32_e64 v68, |v18|, |v2|
	v_max_f32_e64 v69, |v19|, |v3|
	v_max3_f32 v68, v68, 0, v69
	v_max_f32_e64 v69, |v20|, |v4|
	v_max_f32_e64 v70, |v21|, |v5|
	v_max3_f32 v68, v68, v69, v70
	v_max_f32_e64 v69, |v22|, |v6|
	v_max_f32_e64 v70, |v23|, |v7|
	v_max3_f32 v68, v68, v69, v70
	v_max_f32_e64 v69, |v24|, |v8|
	v_max_f32_e64 v70, |v25|, |v9|
	v_max3_f32 v68, v68, v69, v70
	v_max_f32_e64 v69, |v26|, |v10|
	v_max_f32_e64 v70, |v27|, |v11|
	v_max3_f32 v68, v68, v69, v70
	v_max_f32_e64 v69, |v28|, |v12|
	v_max_f32_e64 v70, |v29|, |v13|
	v_max3_f32 v68, v68, v69, v70
	v_max_f32_e64 v69, |v30|, |v14|
	v_max_f32_e64 v70, |v31|, |v15|
	v_max3_f32 v68, v68, v69, v70
	v_max_f32_e64 v69, |v32|, |v16|
	v_max_f32_e64 v70, |v33|, |v17|
	v_max3_f32 v68, v68, v69, v70
	v_cmp_gt_u32_e32 vcc, 64, v104
	v_bfe_u32 v69, v68, 23, 8
	v_and_b32_e32 v68, 0x7fffff, v68
	v_cndmask_b32_e32 v34, v177, v181, vcc
	v_cndmask_b32_e64 v102, 64, 0, vcc
	v_cmp_gt_u32_e32 vcc, s1, v68
	v_ashrrev_i32_e32 v73, 31, v208
	v_and_b32_e32 v100, 32, v104
	v_cndmask_b32_e64 v68, -2, -3, vcc
	v_add3_u32 v68, v69, v68, s97
	v_max_i32_e32 v68, 0xffffff88, v68
	v_add_u32_e32 v68, 0x7f, v68
	v_lshlrev_b32_e32 v72, 23, v68
	v_mul_lo_u32 v82, v68, s3
	v_mov_b64_e32 v[68:69], s[22:23]
	v_mad_i64_i32 v[70:71], s[4:5], v141, s0, v[68:69]
	v_ashrrev_i32_e32 v69, 31, v104
	v_sub_co_u32_e32 v68, vcc, v208, v104
	v_mov_b32_e32 v101, v35
	s_nop 0
	v_subb_co_u32_e32 v69, vcc, v73, v69, vcc
	v_lshl_add_u64 v[70:71], v[68:69], 1, v[70:71]
	v_lshl_add_u64 v[84:85], v[70:71], 0, v[34:35]
	v_cvt_scalef32_2xpk16_fp6_f32 v[76:81], v[18:33], v[2:17], v72
	v_sub_u32_e32 v74, 0x7f000000, v72
	v_lshl_add_u64 v[84:85], v[84:85], 0, v[100:101]
	global_store_dwordx4 v[84:85], v[76:79], off offset:256
	v_mov_b32_e32 v83, v35
	global_store_dwordx4 v[84:85], v[80:83], off offset:272
	v_pk_mul_f32 v[76:77], v[18:19], v[74:75] op_sel_hi:[1,0]
	v_mov_b32_e32 v103, v35
	v_cmp_lt_f32_e64 vcc, |v76|, 4.0
	v_and_b32_e32 v73, 0x7fffffff, v76
	v_permlane32_swap_b32_e32 v52, v36
	v_cndmask_b32_e32 v75, 0.5, v185, vcc
	v_cmp_nlt_f32_e64 vcc, |v76|, 2.0
	v_permlane32_swap_b32_e32 v53, v37
	s_nop 0
	v_cndmask_b32_e32 v75, v197, v75, vcc
	v_permlane32_swap_b32_e32 v54, v38
	v_cmp_lt_f32_e64 vcc, |v77|, 4.0
	v_and_b32_e32 v78, 0x7fffffff, v77
	v_sub_u32_e32 v79, 0x7f000000, v75
	v_mul_f32_e64 v73, |v76|, v79
	v_cndmask_b32_e32 v79, 0.5, v185, vcc
	v_cmp_nlt_f32_e64 vcc, |v77|, 2.0
	v_rndne_f32_e32 v73, v73
	v_mul_f32_e32 v73, v75, v73
	v_cndmask_b32_e32 v79, v197, v79, vcc
	v_min_f32_e32 v73, 0x40f00000, v73
	v_bfi_b32 v76, s10, v73, v76
	v_permlane32_swap_b32_e32 v55, v39
	v_sub_u32_e32 v78, 0x7f000000, v79
	v_mul_f32_e64 v75, |v77|, v78
	v_rndne_f32_e32 v75, v75
	v_mul_f32_e32 v75, v79, v75
	v_min_f32_e32 v75, 0x40f00000, v75
	v_pk_mul_f32 v[78:79], v[2:3], v[74:75] op_sel_hi:[1,0]
	v_bfi_b32 v77, s10, v75, v77
	v_cmp_lt_f32_e64 vcc, |v78|, 4.0
	v_and_b32_e32 v75, 0x7fffffff, v78
	v_pk_mul_f32 v[76:77], v[76:77], v[72:73] op_sel_hi:[1,0]
	v_cndmask_b32_e32 v80, 0.5, v185, vcc
	v_cmp_nlt_f32_e64 vcc, |v78|, 2.0
	v_pk_fma_f32 v[18:19], v[18:19], 2.0, v[76:77] op_sel_hi:[1,0,1] neg_lo:[0,0,1] neg_hi:[0,0,1]
	v_permlane32_swap_b32_e32 v56, v44
	v_cndmask_b32_e32 v80, v197, v80, vcc
	v_permlane32_swap_b32_e32 v57, v45
	v_permlane32_swap_b32_e32 v58, v46
	v_cmp_lt_f32_e64 vcc, |v79|, 4.0
	v_and_b32_e32 v75, 0x7fffffff, v79
	v_sub_u32_e32 v76, 0x7f000000, v80
	v_mul_f32_e64 v73, |v78|, v76
	v_cndmask_b32_e32 v76, 0.5, v185, vcc
	v_cmp_nlt_f32_e64 vcc, |v79|, 2.0
	v_rndne_f32_e32 v73, v73
	v_mul_f32_e32 v73, v80, v73
	v_cndmask_b32_e32 v76, v197, v76, vcc
	v_min_f32_e32 v73, 0x40f00000, v73
	v_sub_u32_e32 v77, 0x7f000000, v76
	v_mul_f32_e64 v75, |v79|, v77
	v_rndne_f32_e32 v75, v75
	v_mul_f32_e32 v75, v76, v75
	v_min_f32_e32 v75, 0x40f00000, v75
	v_pk_mul_f32 v[80:81], v[20:21], v[74:75] op_sel_hi:[1,0]
	v_bfi_b32 v77, s10, v75, v79
	v_cmp_lt_f32_e64 vcc, |v80|, 4.0
	v_and_b32_e32 v75, 0x7fffffff, v80
	v_permlane32_swap_b32_e32 v59, v47
	v_cndmask_b32_e32 v76, 0.5, v185, vcc
	v_cmp_nlt_f32_e64 vcc, |v80|, 2.0
	v_permlane32_swap_b32_e32 v60, v48
	s_nop 0
	v_cndmask_b32_e32 v79, v197, v76, vcc
	v_bfi_b32 v76, s10, v73, v78
	v_pk_mul_f32 v[76:77], v[76:77], v[72:73] op_sel_hi:[1,0]
	v_permlane32_swap_b32_e32 v61, v49
	v_pk_fma_f32 v[2:3], v[2:3], 2.0, v[76:77] op_sel_hi:[1,0,1] neg_lo:[0,0,1] neg_hi:[0,0,1]
	v_cmp_lt_f32_e64 vcc, |v81|, 4.0
	v_and_b32_e32 v75, 0x7fffffff, v81
	v_sub_u32_e32 v76, 0x7f000000, v79
	v_mul_f32_e64 v73, |v80|, v76
	v_cndmask_b32_e32 v76, 0.5, v185, vcc
	v_cmp_nlt_f32_e64 vcc, |v81|, 2.0
	v_rndne_f32_e32 v73, v73
	v_mul_f32_e32 v73, v79, v73
	v_cndmask_b32_e32 v76, v197, v76, vcc
	v_min_f32_e32 v73, 0x40f00000, v73
	v_sub_u32_e32 v77, 0x7f000000, v76
	v_mul_f32_e64 v75, |v81|, v77
	v_rndne_f32_e32 v75, v75
	v_mul_f32_e32 v75, v76, v75
	v_min_f32_e32 v75, 0x40f00000, v75
	v_pk_mul_f32 v[78:79], v[4:5], v[74:75] op_sel_hi:[1,0]
	v_bfi_b32 v77, s10, v75, v81
	v_cmp_lt_f32_e64 vcc, |v78|, 4.0
	v_and_b32_e32 v75, 0x7fffffff, v78
	v_permlane32_swap_b32_e32 v62, v50
	v_cndmask_b32_e32 v76, 0.5, v185, vcc
	v_cmp_nlt_f32_e64 vcc, |v78|, 2.0
	v_permlane32_swap_b32_e32 v63, v51
	s_nop 0
	v_cndmask_b32_e32 v81, v197, v76, vcc
	v_bfi_b32 v76, s10, v73, v80
	v_pk_mul_f32 v[76:77], v[76:77], v[72:73] op_sel_hi:[1,0]
	v_permlane32_swap_b32_e32 v64, v40
	v_pk_fma_f32 v[20:21], v[20:21], 2.0, v[76:77] op_sel_hi:[1,0,1] neg_lo:[0,0,1] neg_hi:[0,0,1]
	v_cmp_lt_f32_e64 vcc, |v79|, 4.0
	v_and_b32_e32 v75, 0x7fffffff, v79
	v_sub_u32_e32 v76, 0x7f000000, v81
	v_mul_f32_e64 v73, |v78|, v76
	v_cndmask_b32_e32 v76, 0.5, v185, vcc
	v_cmp_nlt_f32_e64 vcc, |v79|, 2.0
	v_rndne_f32_e32 v73, v73
	v_mul_f32_e32 v73, v81, v73
	v_cndmask_b32_e32 v76, v197, v76, vcc
	v_min_f32_e32 v73, 0x40f00000, v73
	v_sub_u32_e32 v77, 0x7f000000, v76
	v_mul_f32_e64 v75, |v79|, v77
	v_rndne_f32_e32 v75, v75
	v_mul_f32_e32 v75, v76, v75
	v_min_f32_e32 v75, 0x40f00000, v75
	v_pk_mul_f32 v[80:81], v[22:23], v[74:75] op_sel_hi:[1,0]
	v_bfi_b32 v77, s10, v75, v79
	v_cmp_lt_f32_e64 vcc, |v80|, 4.0
	v_and_b32_e32 v75, 0x7fffffff, v80
	v_permlane32_swap_b32_e32 v65, v41
	v_cndmask_b32_e32 v76, 0.5, v185, vcc
	v_cmp_nlt_f32_e64 vcc, |v80|, 2.0
	v_permlane32_swap_b32_e32 v66, v42
	s_nop 0
	v_cndmask_b32_e32 v79, v197, v76, vcc
	v_bfi_b32 v76, s10, v73, v78
	v_pk_mul_f32 v[76:77], v[76:77], v[72:73] op_sel_hi:[1,0]
	v_permlane32_swap_b32_e32 v67, v43
	v_pk_fma_f32 v[4:5], v[4:5], 2.0, v[76:77] op_sel_hi:[1,0,1] neg_lo:[0,0,1] neg_hi:[0,0,1]
	v_cmp_lt_f32_e64 vcc, |v81|, 4.0
	v_and_b32_e32 v75, 0x7fffffff, v81
	v_sub_u32_e32 v76, 0x7f000000, v79
	v_mul_f32_e64 v73, |v80|, v76
	v_cndmask_b32_e32 v76, 0.5, v185, vcc
	v_cmp_nlt_f32_e64 vcc, |v81|, 2.0
	v_rndne_f32_e32 v73, v73
	v_mul_f32_e32 v73, v79, v73
	v_cndmask_b32_e32 v76, v197, v76, vcc
	v_min_f32_e32 v73, 0x40f00000, v73
	v_sub_u32_e32 v77, 0x7f000000, v76
	v_mul_f32_e64 v75, |v81|, v77
	v_rndne_f32_e32 v75, v75
	v_mul_f32_e32 v75, v76, v75
	v_min_f32_e32 v75, 0x40f00000, v75
	v_pk_mul_f32 v[78:79], v[6:7], v[74:75] op_sel_hi:[1,0]
	v_bfi_b32 v77, s10, v75, v81
	v_cmp_lt_f32_e64 vcc, |v78|, 4.0
	v_and_b32_e32 v75, 0x7fffffff, v78
	v_permlane16_swap_b32_e32 v52, v60
	v_cndmask_b32_e32 v76, 0.5, v185, vcc
	v_cmp_nlt_f32_e64 vcc, |v78|, 2.0
	v_permlane16_swap_b32_e32 v53, v61
	s_nop 0
	v_cndmask_b32_e32 v81, v197, v76, vcc
	v_bfi_b32 v76, s10, v73, v80
	v_pk_mul_f32 v[76:77], v[76:77], v[72:73] op_sel_hi:[1,0]
	v_permlane16_swap_b32_e32 v54, v62
	v_pk_fma_f32 v[22:23], v[22:23], 2.0, v[76:77] op_sel_hi:[1,0,1] neg_lo:[0,0,1] neg_hi:[0,0,1]
	v_cmp_lt_f32_e64 vcc, |v79|, 4.0
	v_and_b32_e32 v75, 0x7fffffff, v79
	v_sub_u32_e32 v76, 0x7f000000, v81
	v_mul_f32_e64 v73, |v78|, v76
	v_cndmask_b32_e32 v76, 0.5, v185, vcc
	v_cmp_nlt_f32_e64 vcc, |v79|, 2.0
	v_rndne_f32_e32 v73, v73
	v_mul_f32_e32 v73, v81, v73
	v_cndmask_b32_e32 v76, v197, v76, vcc
	v_min_f32_e32 v73, 0x40f00000, v73
	v_sub_u32_e32 v77, 0x7f000000, v76
	v_mul_f32_e64 v75, |v79|, v77
	v_rndne_f32_e32 v75, v75
	v_mul_f32_e32 v75, v76, v75
	v_min_f32_e32 v75, 0x40f00000, v75
	v_pk_mul_f32 v[80:81], v[24:25], v[74:75] op_sel_hi:[1,0]
	v_bfi_b32 v77, s10, v75, v79
	v_cmp_lt_f32_e64 vcc, |v80|, 4.0
	v_and_b32_e32 v75, 0x7fffffff, v80
	v_permlane16_swap_b32_e32 v55, v63
	v_cndmask_b32_e32 v76, 0.5, v185, vcc
	v_cmp_nlt_f32_e64 vcc, |v80|, 2.0
	v_permlane16_swap_b32_e32 v56, v64
	s_nop 0
	v_cndmask_b32_e32 v79, v197, v76, vcc
	v_bfi_b32 v76, s10, v73, v78
	v_pk_mul_f32 v[76:77], v[76:77], v[72:73] op_sel_hi:[1,0]
	v_permlane16_swap_b32_e32 v57, v65
	v_pk_fma_f32 v[6:7], v[6:7], 2.0, v[76:77] op_sel_hi:[1,0,1] neg_lo:[0,0,1] neg_hi:[0,0,1]
	v_cmp_lt_f32_e64 vcc, |v81|, 4.0
	v_and_b32_e32 v75, 0x7fffffff, v81
	v_sub_u32_e32 v76, 0x7f000000, v79
	v_mul_f32_e64 v73, |v80|, v76
	v_cndmask_b32_e32 v76, 0.5, v185, vcc
	v_cmp_nlt_f32_e64 vcc, |v81|, 2.0
	v_rndne_f32_e32 v73, v73
	v_mul_f32_e32 v73, v79, v73
	v_cndmask_b32_e32 v76, v197, v76, vcc
	v_min_f32_e32 v73, 0x40f00000, v73
	v_sub_u32_e32 v77, 0x7f000000, v76
	v_mul_f32_e64 v75, |v81|, v77
	v_rndne_f32_e32 v75, v75
	v_mul_f32_e32 v75, v76, v75
	v_min_f32_e32 v75, 0x40f00000, v75
	v_pk_mul_f32 v[78:79], v[8:9], v[74:75] op_sel_hi:[1,0]
	v_bfi_b32 v77, s10, v75, v81
	v_cmp_lt_f32_e64 vcc, |v78|, 4.0
	v_and_b32_e32 v75, 0x7fffffff, v78
	v_permlane16_swap_b32_e32 v58, v66
	v_cndmask_b32_e32 v76, 0.5, v185, vcc
	v_cmp_nlt_f32_e64 vcc, |v78|, 2.0
	v_permlane16_swap_b32_e32 v59, v67
	s_nop 0
	v_cndmask_b32_e32 v81, v197, v76, vcc
	v_bfi_b32 v76, s10, v73, v80
	v_pk_mul_f32 v[76:77], v[76:77], v[72:73] op_sel_hi:[1,0]
	v_permlane16_swap_b32_e32 v36, v48
	v_pk_fma_f32 v[24:25], v[24:25], 2.0, v[76:77] op_sel_hi:[1,0,1] neg_lo:[0,0,1] neg_hi:[0,0,1]
	v_cmp_lt_f32_e64 vcc, |v79|, 4.0
	v_and_b32_e32 v75, 0x7fffffff, v79
	v_sub_u32_e32 v76, 0x7f000000, v81
	v_mul_f32_e64 v73, |v78|, v76
	v_cndmask_b32_e32 v76, 0.5, v185, vcc
	v_cmp_nlt_f32_e64 vcc, |v79|, 2.0
	v_rndne_f32_e32 v73, v73
	v_mul_f32_e32 v73, v81, v73
	v_cndmask_b32_e32 v76, v197, v76, vcc
	v_min_f32_e32 v73, 0x40f00000, v73
	v_sub_u32_e32 v77, 0x7f000000, v76
	v_mul_f32_e64 v75, |v79|, v77
	v_rndne_f32_e32 v75, v75
	v_mul_f32_e32 v75, v76, v75
	v_min_f32_e32 v75, 0x40f00000, v75
	v_pk_mul_f32 v[80:81], v[26:27], v[74:75] op_sel_hi:[1,0]
	v_bfi_b32 v77, s10, v75, v79
	v_cmp_lt_f32_e64 vcc, |v80|, 4.0
	v_and_b32_e32 v75, 0x7fffffff, v80
	v_permlane16_swap_b32_e32 v37, v49
	v_cndmask_b32_e32 v76, 0.5, v185, vcc
	v_cmp_nlt_f32_e64 vcc, |v80|, 2.0
	v_permlane16_swap_b32_e32 v38, v50
	s_nop 0
	v_cndmask_b32_e32 v79, v197, v76, vcc
	v_bfi_b32 v76, s10, v73, v78
	v_pk_mul_f32 v[76:77], v[76:77], v[72:73] op_sel_hi:[1,0]
	v_permlane16_swap_b32_e32 v39, v51
	v_pk_fma_f32 v[8:9], v[8:9], 2.0, v[76:77] op_sel_hi:[1,0,1] neg_lo:[0,0,1] neg_hi:[0,0,1]
	v_cmp_lt_f32_e64 vcc, |v81|, 4.0
	v_and_b32_e32 v75, 0x7fffffff, v81
	v_sub_u32_e32 v76, 0x7f000000, v79
	v_mul_f32_e64 v73, |v80|, v76
	v_cndmask_b32_e32 v76, 0.5, v185, vcc
	v_cmp_nlt_f32_e64 vcc, |v81|, 2.0
	v_rndne_f32_e32 v73, v73
	v_mul_f32_e32 v73, v79, v73
	v_cndmask_b32_e32 v76, v197, v76, vcc
	v_min_f32_e32 v73, 0x40f00000, v73
	v_sub_u32_e32 v77, 0x7f000000, v76
	v_mul_f32_e64 v75, |v81|, v77
	v_rndne_f32_e32 v75, v75
	v_mul_f32_e32 v75, v76, v75
	v_min_f32_e32 v75, 0x40f00000, v75
	v_pk_mul_f32 v[78:79], v[10:11], v[74:75] op_sel_hi:[1,0]
	v_bfi_b32 v77, s10, v75, v81
	v_cmp_lt_f32_e64 vcc, |v78|, 4.0
	v_and_b32_e32 v75, 0x7fffffff, v78
	v_permlane16_swap_b32_e32 v44, v40
	v_cndmask_b32_e32 v76, 0.5, v185, vcc
	v_cmp_nlt_f32_e64 vcc, |v78|, 2.0
	v_permlane16_swap_b32_e32 v45, v41
	s_nop 0
	v_cndmask_b32_e32 v81, v197, v76, vcc
	v_bfi_b32 v76, s10, v73, v80
	v_pk_mul_f32 v[76:77], v[76:77], v[72:73] op_sel_hi:[1,0]
	v_permlane16_swap_b32_e32 v46, v42
	v_pk_fma_f32 v[26:27], v[26:27], 2.0, v[76:77] op_sel_hi:[1,0,1] neg_lo:[0,0,1] neg_hi:[0,0,1]
	v_cmp_lt_f32_e64 vcc, |v79|, 4.0
	v_and_b32_e32 v75, 0x7fffffff, v79
	v_sub_u32_e32 v76, 0x7f000000, v81
	v_mul_f32_e64 v73, |v78|, v76
	v_cndmask_b32_e32 v76, 0.5, v185, vcc
	v_cmp_nlt_f32_e64 vcc, |v79|, 2.0
	v_rndne_f32_e32 v73, v73
	v_mul_f32_e32 v73, v81, v73
	v_cndmask_b32_e32 v76, v197, v76, vcc
	v_min_f32_e32 v73, 0x40f00000, v73
	v_sub_u32_e32 v77, 0x7f000000, v76
	v_mul_f32_e64 v75, |v79|, v77
	v_rndne_f32_e32 v75, v75
	v_mul_f32_e32 v75, v76, v75
	v_min_f32_e32 v75, 0x40f00000, v75
	v_pk_mul_f32 v[80:81], v[28:29], v[74:75] op_sel_hi:[1,0]
	v_bfi_b32 v77, s10, v75, v79
	v_cmp_lt_f32_e64 vcc, |v80|, 4.0
	v_and_b32_e32 v75, 0x7fffffff, v80
	v_permlane16_swap_b32_e32 v47, v43
	v_cndmask_b32_e32 v76, 0.5, v185, vcc
	v_cmp_nlt_f32_e64 vcc, |v80|, 2.0
	s_nop 1
	v_cndmask_b32_e32 v79, v197, v76, vcc
	v_bfi_b32 v76, s10, v73, v78
	v_pk_mul_f32 v[76:77], v[76:77], v[72:73] op_sel_hi:[1,0]
	v_pk_fma_f32 v[10:11], v[10:11], 2.0, v[76:77] op_sel_hi:[1,0,1] neg_lo:[0,0,1] neg_hi:[0,0,1]
	v_cmp_lt_f32_e64 vcc, |v81|, 4.0
	v_and_b32_e32 v75, 0x7fffffff, v81
	v_sub_u32_e32 v76, 0x7f000000, v79
	v_mul_f32_e64 v73, |v80|, v76
	v_cndmask_b32_e32 v76, 0.5, v185, vcc
	v_cmp_nlt_f32_e64 vcc, |v81|, 2.0
	v_rndne_f32_e32 v73, v73
	v_mul_f32_e32 v73, v79, v73
	v_cndmask_b32_e32 v76, v197, v76, vcc
	v_min_f32_e32 v73, 0x40f00000, v73
	v_sub_u32_e32 v77, 0x7f000000, v76
	v_mul_f32_e64 v75, |v81|, v77
	v_rndne_f32_e32 v75, v75
	v_mul_f32_e32 v75, v76, v75
	v_min_f32_e32 v75, 0x40f00000, v75
	v_pk_mul_f32 v[78:79], v[12:13], v[74:75] op_sel_hi:[1,0]
	v_bfi_b32 v77, s10, v75, v81
	v_cmp_lt_f32_e64 vcc, |v78|, 4.0
	v_and_b32_e32 v75, 0x7fffffff, v78
	s_nop 0
	v_cndmask_b32_e32 v76, 0.5, v185, vcc
	v_cmp_nlt_f32_e64 vcc, |v78|, 2.0
	s_nop 1
	v_cndmask_b32_e32 v81, v197, v76, vcc
	v_bfi_b32 v76, s10, v73, v80
	v_pk_mul_f32 v[76:77], v[76:77], v[72:73] op_sel_hi:[1,0]
	v_pk_fma_f32 v[28:29], v[28:29], 2.0, v[76:77] op_sel_hi:[1,0,1] neg_lo:[0,0,1] neg_hi:[0,0,1]
	v_cmp_lt_f32_e64 vcc, |v79|, 4.0
	v_and_b32_e32 v75, 0x7fffffff, v79
	v_sub_u32_e32 v76, 0x7f000000, v81
	v_mul_f32_e64 v73, |v78|, v76
	v_cndmask_b32_e32 v76, 0.5, v185, vcc
	v_cmp_nlt_f32_e64 vcc, |v79|, 2.0
	v_rndne_f32_e32 v73, v73
	v_mul_f32_e32 v73, v81, v73
	v_cndmask_b32_e32 v76, v197, v76, vcc
	v_min_f32_e32 v73, 0x40f00000, v73
	v_sub_u32_e32 v77, 0x7f000000, v76
	v_mul_f32_e64 v75, |v79|, v77
	v_rndne_f32_e32 v75, v75
	v_mul_f32_e32 v75, v76, v75
	v_min_f32_e32 v75, 0x40f00000, v75
	v_pk_mul_f32 v[80:81], v[30:31], v[74:75] op_sel_hi:[1,0]
	v_bfi_b32 v77, s10, v75, v79
	v_cmp_lt_f32_e64 vcc, |v80|, 4.0
	v_and_b32_e32 v75, 0x7fffffff, v80
	s_nop 0
	v_cndmask_b32_e32 v76, 0.5, v185, vcc
	v_cmp_nlt_f32_e64 vcc, |v80|, 2.0
	s_nop 1
	v_cndmask_b32_e32 v79, v197, v76, vcc
	v_bfi_b32 v76, s10, v73, v78
	v_pk_mul_f32 v[76:77], v[76:77], v[72:73] op_sel_hi:[1,0]
	v_pk_fma_f32 v[12:13], v[12:13], 2.0, v[76:77] op_sel_hi:[1,0,1] neg_lo:[0,0,1] neg_hi:[0,0,1]
	v_cmp_lt_f32_e64 vcc, |v81|, 4.0
	v_and_b32_e32 v75, 0x7fffffff, v81
	v_sub_u32_e32 v76, 0x7f000000, v79
	v_mul_f32_e64 v73, |v80|, v76
	v_cndmask_b32_e32 v76, 0.5, v185, vcc
	v_cmp_nlt_f32_e64 vcc, |v81|, 2.0
	v_rndne_f32_e32 v73, v73
	v_mul_f32_e32 v73, v79, v73
	v_cndmask_b32_e32 v76, v197, v76, vcc
	v_min_f32_e32 v73, 0x40f00000, v73
	v_sub_u32_e32 v77, 0x7f000000, v76
	v_mul_f32_e64 v75, |v81|, v77
	v_rndne_f32_e32 v75, v75
	v_mul_f32_e32 v75, v76, v75
	v_min_f32_e32 v75, 0x40f00000, v75
	v_pk_mul_f32 v[78:79], v[14:15], v[74:75] op_sel_hi:[1,0]
	v_bfi_b32 v77, s10, v75, v81
	v_cmp_lt_f32_e64 vcc, |v78|, 4.0
	v_and_b32_e32 v75, 0x7fffffff, v78
	s_nop 0
	v_cndmask_b32_e32 v76, 0.5, v185, vcc
	v_cmp_nlt_f32_e64 vcc, |v78|, 2.0
	s_nop 1
	v_cndmask_b32_e32 v81, v197, v76, vcc
	v_bfi_b32 v76, s10, v73, v80
	v_pk_mul_f32 v[76:77], v[76:77], v[72:73] op_sel_hi:[1,0]
	v_pk_fma_f32 v[30:31], v[30:31], 2.0, v[76:77] op_sel_hi:[1,0,1] neg_lo:[0,0,1] neg_hi:[0,0,1]
	v_cmp_lt_f32_e64 vcc, |v79|, 4.0
	v_and_b32_e32 v75, 0x7fffffff, v79
	v_sub_u32_e32 v76, 0x7f000000, v81
	v_mul_f32_e64 v73, |v78|, v76
	v_cndmask_b32_e32 v76, 0.5, v185, vcc
	v_cmp_nlt_f32_e64 vcc, |v79|, 2.0
	v_rndne_f32_e32 v73, v73
	v_mul_f32_e32 v73, v81, v73
	v_cndmask_b32_e32 v76, v197, v76, vcc
	v_min_f32_e32 v73, 0x40f00000, v73
	v_sub_u32_e32 v77, 0x7f000000, v76
	v_mul_f32_e64 v75, |v79|, v77
	v_rndne_f32_e32 v75, v75
	v_mul_f32_e32 v75, v76, v75
	v_min_f32_e32 v75, 0x40f00000, v75
	v_pk_mul_f32 v[80:81], v[32:33], v[74:75] op_sel_hi:[1,0]
	v_bfi_b32 v77, s10, v75, v79
	v_cmp_lt_f32_e64 vcc, |v80|, 4.0
	v_and_b32_e32 v75, 0x7fffffff, v80
	s_nop 0
	v_cndmask_b32_e32 v76, 0.5, v185, vcc
	v_cmp_nlt_f32_e64 vcc, |v80|, 2.0
	s_nop 1
	v_cndmask_b32_e32 v79, v197, v76, vcc
	v_bfi_b32 v76, s10, v73, v78
	v_pk_mul_f32 v[76:77], v[76:77], v[72:73] op_sel_hi:[1,0]
	v_pk_fma_f32 v[14:15], v[14:15], 2.0, v[76:77] op_sel_hi:[1,0,1] neg_lo:[0,0,1] neg_hi:[0,0,1]
	v_cmp_lt_f32_e64 vcc, |v81|, 4.0
	v_and_b32_e32 v75, 0x7fffffff, v81
	v_sub_u32_e32 v76, 0x7f000000, v79
	v_mul_f32_e64 v73, |v80|, v76
	v_cndmask_b32_e32 v76, 0.5, v185, vcc
	v_cmp_nlt_f32_e64 vcc, |v81|, 2.0
	v_rndne_f32_e32 v73, v73
	v_mul_f32_e32 v73, v79, v73
	v_cndmask_b32_e32 v76, v197, v76, vcc
	v_min_f32_e32 v73, 0x40f00000, v73
	v_sub_u32_e32 v77, 0x7f000000, v76
	v_mul_f32_e64 v75, |v81|, v77
	v_rndne_f32_e32 v75, v75
	v_mul_f32_e32 v75, v76, v75
	v_min_f32_e32 v75, 0x40f00000, v75
	v_bfi_b32 v75, s10, v75, v81
	v_pk_mul_f32 v[76:77], v[16:17], v[74:75] op_sel_hi:[1,0]
	s_nop 0
	v_cmp_lt_f32_e64 vcc, |v76|, 4.0
	v_and_b32_e32 v78, 0x7fffffff, v76
	s_nop 0
	v_cndmask_b32_e32 v74, 0.5, v185, vcc
	v_cmp_nlt_f32_e64 vcc, |v76|, 2.0
	s_nop 1
	v_cndmask_b32_e32 v79, v197, v74, vcc
	v_bfi_b32 v74, s10, v73, v80
	v_pk_mul_f32 v[74:75], v[74:75], v[72:73] op_sel_hi:[1,0]
	v_pk_fma_f32 v[32:33], v[32:33], 2.0, v[74:75] op_sel_hi:[1,0,1] neg_lo:[0,0,1] neg_hi:[0,0,1]
	v_cmp_lt_f32_e64 vcc, |v77|, 4.0
	v_and_b32_e32 v74, 0x7fffffff, v77
	v_sub_u32_e32 v75, 0x7f000000, v79
	v_mul_f32_e64 v73, |v76|, v75
	v_cndmask_b32_e32 v75, 0.5, v185, vcc
	v_cmp_nlt_f32_e64 vcc, |v77|, 2.0
	v_rndne_f32_e32 v73, v73
	v_mul_f32_e32 v73, v79, v73
	v_cndmask_b32_e32 v75, v197, v75, vcc
	v_min_f32_e32 v73, 0x40f00000, v73
	v_sub_u32_e32 v78, 0x7f000000, v75
	v_mul_f32_e64 v74, |v77|, v78
	v_rndne_f32_e32 v74, v74
	v_mul_f32_e32 v74, v75, v74
	v_min_f32_e32 v74, 0x40f00000, v74
	v_bfi_b32 v75, s10, v74, v77
	v_bfi_b32 v74, s10, v73, v76
	v_pk_mul_f32 v[72:73], v[74:75], v[72:73] op_sel_hi:[1,0]
	v_max_f32_e64 v74, |v21|, |v5|
	v_pk_fma_f32 v[16:17], v[16:17], 2.0, v[72:73] op_sel_hi:[1,0,1] neg_lo:[0,0,1] neg_hi:[0,0,1]
	v_max_f32_e64 v72, |v18|, |v2|
	v_max_f32_e64 v73, |v19|, |v3|
	v_max3_f32 v72, v72, 0, v73
	v_max_f32_e64 v73, |v20|, |v4|
	v_max3_f32 v72, v72, v73, v74
	v_max_f32_e64 v73, |v22|, |v6|
	v_max_f32_e64 v74, |v23|, |v7|
	v_max3_f32 v72, v72, v73, v74
	v_max_f32_e64 v73, |v24|, |v8|
	v_max_f32_e64 v74, |v25|, |v9|
	v_max3_f32 v72, v72, v73, v74
	v_max_f32_e64 v73, |v26|, |v10|
	v_max_f32_e64 v74, |v27|, |v11|
	v_max3_f32 v72, v72, v73, v74
	v_max_f32_e64 v73, |v28|, |v12|
	v_max_f32_e64 v74, |v29|, |v13|
	v_max3_f32 v72, v72, v73, v74
	v_max_f32_e64 v73, |v30|, |v14|
	v_max_f32_e64 v74, |v31|, |v15|
	v_max3_f32 v72, v72, v73, v74
	v_max_f32_e64 v73, |v32|, |v16|
	v_max_f32_e64 v74, |v33|, |v17|
	v_max3_f32 v72, v72, v73, v74
	v_bfe_u32 v73, v72, 23, 8
	v_and_b32_e32 v72, 0x7fffff, v72
	v_cmp_gt_u32_e32 vcc, s1, v72
	s_nop 1
	v_cndmask_b32_e64 v72, -2, -3, vcc
	v_add3_u32 v72, v73, v72, s97
	v_max_i32_e32 v72, 0xffffff88, v72
	v_add_u32_e32 v72, 0x7f, v72
	v_lshlrev_b32_e32 v79, 23, v72
	v_mul_lo_u32 v78, v72, s3
	v_cvt_scalef32_2xpk16_fp6_f32 v[72:77], v[18:33], v[2:17], v79
	v_lshl_add_u64 v[2:3], v[70:71], 0, v[102:103]
	v_lshl_add_u64 v[2:3], v[2:3], 0, v[100:101]
	v_mov_b32_e32 v79, v35
	v_cmp_lt_i32_e32 vcc, 1, v199
	global_store_dwordx4 v[2:3], v[72:75], off offset:256
	global_store_dwordx4 v[2:3], v[76:79], off offset:272
	s_and_saveexec_b64 s[4:5], vcc
	s_xor_b64 s[4:5], exec, s[4:5]
	s_cbranch_execz .LBB0_1634
	v_cmp_gt_i32_e32 vcc, 3, v199
	s_and_saveexec_b64 s[56:57], vcc
	v_mov_b32_e32 v207, v204
	s_or_b64 exec, exec, s[56:57]

.LBB0_1640:
	s_or_b64 exec, exec, s[56:57]
	v_mul_f32_e32 v2, 0x3dd53b94, v207
	v_pk_mul_f32 v[32:33], v[2:3], v[66:67] op_sel_hi:[0,1]
	v_pk_mul_f32 v[30:31], v[2:3], v[64:65] op_sel_hi:[0,1]
	v_pk_mul_f32 v[28:29], v[2:3], v[62:63] op_sel_hi:[0,1]
	v_pk_mul_f32 v[26:27], v[2:3], v[60:61] op_sel_hi:[0,1]
	v_pk_mul_f32 v[24:25], v[2:3], v[58:59] op_sel_hi:[0,1]
	v_pk_mul_f32 v[22:23], v[2:3], v[56:57] op_sel_hi:[0,1]
	v_pk_mul_f32 v[20:21], v[2:3], v[54:55] op_sel_hi:[0,1]
	v_pk_mul_f32 v[18:19], v[2:3], v[52:53] op_sel_hi:[0,1]
	v_pk_mul_f32 v[16:17], v[2:3], v[42:43] op_sel_hi:[0,1]
	v_pk_mul_f32 v[14:15], v[2:3], v[40:41] op_sel_hi:[0,1]
	v_pk_mul_f32 v[12:13], v[2:3], v[50:51] op_sel_hi:[0,1]
	v_pk_mul_f32 v[10:11], v[2:3], v[48:49] op_sel_hi:[0,1]
	v_pk_mul_f32 v[8:9], v[2:3], v[46:47] op_sel_hi:[0,1]
	v_pk_mul_f32 v[6:7], v[2:3], v[44:45] op_sel_hi:[0,1]
	v_pk_mul_f32 v[4:5], v[2:3], v[38:39] op_sel_hi:[0,1]
	v_pk_mul_f32 v[2:3], v[2:3], v[36:37] op_sel_hi:[0,1]
	v_max_f32_e64 v36, |v18|, |v2|
	v_max_f32_e64 v37, |v19|, |v3|
	v_max3_f32 v36, v36, 0, v37
	v_max_f32_e64 v37, |v20|, |v4|
	v_max_f32_e64 v38, |v21|, |v5|
	v_max3_f32 v36, v36, v37, v38
	v_max_f32_e64 v37, |v22|, |v6|
	v_max_f32_e64 v38, |v23|, |v7|
	v_max3_f32 v36, v36, v37, v38
	v_max_f32_e64 v37, |v24|, |v8|
	v_max_f32_e64 v38, |v25|, |v9|
	v_max3_f32 v36, v36, v37, v38
	v_max_f32_e64 v37, |v26|, |v10|
	v_max_f32_e64 v38, |v27|, |v11|
	v_max3_f32 v36, v36, v37, v38
	v_max_f32_e64 v37, |v28|, |v12|
	v_max_f32_e64 v38, |v29|, |v13|
	v_max3_f32 v36, v36, v37, v38
	v_max_f32_e64 v37, |v30|, |v14|
	v_max_f32_e64 v38, |v31|, |v15|
	v_max3_f32 v36, v36, v37, v38
	v_max_f32_e64 v37, |v32|, |v16|
	v_max_f32_e64 v38, |v33|, |v17|
	v_max3_f32 v36, v36, v37, v38
	v_bfe_u32 v37, v36, 23, 8
	v_and_b32_e32 v36, 0x7fffff, v36
	v_cmp_gt_u32_e32 vcc, s1, v36
	v_add_u32_e32 v39, 0x80, v141
	v_mov_b32_e32 v49, v35
	v_cndmask_b32_e64 v36, -2, -3, vcc
	v_add3_u32 v36, v37, v36, s97
	v_max_i32_e32 v36, 0xffffff88, v36
	v_add_u32_e32 v36, 0x7f, v36
	v_lshlrev_b32_e32 v38, 23, v36
	v_mul_lo_u32 v48, v36, s3
	v_mov_b64_e32 v[36:37], s[22:23]
	v_mad_i64_i32 v[36:37], s[4:5], v39, s0, v[36:37]
	v_lshl_add_u64 v[36:37], v[68:69], 1, v[36:37]
	v_lshl_add_u64 v[50:51], v[36:37], 0, v[34:35]
	v_cvt_scalef32_2xpk16_fp6_f32 v[42:47], v[18:33], v[2:17], v38
	v_sub_u32_e32 v40, 0x7f000000, v38
	v_lshl_add_u64 v[50:51], v[50:51], 0, v[100:101]
	global_store_dwordx4 v[50:51], v[42:45], off offset:256
	global_store_dwordx4 v[50:51], v[46:49], off offset:272
	s_nop 0
	v_pk_mul_f32 v[42:43], v[18:19], v[40:41] op_sel_hi:[1,0]
	s_nop 0
	v_cmp_lt_f32_e64 vcc, |v42|, 4.0
	v_and_b32_e32 v34, 0x7fffffff, v42
	s_nop 0
	v_cndmask_b32_e32 v39, 0.5, v185, vcc
	v_cmp_nlt_f32_e64 vcc, |v42|, 2.0
	s_nop 1
	v_cndmask_b32_e32 v39, v197, v39, vcc
	v_cmp_lt_f32_e64 vcc, |v43|, 4.0
	v_and_b32_e32 v41, 0x7fffffff, v43
	v_sub_u32_e32 v44, 0x7f000000, v39
	v_mul_f32_e64 v34, |v42|, v44
	v_cndmask_b32_e32 v44, 0.5, v185, vcc
	v_cmp_nlt_f32_e64 vcc, |v43|, 2.0
	v_rndne_f32_e32 v34, v34
	v_mul_f32_e32 v34, v39, v34
	v_cndmask_b32_e32 v44, v197, v44, vcc
	v_min_f32_e32 v34, 0x40f00000, v34
	v_bfi_b32 v42, s10, v34, v42
	v_sub_u32_e32 v41, 0x7f000000, v44
	v_mul_f32_e64 v39, |v43|, v41
	v_rndne_f32_e32 v39, v39
	v_mul_f32_e32 v39, v44, v39
	v_pk_mul_f32 v[44:45], v[2:3], v[40:41] op_sel_hi:[1,0]
	v_min_f32_e32 v39, 0x40f00000, v39
	v_cmp_lt_f32_e64 vcc, |v44|, 4.0
	v_bfi_b32 v43, s10, v39, v43
	v_and_b32_e32 v39, 0x7fffffff, v44
	v_cndmask_b32_e32 v41, 0.5, v185, vcc
	v_cmp_nlt_f32_e64 vcc, |v44|, 2.0
	v_pk_mul_f32 v[42:43], v[42:43], v[38:39] op_sel_hi:[1,0]
	s_nop 0
	v_cndmask_b32_e32 v41, v197, v41, vcc
	v_pk_fma_f32 v[18:19], v[18:19], 2.0, v[42:43] op_sel_hi:[1,0,1] neg_lo:[0,0,1] neg_hi:[0,0,1]
	v_cmp_lt_f32_e64 vcc, |v45|, 4.0
	v_and_b32_e32 v39, 0x7fffffff, v45
	v_sub_u32_e32 v42, 0x7f000000, v41
	v_mul_f32_e64 v34, |v44|, v42
	v_cndmask_b32_e32 v42, 0.5, v185, vcc
	v_cmp_nlt_f32_e64 vcc, |v45|, 2.0
	v_rndne_f32_e32 v34, v34
	v_mul_f32_e32 v34, v41, v34
	v_cndmask_b32_e32 v42, v197, v42, vcc
	v_min_f32_e32 v34, 0x40f00000, v34
	v_sub_u32_e32 v41, 0x7f000000, v42
	v_mul_f32_e64 v39, |v45|, v41
	v_rndne_f32_e32 v39, v39
	v_pk_mul_f32 v[46:47], v[20:21], v[40:41] op_sel_hi:[1,0]
	v_mul_f32_e32 v39, v42, v39
	v_cmp_lt_f32_e64 vcc, |v46|, 4.0
	v_min_f32_e32 v39, 0x40f00000, v39
	v_bfi_b32 v43, s10, v39, v45
	v_cndmask_b32_e32 v41, 0.5, v185, vcc
	v_cmp_nlt_f32_e64 vcc, |v46|, 2.0
	v_and_b32_e32 v39, 0x7fffffff, v46
	v_bfi_b32 v42, s10, v34, v44
	v_cndmask_b32_e32 v41, v197, v41, vcc
	v_pk_mul_f32 v[42:43], v[42:43], v[38:39] op_sel_hi:[1,0]
	v_pk_fma_f32 v[2:3], v[2:3], 2.0, v[42:43] op_sel_hi:[1,0,1] neg_lo:[0,0,1] neg_hi:[0,0,1]
	v_cmp_lt_f32_e64 vcc, |v47|, 4.0
	v_and_b32_e32 v39, 0x7fffffff, v47
	v_sub_u32_e32 v42, 0x7f000000, v41
	v_mul_f32_e64 v34, |v46|, v42
	v_cndmask_b32_e32 v42, 0.5, v185, vcc
	v_cmp_nlt_f32_e64 vcc, |v47|, 2.0
	v_rndne_f32_e32 v34, v34
	v_mul_f32_e32 v34, v41, v34
	v_cndmask_b32_e32 v42, v197, v42, vcc
	v_min_f32_e32 v34, 0x40f00000, v34
	v_sub_u32_e32 v41, 0x7f000000, v42
	v_mul_f32_e64 v39, |v47|, v41
	v_rndne_f32_e32 v39, v39
	v_pk_mul_f32 v[44:45], v[4:5], v[40:41] op_sel_hi:[1,0]
	v_mul_f32_e32 v39, v42, v39
	v_cmp_lt_f32_e64 vcc, |v44|, 4.0
	v_min_f32_e32 v39, 0x40f00000, v39
	v_bfi_b32 v43, s10, v39, v47
	v_cndmask_b32_e32 v41, 0.5, v185, vcc
	v_cmp_nlt_f32_e64 vcc, |v44|, 2.0
	v_and_b32_e32 v39, 0x7fffffff, v44
	v_bfi_b32 v42, s10, v34, v46
	v_cndmask_b32_e32 v41, v197, v41, vcc
	v_pk_mul_f32 v[42:43], v[42:43], v[38:39] op_sel_hi:[1,0]
	v_pk_fma_f32 v[20:21], v[20:21], 2.0, v[42:43] op_sel_hi:[1,0,1] neg_lo:[0,0,1] neg_hi:[0,0,1]
	v_cmp_lt_f32_e64 vcc, |v45|, 4.0
	v_and_b32_e32 v39, 0x7fffffff, v45
	v_sub_u32_e32 v42, 0x7f000000, v41
	v_mul_f32_e64 v34, |v44|, v42
	v_cndmask_b32_e32 v42, 0.5, v185, vcc
	v_cmp_nlt_f32_e64 vcc, |v45|, 2.0
	v_rndne_f32_e32 v34, v34
	v_mul_f32_e32 v34, v41, v34
	v_cndmask_b32_e32 v42, v197, v42, vcc
	v_min_f32_e32 v34, 0x40f00000, v34
	v_sub_u32_e32 v41, 0x7f000000, v42
	v_mul_f32_e64 v39, |v45|, v41
	v_rndne_f32_e32 v39, v39
	v_pk_mul_f32 v[46:47], v[22:23], v[40:41] op_sel_hi:[1,0]
	v_mul_f32_e32 v39, v42, v39
	v_cmp_lt_f32_e64 vcc, |v46|, 4.0
	v_min_f32_e32 v39, 0x40f00000, v39
	v_bfi_b32 v43, s10, v39, v45
	v_cndmask_b32_e32 v41, 0.5, v185, vcc
	v_cmp_nlt_f32_e64 vcc, |v46|, 2.0
	v_and_b32_e32 v39, 0x7fffffff, v46
	v_bfi_b32 v42, s10, v34, v44
	v_cndmask_b32_e32 v41, v197, v41, vcc
	v_pk_mul_f32 v[42:43], v[42:43], v[38:39] op_sel_hi:[1,0]
	v_pk_fma_f32 v[4:5], v[4:5], 2.0, v[42:43] op_sel_hi:[1,0,1] neg_lo:[0,0,1] neg_hi:[0,0,1]
	v_cmp_lt_f32_e64 vcc, |v47|, 4.0
	v_and_b32_e32 v39, 0x7fffffff, v47
	v_sub_u32_e32 v42, 0x7f000000, v41
	v_mul_f32_e64 v34, |v46|, v42
	v_cndmask_b32_e32 v42, 0.5, v185, vcc
	v_cmp_nlt_f32_e64 vcc, |v47|, 2.0
	v_rndne_f32_e32 v34, v34
	v_mul_f32_e32 v34, v41, v34
	v_cndmask_b32_e32 v42, v197, v42, vcc
	v_min_f32_e32 v34, 0x40f00000, v34
	v_sub_u32_e32 v41, 0x7f000000, v42
	v_mul_f32_e64 v39, |v47|, v41
	v_rndne_f32_e32 v39, v39
	v_pk_mul_f32 v[44:45], v[6:7], v[40:41] op_sel_hi:[1,0]
	v_mul_f32_e32 v39, v42, v39
	v_cmp_lt_f32_e64 vcc, |v44|, 4.0
	v_min_f32_e32 v39, 0x40f00000, v39
	v_bfi_b32 v43, s10, v39, v47
	v_cndmask_b32_e32 v41, 0.5, v185, vcc
	v_cmp_nlt_f32_e64 vcc, |v44|, 2.0
	v_and_b32_e32 v39, 0x7fffffff, v44
	v_bfi_b32 v42, s10, v34, v46
	v_cndmask_b32_e32 v41, v197, v41, vcc
	v_pk_mul_f32 v[42:43], v[42:43], v[38:39] op_sel_hi:[1,0]
	v_pk_fma_f32 v[22:23], v[22:23], 2.0, v[42:43] op_sel_hi:[1,0,1] neg_lo:[0,0,1] neg_hi:[0,0,1]
	v_cmp_lt_f32_e64 vcc, |v45|, 4.0
	v_and_b32_e32 v39, 0x7fffffff, v45
	v_sub_u32_e32 v42, 0x7f000000, v41
	v_mul_f32_e64 v34, |v44|, v42
	v_cndmask_b32_e32 v42, 0.5, v185, vcc
	v_cmp_nlt_f32_e64 vcc, |v45|, 2.0
	v_rndne_f32_e32 v34, v34
	v_mul_f32_e32 v34, v41, v34
	v_cndmask_b32_e32 v42, v197, v42, vcc
	v_min_f32_e32 v34, 0x40f00000, v34
	v_sub_u32_e32 v41, 0x7f000000, v42
	v_mul_f32_e64 v39, |v45|, v41
	v_rndne_f32_e32 v39, v39
	v_pk_mul_f32 v[46:47], v[24:25], v[40:41] op_sel_hi:[1,0]
	v_mul_f32_e32 v39, v42, v39
	v_cmp_lt_f32_e64 vcc, |v46|, 4.0
	v_min_f32_e32 v39, 0x40f00000, v39
	v_bfi_b32 v43, s10, v39, v45
	v_cndmask_b32_e32 v41, 0.5, v185, vcc
	v_cmp_nlt_f32_e64 vcc, |v46|, 2.0
	v_and_b32_e32 v39, 0x7fffffff, v46
	v_bfi_b32 v42, s10, v34, v44
	v_cndmask_b32_e32 v41, v197, v41, vcc
	v_pk_mul_f32 v[42:43], v[42:43], v[38:39] op_sel_hi:[1,0]
	v_pk_fma_f32 v[6:7], v[6:7], 2.0, v[42:43] op_sel_hi:[1,0,1] neg_lo:[0,0,1] neg_hi:[0,0,1]
	v_cmp_lt_f32_e64 vcc, |v47|, 4.0
	v_and_b32_e32 v39, 0x7fffffff, v47
	v_sub_u32_e32 v42, 0x7f000000, v41
	v_mul_f32_e64 v34, |v46|, v42
	v_cndmask_b32_e32 v42, 0.5, v185, vcc
	v_cmp_nlt_f32_e64 vcc, |v47|, 2.0
	v_rndne_f32_e32 v34, v34
	v_mul_f32_e32 v34, v41, v34
	v_cndmask_b32_e32 v42, v197, v42, vcc
	v_min_f32_e32 v34, 0x40f00000, v34
	v_sub_u32_e32 v41, 0x7f000000, v42
	v_mul_f32_e64 v39, |v47|, v41
	v_rndne_f32_e32 v39, v39
	v_pk_mul_f32 v[44:45], v[8:9], v[40:41] op_sel_hi:[1,0]
	v_mul_f32_e32 v39, v42, v39
	v_cmp_lt_f32_e64 vcc, |v44|, 4.0
	v_min_f32_e32 v39, 0x40f00000, v39
	v_bfi_b32 v43, s10, v39, v47
	v_cndmask_b32_e32 v41, 0.5, v185, vcc
	v_cmp_nlt_f32_e64 vcc, |v44|, 2.0
	v_and_b32_e32 v39, 0x7fffffff, v44
	v_bfi_b32 v42, s10, v34, v46
	v_cndmask_b32_e32 v41, v197, v41, vcc
	v_pk_mul_f32 v[42:43], v[42:43], v[38:39] op_sel_hi:[1,0]
	v_pk_fma_f32 v[24:25], v[24:25], 2.0, v[42:43] op_sel_hi:[1,0,1] neg_lo:[0,0,1] neg_hi:[0,0,1]
	v_cmp_lt_f32_e64 vcc, |v45|, 4.0
	v_and_b32_e32 v39, 0x7fffffff, v45
	v_sub_u32_e32 v42, 0x7f000000, v41
	v_mul_f32_e64 v34, |v44|, v42
	v_cndmask_b32_e32 v42, 0.5, v185, vcc
	v_cmp_nlt_f32_e64 vcc, |v45|, 2.0
	v_rndne_f32_e32 v34, v34
	v_mul_f32_e32 v34, v41, v34
	v_cndmask_b32_e32 v42, v197, v42, vcc
	v_min_f32_e32 v34, 0x40f00000, v34
	v_sub_u32_e32 v41, 0x7f000000, v42
	v_mul_f32_e64 v39, |v45|, v41
	v_rndne_f32_e32 v39, v39
	v_pk_mul_f32 v[46:47], v[26:27], v[40:41] op_sel_hi:[1,0]
	v_mul_f32_e32 v39, v42, v39
	v_cmp_lt_f32_e64 vcc, |v46|, 4.0
	v_min_f32_e32 v39, 0x40f00000, v39
	v_bfi_b32 v43, s10, v39, v45
	v_cndmask_b32_e32 v41, 0.5, v185, vcc
	v_cmp_nlt_f32_e64 vcc, |v46|, 2.0
	v_and_b32_e32 v39, 0x7fffffff, v46
	v_bfi_b32 v42, s10, v34, v44
	v_cndmask_b32_e32 v41, v197, v41, vcc
	v_pk_mul_f32 v[42:43], v[42:43], v[38:39] op_sel_hi:[1,0]
	v_pk_fma_f32 v[8:9], v[8:9], 2.0, v[42:43] op_sel_hi:[1,0,1] neg_lo:[0,0,1] neg_hi:[0,0,1]
	v_cmp_lt_f32_e64 vcc, |v47|, 4.0
	v_and_b32_e32 v39, 0x7fffffff, v47
	v_sub_u32_e32 v42, 0x7f000000, v41
	v_mul_f32_e64 v34, |v46|, v42
	v_cndmask_b32_e32 v42, 0.5, v185, vcc
	v_cmp_nlt_f32_e64 vcc, |v47|, 2.0
	v_rndne_f32_e32 v34, v34
	v_mul_f32_e32 v34, v41, v34
	v_cndmask_b32_e32 v42, v197, v42, vcc
	v_min_f32_e32 v34, 0x40f00000, v34
	v_sub_u32_e32 v41, 0x7f000000, v42
	v_mul_f32_e64 v39, |v47|, v41
	v_rndne_f32_e32 v39, v39
	v_pk_mul_f32 v[44:45], v[10:11], v[40:41] op_sel_hi:[1,0]
	v_mul_f32_e32 v39, v42, v39
	v_cmp_lt_f32_e64 vcc, |v44|, 4.0
	v_min_f32_e32 v39, 0x40f00000, v39
	v_bfi_b32 v43, s10, v39, v47
	v_cndmask_b32_e32 v41, 0.5, v185, vcc
	v_cmp_nlt_f32_e64 vcc, |v44|, 2.0
	v_and_b32_e32 v39, 0x7fffffff, v44
	v_bfi_b32 v42, s10, v34, v46
	v_cndmask_b32_e32 v41, v197, v41, vcc
	v_pk_mul_f32 v[42:43], v[42:43], v[38:39] op_sel_hi:[1,0]
	v_pk_fma_f32 v[26:27], v[26:27], 2.0, v[42:43] op_sel_hi:[1,0,1] neg_lo:[0,0,1] neg_hi:[0,0,1]
	v_cmp_lt_f32_e64 vcc, |v45|, 4.0
	v_and_b32_e32 v39, 0x7fffffff, v45
	v_sub_u32_e32 v42, 0x7f000000, v41
	v_mul_f32_e64 v34, |v44|, v42
	v_cndmask_b32_e32 v42, 0.5, v185, vcc
	v_cmp_nlt_f32_e64 vcc, |v45|, 2.0
	v_rndne_f32_e32 v34, v34
	v_mul_f32_e32 v34, v41, v34
	v_cndmask_b32_e32 v42, v197, v42, vcc
	v_min_f32_e32 v34, 0x40f00000, v34
	v_sub_u32_e32 v41, 0x7f000000, v42
	v_mul_f32_e64 v39, |v45|, v41
	v_rndne_f32_e32 v39, v39
	v_pk_mul_f32 v[46:47], v[28:29], v[40:41] op_sel_hi:[1,0]
	v_mul_f32_e32 v39, v42, v39
	v_cmp_lt_f32_e64 vcc, |v46|, 4.0
	v_min_f32_e32 v39, 0x40f00000, v39
	v_bfi_b32 v43, s10, v39, v45
	v_cndmask_b32_e32 v41, 0.5, v185, vcc
	v_cmp_nlt_f32_e64 vcc, |v46|, 2.0
	v_and_b32_e32 v39, 0x7fffffff, v46
	v_bfi_b32 v42, s10, v34, v44
	v_cndmask_b32_e32 v41, v197, v41, vcc
	v_pk_mul_f32 v[42:43], v[42:43], v[38:39] op_sel_hi:[1,0]
	v_pk_fma_f32 v[10:11], v[10:11], 2.0, v[42:43] op_sel_hi:[1,0,1] neg_lo:[0,0,1] neg_hi:[0,0,1]
	v_cmp_lt_f32_e64 vcc, |v47|, 4.0
	v_and_b32_e32 v39, 0x7fffffff, v47
	v_sub_u32_e32 v42, 0x7f000000, v41
	v_mul_f32_e64 v34, |v46|, v42
	v_cndmask_b32_e32 v42, 0.5, v185, vcc
	v_cmp_nlt_f32_e64 vcc, |v47|, 2.0
	v_rndne_f32_e32 v34, v34
	v_mul_f32_e32 v34, v41, v34
	v_cndmask_b32_e32 v42, v197, v42, vcc
	v_min_f32_e32 v34, 0x40f00000, v34
	v_sub_u32_e32 v41, 0x7f000000, v42
	v_mul_f32_e64 v39, |v47|, v41
	v_rndne_f32_e32 v39, v39
	v_pk_mul_f32 v[44:45], v[12:13], v[40:41] op_sel_hi:[1,0]
	v_mul_f32_e32 v39, v42, v39
	v_cmp_lt_f32_e64 vcc, |v44|, 4.0
	v_min_f32_e32 v39, 0x40f00000, v39
	v_bfi_b32 v43, s10, v39, v47
	v_cndmask_b32_e32 v41, 0.5, v185, vcc
	v_cmp_nlt_f32_e64 vcc, |v44|, 2.0
	v_and_b32_e32 v39, 0x7fffffff, v44
	v_bfi_b32 v42, s10, v34, v46
	v_cndmask_b32_e32 v41, v197, v41, vcc
	v_pk_mul_f32 v[42:43], v[42:43], v[38:39] op_sel_hi:[1,0]
	v_pk_fma_f32 v[28:29], v[28:29], 2.0, v[42:43] op_sel_hi:[1,0,1] neg_lo:[0,0,1] neg_hi:[0,0,1]
	v_cmp_lt_f32_e64 vcc, |v45|, 4.0
	v_and_b32_e32 v39, 0x7fffffff, v45
	v_sub_u32_e32 v42, 0x7f000000, v41
	v_mul_f32_e64 v34, |v44|, v42
	v_cndmask_b32_e32 v42, 0.5, v185, vcc
	v_cmp_nlt_f32_e64 vcc, |v45|, 2.0
	v_rndne_f32_e32 v34, v34
	v_mul_f32_e32 v34, v41, v34
	v_cndmask_b32_e32 v42, v197, v42, vcc
	v_min_f32_e32 v34, 0x40f00000, v34
	v_sub_u32_e32 v41, 0x7f000000, v42
	v_mul_f32_e64 v39, |v45|, v41
	v_rndne_f32_e32 v39, v39
	v_pk_mul_f32 v[46:47], v[30:31], v[40:41] op_sel_hi:[1,0]
	v_mul_f32_e32 v39, v42, v39
	v_cmp_lt_f32_e64 vcc, |v46|, 4.0
	v_min_f32_e32 v39, 0x40f00000, v39
	v_bfi_b32 v43, s10, v39, v45
	v_cndmask_b32_e32 v41, 0.5, v185, vcc
	v_cmp_nlt_f32_e64 vcc, |v46|, 2.0
	v_and_b32_e32 v39, 0x7fffffff, v46
	v_bfi_b32 v42, s10, v34, v44
	v_cndmask_b32_e32 v41, v197, v41, vcc
	v_pk_mul_f32 v[42:43], v[42:43], v[38:39] op_sel_hi:[1,0]
	v_pk_fma_f32 v[12:13], v[12:13], 2.0, v[42:43] op_sel_hi:[1,0,1] neg_lo:[0,0,1] neg_hi:[0,0,1]
	v_cmp_lt_f32_e64 vcc, |v47|, 4.0
	v_and_b32_e32 v39, 0x7fffffff, v47
	v_sub_u32_e32 v42, 0x7f000000, v41
	v_mul_f32_e64 v34, |v46|, v42
	v_cndmask_b32_e32 v42, 0.5, v185, vcc
	v_cmp_nlt_f32_e64 vcc, |v47|, 2.0
	v_rndne_f32_e32 v34, v34
	v_mul_f32_e32 v34, v41, v34
	v_cndmask_b32_e32 v42, v197, v42, vcc
	v_min_f32_e32 v34, 0x40f00000, v34
	v_sub_u32_e32 v41, 0x7f000000, v42
	v_mul_f32_e64 v39, |v47|, v41
	v_rndne_f32_e32 v39, v39
	v_pk_mul_f32 v[44:45], v[14:15], v[40:41] op_sel_hi:[1,0]
	v_mul_f32_e32 v39, v42, v39
	v_cmp_lt_f32_e64 vcc, |v44|, 4.0
	v_min_f32_e32 v39, 0x40f00000, v39
	v_bfi_b32 v43, s10, v39, v47
	v_cndmask_b32_e32 v41, 0.5, v185, vcc
	v_cmp_nlt_f32_e64 vcc, |v44|, 2.0
	v_and_b32_e32 v39, 0x7fffffff, v44
	v_bfi_b32 v42, s10, v34, v46
	v_cndmask_b32_e32 v41, v197, v41, vcc
	v_pk_mul_f32 v[42:43], v[42:43], v[38:39] op_sel_hi:[1,0]
	v_pk_fma_f32 v[30:31], v[30:31], 2.0, v[42:43] op_sel_hi:[1,0,1] neg_lo:[0,0,1] neg_hi:[0,0,1]
	v_cmp_lt_f32_e64 vcc, |v45|, 4.0
	v_and_b32_e32 v39, 0x7fffffff, v45
	v_sub_u32_e32 v42, 0x7f000000, v41
	v_mul_f32_e64 v34, |v44|, v42
	v_cndmask_b32_e32 v42, 0.5, v185, vcc
	v_cmp_nlt_f32_e64 vcc, |v45|, 2.0
	v_rndne_f32_e32 v34, v34
	v_mul_f32_e32 v34, v41, v34
	v_cndmask_b32_e32 v42, v197, v42, vcc
	v_min_f32_e32 v34, 0x40f00000, v34
	v_sub_u32_e32 v41, 0x7f000000, v42
	v_mul_f32_e64 v39, |v45|, v41
	v_rndne_f32_e32 v39, v39
	v_pk_mul_f32 v[46:47], v[32:33], v[40:41] op_sel_hi:[1,0]
	v_mul_f32_e32 v39, v42, v39
	v_cmp_lt_f32_e64 vcc, |v46|, 4.0
	v_min_f32_e32 v39, 0x40f00000, v39
	v_bfi_b32 v43, s10, v39, v45
	v_cndmask_b32_e32 v41, 0.5, v185, vcc
	v_cmp_nlt_f32_e64 vcc, |v46|, 2.0
	v_and_b32_e32 v39, 0x7fffffff, v46
	v_bfi_b32 v42, s10, v34, v44
	v_cndmask_b32_e32 v41, v197, v41, vcc
	v_pk_mul_f32 v[42:43], v[42:43], v[38:39] op_sel_hi:[1,0]
	v_pk_fma_f32 v[14:15], v[14:15], 2.0, v[42:43] op_sel_hi:[1,0,1] neg_lo:[0,0,1] neg_hi:[0,0,1]
	v_cmp_lt_f32_e64 vcc, |v47|, 4.0
	v_and_b32_e32 v39, 0x7fffffff, v47
	v_sub_u32_e32 v42, 0x7f000000, v41
	v_mul_f32_e64 v34, |v46|, v42
	v_cndmask_b32_e32 v42, 0.5, v185, vcc
	v_cmp_nlt_f32_e64 vcc, |v47|, 2.0
	v_rndne_f32_e32 v34, v34
	v_mul_f32_e32 v34, v41, v34
	v_cndmask_b32_e32 v42, v197, v42, vcc
	v_min_f32_e32 v34, 0x40f00000, v34
	v_sub_u32_e32 v41, 0x7f000000, v42
	v_mul_f32_e64 v39, |v47|, v41
	v_rndne_f32_e32 v39, v39
	v_mul_f32_e32 v39, v42, v39
	v_min_f32_e32 v39, 0x40f00000, v39
	v_bfi_b32 v41, s10, v39, v47
	v_pk_mul_f32 v[42:43], v[16:17], v[40:41] op_sel_hi:[1,0]
	s_nop 0
	v_cmp_lt_f32_e64 vcc, |v42|, 4.0
	v_and_b32_e32 v39, 0x7fffffff, v42
	s_nop 0
	v_cndmask_b32_e32 v40, 0.5, v185, vcc
	v_cmp_nlt_f32_e64 vcc, |v42|, 2.0
	s_nop 1
	v_cndmask_b32_e32 v44, v197, v40, vcc
	v_bfi_b32 v40, s10, v34, v46
	v_pk_mul_f32 v[40:41], v[40:41], v[38:39] op_sel_hi:[1,0]
	v_pk_fma_f32 v[32:33], v[32:33], 2.0, v[40:41] op_sel_hi:[1,0,1] neg_lo:[0,0,1] neg_hi:[0,0,1]
	v_cmp_lt_f32_e64 vcc, |v43|, 4.0
	v_and_b32_e32 v39, 0x7fffffff, v43
	v_sub_u32_e32 v40, 0x7f000000, v44
	v_mul_f32_e64 v34, |v42|, v40
	v_cndmask_b32_e32 v40, 0.5, v185, vcc
	v_cmp_nlt_f32_e64 vcc, |v43|, 2.0
	v_rndne_f32_e32 v34, v34
	v_mul_f32_e32 v34, v44, v34
	v_cndmask_b32_e32 v40, v197, v40, vcc
	v_min_f32_e32 v34, 0x40f00000, v34
	v_sub_u32_e32 v41, 0x7f000000, v40
	v_mul_f32_e64 v39, |v43|, v41
	v_rndne_f32_e32 v39, v39
	v_mul_f32_e32 v39, v40, v39
	v_min_f32_e32 v39, 0x40f00000, v39
	v_bfi_b32 v41, s10, v39, v43
	v_bfi_b32 v40, s10, v34, v42
	v_pk_mul_f32 v[38:39], v[40:41], v[38:39] op_sel_hi:[1,0]
	v_max_f32_e64 v34, |v18|, |v2|
	v_pk_fma_f32 v[16:17], v[16:17], 2.0, v[38:39] op_sel_hi:[1,0,1] neg_lo:[0,0,1] neg_hi:[0,0,1]
	v_max_f32_e64 v38, |v19|, |v3|
	v_max3_f32 v34, v34, 0, v38
	v_max_f32_e64 v38, |v20|, |v4|
	v_max_f32_e64 v39, |v21|, |v5|
	v_max3_f32 v34, v34, v38, v39
	v_max_f32_e64 v38, |v22|, |v6|
	v_max_f32_e64 v39, |v23|, |v7|
	v_max3_f32 v34, v34, v38, v39
	v_max_f32_e64 v38, |v24|, |v8|
	v_max_f32_e64 v39, |v25|, |v9|
	v_max3_f32 v34, v34, v38, v39
	v_max_f32_e64 v38, |v26|, |v10|
	v_max_f32_e64 v39, |v27|, |v11|
	v_max3_f32 v34, v34, v38, v39
	v_max_f32_e64 v38, |v28|, |v12|
	v_max_f32_e64 v39, |v29|, |v13|
	v_max3_f32 v34, v34, v38, v39
	v_max_f32_e64 v38, |v30|, |v14|
	v_max_f32_e64 v39, |v31|, |v15|
	v_max3_f32 v34, v34, v38, v39
	v_max_f32_e64 v38, |v32|, |v16|
	v_max_f32_e64 v39, |v33|, |v17|
	v_max3_f32 v34, v34, v38, v39
	v_bfe_u32 v38, v34, 23, 8
	v_and_b32_e32 v34, 0x7fffff, v34
	v_cmp_gt_u32_e32 vcc, s1, v34
	s_nop 1
	v_cndmask_b32_e64 v34, -2, -3, vcc
	v_add3_u32 v34, v38, v34, s97
	v_max_i32_e32 v34, 0xffffff88, v34
	v_add_u32_e32 v34, 0x7f, v34
	v_lshlrev_b32_e32 v44, 23, v34
	v_cvt_scalef32_2xpk16_fp6_f32 v[38:43], v[18:33], v[2:17], v44
	v_lshl_add_u64 v[2:3], v[36:37], 0, v[102:103]
	v_mul_lo_u32 v34, v34, s3
	v_lshl_add_u64 v[2:3], v[2:3], 0, v[100:101]
	v_mov_b32_e32 v32, v42
	v_mov_b32_e32 v33, v43
	global_store_dwordx4 v[2:3], v[38:41], off offset:256
	global_store_dwordx4 v[2:3], v[32:35], off offset:272
	s_or_b64 exec, exec, s[6:7]
	s_cmp_eq_u32 s87, s92
	s_mov_b64 s[4:5], -1
	s_cbranch_scc1 .LBB0_1589
